# row-pair-interleaved A operands (HB1,HB2,U) with full-line LDS-DMA + software-pipelined k-loops for zgemm/mlp1/mlp2; prep tile balance; plus earlier scan/merge/qkv changes
# speedup vs baseline: 1.0563x; 1.0298x over previous
; #define JOB(SRC, KK, NN, DSTOFF, SC, PERM, CNT) if (t < (CNT)) { do_transpose((SRC), (KK), (NN), (u16*)(wl + (DSTOFF)), (SC), (PERM), t, tl); continue; } t -= (CNT);
; DI void phase_prep(const Params& p, char* smem) {
;     ...
;   for (int g = blk__; g < 2 * T_LAYER; g += gridDim.x) {
;     const int l = g / T_LAYER; int t = g - l * T_LAYER;
;     char* wl = p.ws + OFF_W + (size_t)l * W_LAYER;
;     ...
;     JOB(p.in[I_WIN] + (size_t)l * 1024 * INC, 1024, INC, WO_WIN, nullptr, 0, T_WIN)
;     ...
;     for (int it = blk__; it < 192; it += gridDim.x) {
.LBB0_7:
	s_load_dword s4, s[0:1], 0x120
	s_waitcnt lgkmcnt(0)
	s_mul_i32 s5, s4, 10
	s_cmp_ge_i32 s94, s5
	s_cbranch_scc1 .Lprep_b
	s_add_i32 s94, s94, s4
	s_cmp_lt_i32 s94, s5
	s_cbranch_scc1 .Lprep_upd
	s_cmpk_lt_i32 s2, 0xc0
	s_cbranch_scc1 .LBB0_297
	s_add_i32 s94, s5, s2
	s_addk_i32 s94, 0xff40
	s_branch .Lprep_upd
.Lprep_b:
	s_add_i32 s94, s94, s4
	s_addk_i32 s94, 0xff40
.Lprep_upd:
	s_add_i32 s33, s94, 0xfffff098
	s_lshl_b32 s66, s94, 6
	s_add_i32 s69, s66, 0xfffe2a00
	s_add_i32 s68, s94, 0xfffff4a8
	s_add_i32 s72, s94, 0xfffff8a8
	s_add_i32 s73, s94, 0xfffff9a8
	s_add_i32 s74, s94, 0xfffff9e8
	s_add_i32 s75, s94, 0xfffffa68
	s_add_i32 s76, s94, 0xfffffaa8
	s_add_i32 s79, s94, 0xfff0
	s_add_i32 s80, s94, 0xfffffaf0
	s_cmpk_gt_i32 s94, 0x1edf
	s_cbranch_scc1 .LBB0_297

; template <int MI, int NI>
; DI void gemm256(f32x4 (&acc)[MI][NI], const u16* __restrict__ A, int lda, const u16* __restrict__ Bt, int ldb, int K, int m0, int n0, char* smem) {
;     ...
;   for (int kt = 0; kt < nk; ++kt) {
;     if (kt + 1 < nk) asm volatile("s_waitcnt vmcnt(%0) lgkmcnt(0)" :: "n"(LPS) : "memory");
;     else asm volatile("s_waitcnt vmcnt(0) lgkmcnt(0)" ::: "memory");
;     __builtin_amdgcn_s_barrier();
;     __builtin_amdgcn_s_setprio(1);
;     const char* sb = smem + st * STAGE + foff;
;     bf16x8 af[MI], bfr[NI];
; #pragma unroll
;     for (int mi = 0; mi < MI; ++mi) af[mi] = *(const bf16x8*)(sb + (wr * MI + mi) * 1024);
; #pragma unroll
;     for (int ni = 0; ni < NI; ++ni) bfr[ni] = *(const bf16x8*)(sb + ABYTES + (wc * NI + ni) * 1024);
;     __builtin_amdgcn_sched_barrier(0x0);
;     if (kt + 2 < nk) { const int s2 = st >= 1 ? st - 1 : 2; G256_ISSUE(s2, (kt + 2) * 32); }
;     __builtin_amdgcn_s_setprio(0);
; #pragma unroll
;     for (int mi = 0; mi < MI; ++mi)
; #pragma unroll
;       for (int ni = 0; ni < NI; ++ni)
;         acc[mi][ni] = __builtin_amdgcn_mfma_f32_16x16x32_bf16(bfr[ni], af[mi], acc[mi][ni], 0, 0, 0);
;     st = st == 2 ? 0 : st + 1;
;   }
.Lpipe_mlp1:
	v_add_u32_e32 v160, s11, v143
	ds_read_b128 v[164:167], v160 offset:4096
	ds_read_b128 v[168:171], v160 offset:5120
	ds_read_b128 v[172:175], v160 offset:6144
	ds_read_b128 v[176:179], v160 offset:7168
	s_add_i32 s12, s11, 0xffffa000
	s_cmp_eq_u32 s11, 0
	s_cselect_b32 s12, 0xc000, s12
	s_add_i32 s13, s12, s14
	s_add_i32 s12, s12, s4
	s_mov_b32 m0, s13
	s_waitcnt lgkmcnt(7)
	v_mfma_f32_16x16x32_bf16 v[126:129], v[180:183], v[144:147], v[126:129]
	global_load_lds_dwordx4 v[198:199], off
	v_mfma_f32_16x16x32_bf16 v[110:113], v[180:183], v[148:151], v[110:113]
	v_lshl_add_u64 v[198:199], v[198:199], 0, s[98:99]
	s_add_i32 m0, s13, 0x400
	v_mfma_f32_16x16x32_bf16 v[94:97], v[180:183], v[152:155], v[94:97]
	global_load_lds_dwordx4 v[200:201], off
	v_mfma_f32_16x16x32_bf16 v[78:81], v[180:183], v[156:159], v[78:81]
	v_lshl_add_u64 v[200:201], v[200:201], 0, s[98:99]
	s_add_i32 m0, s13, 0x800
	s_waitcnt lgkmcnt(6)
	v_mfma_f32_16x16x32_bf16 v[122:125], v[184:187], v[144:147], v[122:125]
	global_load_lds_dwordx4 v[202:203], off
	v_mfma_f32_16x16x32_bf16 v[106:109], v[184:187], v[148:151], v[106:109]
	v_lshl_add_u64 v[202:203], v[202:203], 0, s[98:99]
	s_add_i32 m0, s13, 0xc00
	v_mfma_f32_16x16x32_bf16 v[90:93], v[184:187], v[152:155], v[90:93]
	global_load_lds_dwordx4 v[204:205], off
	v_mfma_f32_16x16x32_bf16 v[74:77], v[184:187], v[156:159], v[74:77]
	v_lshl_add_u64 v[204:205], v[204:205], 0, s[98:99]
	s_mov_b32 m0, s12
	s_waitcnt lgkmcnt(5)
	v_mfma_f32_16x16x32_bf16 v[118:121], v[188:191], v[144:147], v[118:121]
	global_load_lds_dwordx4 v[206:207], off
	v_mfma_f32_16x16x32_bf16 v[102:105], v[188:191], v[148:151], v[102:105]
	v_lshl_add_u64 v[206:207], v[206:207], 0, 64
	s_add_i32 m0, s12, 0x400
	v_mfma_f32_16x16x32_bf16 v[86:89], v[188:191], v[152:155], v[86:89]
	global_load_lds_dwordx4 v[208:209], off
	v_mfma_f32_16x16x32_bf16 v[70:73], v[188:191], v[156:159], v[70:73]
	v_lshl_add_u64 v[208:209], v[208:209], 0, 64
	s_waitcnt lgkmcnt(4)
	v_mfma_f32_16x16x32_bf16 v[114:117], v[192:195], v[144:147], v[114:117]
	v_mfma_f32_16x16x32_bf16 v[98:101], v[192:195], v[148:151], v[98:101]
	v_mfma_f32_16x16x32_bf16 v[82:85], v[192:195], v[152:155], v[82:85]
	v_mfma_f32_16x16x32_bf16 v[66:69], v[192:195], v[156:159], v[66:69]
	s_waitcnt vmcnt(6) lgkmcnt(0)
	s_barrier
	s_add_i32 s13, s11, 0x6000
	s_cmp_eq_u32 s11, 0xc000
	s_cselect_b32 s11, 0, s13
	v_add_u32_e32 v196, s11, v143
	v_add_u32_e32 v197, s11, v0
	v_mfma_f32_16x16x32_bf16 v[62:65], v[180:183], v[164:167], v[62:65]
	ds_read_b128 v[144:147], v196
	v_mfma_f32_16x16x32_bf16 v[46:49], v[180:183], v[168:171], v[46:49]
	ds_read_b128 v[148:151], v196 offset:1024
	v_mfma_f32_16x16x32_bf16 v[30:33], v[180:183], v[172:175], v[30:33]
	ds_read_b128 v[152:155], v196 offset:2048
	v_mfma_f32_16x16x32_bf16 v[14:17], v[180:183], v[176:179], v[14:17]
	ds_read_b128 v[156:159], v196 offset:3072
	ds_read_b128 v[180:183], v197 offset:16384
	v_mfma_f32_16x16x32_bf16 v[58:61], v[184:187], v[164:167], v[58:61]
	v_mfma_f32_16x16x32_bf16 v[42:45], v[184:187], v[168:171], v[42:45]
	v_mfma_f32_16x16x32_bf16 v[26:29], v[184:187], v[172:175], v[26:29]
	v_mfma_f32_16x16x32_bf16 v[10:13], v[184:187], v[176:179], v[10:13]
	ds_read_b128 v[184:187], v197 offset:17408
	v_mfma_f32_16x16x32_bf16 v[54:57], v[188:191], v[164:167], v[54:57]
	v_mfma_f32_16x16x32_bf16 v[38:41], v[188:191], v[168:171], v[38:41]
	v_mfma_f32_16x16x32_bf16 v[22:25], v[188:191], v[172:175], v[22:25]
	v_mfma_f32_16x16x32_bf16 v[6:9], v[188:191], v[176:179], v[6:9]
	ds_read_b128 v[188:191], v197 offset:18432
	v_mfma_f32_16x16x32_bf16 v[50:53], v[192:195], v[164:167], v[50:53]
	v_mfma_f32_16x16x32_bf16 v[34:37], v[192:195], v[168:171], v[34:37]
	v_mfma_f32_16x16x32_bf16 v[18:21], v[192:195], v[172:175], v[18:21]
	v_mfma_f32_16x16x32_bf16 v[2:5], v[192:195], v[176:179], v[2:5]
	ds_read_b128 v[192:195], v197 offset:19456
	s_sub_i32 s5, s5, 1
	s_cmp_lg_u32 s5, 0
	s_cbranch_scc1 .Lpipe_mlp1
	v_add_u32_e32 v160, s11, v143
	ds_read_b128 v[164:167], v160 offset:4096
	ds_read_b128 v[168:171], v160 offset:5120
	ds_read_b128 v[172:175], v160 offset:6144
	ds_read_b128 v[176:179], v160 offset:7168
	s_add_i32 s12, s11, 0xffffa000
	s_cmp_eq_u32 s11, 0
	s_cselect_b32 s12, 0xc000, s12
	s_add_i32 s13, s12, s14
	s_add_i32 s12, s12, s4
	s_mov_b32 m0, s13
	s_waitcnt lgkmcnt(7)
	v_mfma_f32_16x16x32_bf16 v[126:129], v[180:183], v[144:147], v[126:129]
	global_load_lds_dwordx4 v[198:199], off
	v_mfma_f32_16x16x32_bf16 v[110:113], v[180:183], v[148:151], v[110:113]
	v_lshl_add_u64 v[198:199], v[198:199], 0, s[98:99]
	s_add_i32 m0, s13, 0x400
	v_mfma_f32_16x16x32_bf16 v[94:97], v[180:183], v[152:155], v[94:97]
	global_load_lds_dwordx4 v[200:201], off
	v_mfma_f32_16x16x32_bf16 v[78:81], v[180:183], v[156:159], v[78:81]
	v_lshl_add_u64 v[200:201], v[200:201], 0, s[98:99]
	s_add_i32 m0, s13, 0x800
	s_waitcnt lgkmcnt(6)
	v_mfma_f32_16x16x32_bf16 v[122:125], v[184:187], v[144:147], v[122:125]
	global_load_lds_dwordx4 v[202:203], off
	v_mfma_f32_16x16x32_bf16 v[106:109], v[184:187], v[148:151], v[106:109]
	v_lshl_add_u64 v[202:203], v[202:203], 0, s[98:99]
	s_add_i32 m0, s13, 0xc00
	v_mfma_f32_16x16x32_bf16 v[90:93], v[184:187], v[152:155], v[90:93]
	global_load_lds_dwordx4 v[204:205], off
	v_mfma_f32_16x16x32_bf16 v[74:77], v[184:187], v[156:159], v[74:77]
	v_lshl_add_u64 v[204:205], v[204:205], 0, s[98:99]
	s_mov_b32 m0, s12
	s_waitcnt lgkmcnt(5)
; template <int MI, int NI>
; DI void gemm256(f32x4 (&acc)[MI][NI], const u16* __restrict__ A, int lda, const u16* __restrict__ Bt, int ldb, int K, int m0, int n0, char* smem) {
;     ...
;   for (int kt = 0; kt < nk; ++kt) {
;     if (kt + 1 < nk) asm volatile("s_waitcnt vmcnt(%0) lgkmcnt(0)" :: "n"(LPS) : "memory");
;     else asm volatile("s_waitcnt vmcnt(0) lgkmcnt(0)" ::: "memory");
;     __builtin_amdgcn_s_barrier();
;     __builtin_amdgcn_s_setprio(1);
;     const char* sb = smem + st * STAGE + foff;
;     bf16x8 af[MI], bfr[NI];
; #pragma unroll
;     for (int mi = 0; mi < MI; ++mi) af[mi] = *(const bf16x8*)(sb + (wr * MI + mi) * 1024);
; #pragma unroll
;     for (int ni = 0; ni < NI; ++ni) bfr[ni] = *(const bf16x8*)(sb + ABYTES + (wc * NI + ni) * 1024);
;     __builtin_amdgcn_sched_barrier(0x0);
;     if (kt + 2 < nk) { const int s2 = st >= 1 ? st - 1 : 2; G256_ISSUE(s2, (kt + 2) * 32); }
;     __builtin_amdgcn_s_setprio(0);
; #pragma unroll
;     for (int mi = 0; mi < MI; ++mi)
; #pragma unroll
;       for (int ni = 0; ni < NI; ++ni)
;         acc[mi][ni] = __builtin_amdgcn_mfma_f32_16x16x32_bf16(bfr[ni], af[mi], acc[mi][ni], 0, 0, 0);
;     st = st == 2 ? 0 : st + 1;
;   }
	v_mfma_f32_16x16x32_bf16 v[118:121], v[188:191], v[144:147], v[118:121]
	global_load_lds_dwordx4 v[206:207], off
	v_mfma_f32_16x16x32_bf16 v[102:105], v[188:191], v[148:151], v[102:105]
	v_lshl_add_u64 v[206:207], v[206:207], 0, 64
	s_add_i32 m0, s12, 0x400
	v_mfma_f32_16x16x32_bf16 v[86:89], v[188:191], v[152:155], v[86:89]
	global_load_lds_dwordx4 v[208:209], off
	v_mfma_f32_16x16x32_bf16 v[70:73], v[188:191], v[156:159], v[70:73]
	v_lshl_add_u64 v[208:209], v[208:209], 0, 64
	s_waitcnt lgkmcnt(4)
	v_mfma_f32_16x16x32_bf16 v[114:117], v[192:195], v[144:147], v[114:117]
	v_mfma_f32_16x16x32_bf16 v[98:101], v[192:195], v[148:151], v[98:101]
	v_mfma_f32_16x16x32_bf16 v[82:85], v[192:195], v[152:155], v[82:85]
	v_mfma_f32_16x16x32_bf16 v[66:69], v[192:195], v[156:159], v[66:69]
	s_waitcnt lgkmcnt(0)
	v_mfma_f32_16x16x32_bf16 v[62:65], v[180:183], v[164:167], v[62:65]
	v_mfma_f32_16x16x32_bf16 v[46:49], v[180:183], v[168:171], v[46:49]
	v_mfma_f32_16x16x32_bf16 v[30:33], v[180:183], v[172:175], v[30:33]
	v_mfma_f32_16x16x32_bf16 v[14:17], v[180:183], v[176:179], v[14:17]
	v_mfma_f32_16x16x32_bf16 v[58:61], v[184:187], v[164:167], v[58:61]
	v_mfma_f32_16x16x32_bf16 v[42:45], v[184:187], v[168:171], v[42:45]
	v_mfma_f32_16x16x32_bf16 v[26:29], v[184:187], v[172:175], v[26:29]
	v_mfma_f32_16x16x32_bf16 v[10:13], v[184:187], v[176:179], v[10:13]
	v_mfma_f32_16x16x32_bf16 v[54:57], v[188:191], v[164:167], v[54:57]
	v_mfma_f32_16x16x32_bf16 v[38:41], v[188:191], v[168:171], v[38:41]
	v_mfma_f32_16x16x32_bf16 v[22:25], v[188:191], v[172:175], v[22:25]
	v_mfma_f32_16x16x32_bf16 v[6:9], v[188:191], v[176:179], v[6:9]
	v_mfma_f32_16x16x32_bf16 v[50:53], v[192:195], v[164:167], v[50:53]
	v_mfma_f32_16x16x32_bf16 v[34:37], v[192:195], v[168:171], v[34:37]
	v_mfma_f32_16x16x32_bf16 v[18:21], v[192:195], v[172:175], v[18:21]
	v_mfma_f32_16x16x32_bf16 v[2:5], v[192:195], v[176:179], v[2:5]
	s_waitcnt vmcnt(6) lgkmcnt(0)
	s_barrier
	s_setprio 1
	v_add_u32_e32 v0, v140, v142
	s_waitcnt vmcnt(0)
	ds_read_b128 v[130:133], v0
	ds_read_b128 v[142:145], v0 offset:1024
	ds_read_b128 v[146:149], v0 offset:2048
	ds_read_b128 v[150:153], v0 offset:3072
	ds_read_b128 v[154:157], v0 offset:4096
	ds_read_b128 v[158:161], v0 offset:5120
	ds_read_b128 v[164:167], v0 offset:6144
	ds_read_b128 v[168:171], v0 offset:7168
	v_add_u32_e32 v212, v140, v141
	ds_read_b128 v[138:141], v212 offset:16384
	ds_read_b128 v[172:175], v212 offset:17408
	ds_read_b128 v[176:179], v212 offset:18432
	ds_read_b128 v[180:183], v212 offset:19456
	s_setprio 0
	s_waitcnt vmcnt(0) lgkmcnt(0)
	s_waitcnt lgkmcnt(3)
	v_mfma_f32_16x16x32_bf16 v[126:129], v[138:141], v[130:133], v[126:129]
	s_barrier
	s_waitcnt lgkmcnt(2)
	v_mfma_f32_16x16x32_bf16 v[122:125], v[172:175], v[130:133], v[122:125]
	s_waitcnt lgkmcnt(1)
	v_mfma_f32_16x16x32_bf16 v[184:187], v[176:179], v[130:133], v[118:121]
	s_waitcnt lgkmcnt(0)
	v_mfma_f32_16x16x32_bf16 v[114:117], v[180:183], v[130:133], v[114:117]
	v_mfma_f32_16x16x32_bf16 v[130:133], v[138:141], v[142:145], v[110:113]
	v_mfma_f32_16x16x32_bf16 v[106:109], v[172:175], v[142:145], v[106:109]
	v_mfma_f32_16x16x32_bf16 v[188:191], v[176:179], v[142:145], v[102:105]
	v_mfma_f32_16x16x32_bf16 v[98:101], v[180:183], v[142:145], v[98:101]
	v_mfma_f32_16x16x32_bf16 v[94:97], v[138:141], v[146:149], v[94:97]
	v_mfma_f32_16x16x32_bf16 v[90:93], v[172:175], v[146:149], v[90:93]
	v_mfma_f32_16x16x32_bf16 v[142:145], v[176:179], v[146:149], v[86:89]
	v_mfma_f32_16x16x32_bf16 v[82:85], v[180:183], v[146:149], v[82:85]
	v_mfma_f32_16x16x32_bf16 v[146:149], v[138:141], v[150:153], v[78:81]
	v_mfma_f32_16x16x32_bf16 v[74:77], v[172:175], v[150:153], v[74:77]
	v_mfma_f32_16x16x32_bf16 v[192:195], v[176:179], v[150:153], v[70:73]
	v_mfma_f32_16x16x32_bf16 v[66:69], v[180:183], v[150:153], v[66:69]
	v_mfma_f32_16x16x32_bf16 v[62:65], v[138:141], v[154:157], v[62:65]
	v_mfma_f32_16x16x32_bf16 v[58:61], v[172:175], v[154:157], v[58:61]
	v_mfma_f32_16x16x32_bf16 v[150:153], v[176:179], v[154:157], v[54:57]
	v_mfma_f32_16x16x32_bf16 v[50:53], v[180:183], v[154:157], v[50:53]
	v_mfma_f32_16x16x32_bf16 v[154:157], v[138:141], v[158:161], v[46:49]
	v_mfma_f32_16x16x32_bf16 v[42:45], v[172:175], v[158:161], v[42:45]
	v_mfma_f32_16x16x32_bf16 v[196:199], v[176:179], v[158:161], v[38:41]
	v_mfma_f32_16x16x32_bf16 v[34:37], v[180:183], v[158:161], v[34:37]
	v_mfma_f32_16x16x32_bf16 v[30:33], v[138:141], v[164:167], v[30:33]
	v_mfma_f32_16x16x32_bf16 v[26:29], v[172:175], v[164:167], v[26:29]
	v_mfma_f32_16x16x32_bf16 v[158:161], v[176:179], v[164:167], v[22:25]
	v_mfma_f32_16x16x32_bf16 v[18:21], v[180:183], v[164:167], v[18:21]
	v_mfma_f32_16x16x32_bf16 v[138:141], v[138:141], v[168:171], v[14:17]
	v_mfma_f32_16x16x32_bf16 v[10:13], v[172:175], v[168:171], v[10:13]
	v_mfma_f32_16x16x32_bf16 v[164:167], v[176:179], v[168:171], v[6:9]
	v_mfma_f32_16x16x32_bf16 v[2:5], v[180:183], v[168:171], v[2:5]
	s_setprio 1
	s_nop 0
	ds_read_b128 v[6:9], v0 offset:24576
	ds_read_b128 v[14:17], v0 offset:25600
	ds_read_b128 v[22:25], v0 offset:26624
	ds_read_b128 v[38:41], v0 offset:27648
	ds_read_b128 v[168:171], v0 offset:28672
	ds_read_b128 v[172:175], v0 offset:29696
	ds_read_b128 v[176:179], v0 offset:30720
	ds_read_b128 v[180:183], v0 offset:31744
	ds_read_b128 v[200:203], v212 offset:40960
	ds_read_b128 v[204:207], v212 offset:41984
	ds_read_b128 v[208:211], v212 offset:43008
	ds_read_b128 v[212:215], v212 offset:44032
	s_setprio 0
	s_waitcnt lgkmcnt(3)
	v_mfma_f32_16x16x32_bf16 v[216:219], v[200:203], v[6:9], v[126:129]
	v_mov_b32_e32 v0, v136
	s_waitcnt lgkmcnt(0)
	s_barrier
; DI unsigned pack2(float a, float b) { float2_t v = {a, b}; bf16x2_t r = __builtin_convertvector(v, bf16x2_t); return __builtin_bit_cast(unsigned, r); }
; #define EPI_BEGIN const int lr1_ = launder_v(lr), lq1_ = launder_v(lq), wr1_ = launder_v(wr), wc1_ = launder_v(wc); { const int lr = lr1_, lq = lq1_, wr = wr1_, wc = wc1_; (void)lr; (void)lq; (void)wr; (void)wc;
; DI void phase_mlp1(const Params& p, int l, int Mout, char* smem) {
;     ...
;     EPI_BEGIN
; #pragma unroll
;     for (int mi = 0; mi < 8; mi += 2) {
;       const int m = m0 + wr * 128 + (mi + (lq & 1)) * 16 + lr;
; #pragma unroll
;       for (int ni = 0; ni < 4; ++ni) {
;         const int n = n0 + wc * 64 + ni * 16 + (lq >> 1) * 8;
;         float va[4], vb[4];
; #pragma unroll
;         for (int j = 0; j < 4; ++j) { const float a = fmaxf(acc[mi][ni][j], 0.f); va[j] = a * a; const float b = fmaxf(acc[mi + 1][ni][j], 0.f); vb[j] = b * b; }
;         *(uint4*)(U + (size_t)m * DFF + n) = widen16(make_uint2(pack2(va[0], va[1]), pack2(va[2], va[3])), make_uint2(pack2(vb[0], vb[1]), pack2(vb[2], vb[3])));
;       }
;       __builtin_amdgcn_sched_barrier(0);
;     }
	s_waitcnt lgkmcnt(2)
	v_mfma_f32_16x16x32_bf16 v[118:121], v[204:207], v[6:9], v[122:125]
	v_mov_b32_e32 v126, v137
	v_mov_b32_e32 v127, v134
	v_lshlrev_b32_e32 v129, 2, v126
	v_lshlrev_b32_e32 v126, 4, v126
	v_mfma_f32_16x16x32_bf16 v[122:125], v[200:203], v[14:17], v[130:133]
	v_mov_b32_e32 v128, v135
	v_lshlrev_b32_e32 v127, 7, v127
	v_add_u32_e32 v0, s10, v0
	v_and_b32_e32 v126, 16, v126
	v_add3_u32 v126, v0, v127, v126
	v_lshlrev_b32_e32 v128, 6, v128
	v_and_b32_e32 v129, -8, v129
	v_ashrrev_i32_e32 v127, 31, v126
	v_add3_u32 v132, v129, s9, v128
	v_and_b32_e32 v220, 1, v126
	v_lshrrev_b32_e32 v128, 1, v126
	v_mov_b32_e32 v129, 0
	v_lshlrev_b64 v[128:129], 14, v[128:129]
	v_lshl_or_b32 v128, v220, 6, v128
	v_max_f32_e32 v0, v216, v216
	v_mfma_f32_16x16x32_bf16 v[94:97], v[200:203], v[22:25], v[94:97]
	v_ashrrev_i32_e32 v133, 31, v132
	v_mfma_f32_16x16x32_bf16 v[86:89], v[204:207], v[22:25], v[90:93]
	s_waitcnt lgkmcnt(1)
	v_mfma_f32_16x16x32_bf16 v[78:81], v[208:211], v[22:25], v[142:145]
	s_waitcnt lgkmcnt(0)
	v_mfma_f32_16x16x32_bf16 v[70:73], v[212:215], v[22:25], v[82:85]
	v_mfma_f32_16x16x32_bf16 v[22:25], v[204:207], v[176:179], v[26:29]
	v_mfma_f32_16x16x32_bf16 v[26:29], v[200:203], v[180:183], v[138:141]
	s_nop 2
	v_lshl_add_u64 v[138:139], s[60:61], 0, v[128:129]
	v_max_f32_e32 v128, 0, v0
	v_max_f32_e32 v0, v122, v122
	v_max_f32_e32 v122, 0, v0
	v_max_f32_e32 v0, v217, v217
	v_max_f32_e32 v129, 0, v0
	v_max_f32_e32 v0, v123, v123
	v_max_f32_e32 v123, 0, v0
	v_max_f32_e32 v0, v218, v218
	v_mfma_f32_16x16x32_bf16 v[102:105], v[212:215], v[6:9], v[114:117]
	v_max_f32_e32 v130, 0, v0
	v_max_f32_e32 v0, v124, v124
	v_max_f32_e32 v124, 0, v0
	v_mfma_f32_16x16x32_bf16 v[114:117], v[204:207], v[14:17], v[106:109]
	v_max_f32_e32 v0, v219, v219
	v_max_f32_e32 v131, 0, v0
	v_max_f32_e32 v0, v125, v125
	v_max_f32_e32 v125, 0, v0
	v_max_f32_e32 v0, v118, v118
	v_max_f32_e32 v118, 0, v0
	s_nop 1
	v_max_f32_e32 v0, v114, v114
	v_pk_mul_f32 v[128:129], v[128:129], v[128:129]
	v_pk_mul_f32 v[122:123], v[122:123], v[122:123]
	v_pk_mul_f32 v[130:131], v[130:131], v[130:131]
	v_pk_mul_f32 v[124:125], v[124:125], v[124:125]
	v_max_f32_e32 v114, 0, v0
	v_max_f32_e32 v0, v119, v119
	v_cvt_pk_bf16_f32 v128, v128, v129
	v_cvt_pk_bf16_f32 v129, v130, v131
	v_cvt_pk_bf16_f32 v130, v122, v123
	v_cvt_pk_bf16_f32 v131, v124, v125
	v_and_b32_e32 v220, 31, v132
	v_lshrrev_b32_e32 v122, 5, v132
	v_lshlrev_b32_e32 v122, 7, v122
	v_lshl_or_b32 v122, v220, 1, v122
	v_mov_b32_e32 v123, 0
	v_max_f32_e32 v119, 0, v0
	v_max_f32_e32 v0, v115, v115
	v_mfma_f32_16x16x32_bf16 v[110:113], v[208:211], v[6:9], v[184:187]
	v_permlane16_swap_b32_e32 v128, v130
	v_permlane16_swap_b32_e32 v129, v131
	v_lshl_add_u64 v[124:125], v[138:139], 0, v[122:123]
	v_max_f32_e32 v115, 0, v0
	v_max_f32_e32 v0, v120, v120
	v_mfma_f32_16x16x32_bf16 v[106:109], v[208:211], v[14:17], v[188:191]
	flat_store_dwordx4 v[124:125], v[128:131]
	v_pk_mul_f32 v[118:119], v[118:119], v[118:119]
	s_nop 0
	v_pk_mul_f32 v[128:129], v[114:115], v[114:115]
	v_max_f32_e32 v114, 0, v0
	v_max_f32_e32 v0, v116, v116
	v_max_f32_e32 v116, 0, v0
	v_max_f32_e32 v0, v121, v121
	v_max_f32_e32 v115, 0, v0
	v_max_f32_e32 v0, v117, v117
	v_max_f32_e32 v117, 0, v0
	v_max_f32_e32 v0, v110, v110
	v_max_f32_e32 v110, 0, v0
	v_max_f32_e32 v0, v106, v106
	v_pk_mul_f32 v[120:121], v[114:115], v[114:115]
	v_pk_mul_f32 v[130:131], v[116:117], v[116:117]
	v_max_f32_e32 v106, 0, v0
	v_max_f32_e32 v0, v111, v111
	v_cvt_pk_bf16_f32 v114, v118, v119
	v_cvt_pk_bf16_f32 v115, v120, v121
	v_cvt_pk_bf16_f32 v116, v128, v129
	v_cvt_pk_bf16_f32 v117, v130, v131
	v_max_f32_e32 v111, 0, v0
	v_max_f32_e32 v0, v107, v107
	v_permlane16_swap_b32_e32 v114, v116
	v_permlane16_swap_b32_e32 v115, v117
	v_max_f32_e32 v107, 0, v0
	v_max_f32_e32 v0, v112, v112
	v_mfma_f32_16x16x32_bf16 v[98:101], v[212:215], v[14:17], v[98:101]
	flat_store_dwordx4 v[124:125], v[114:117] offset:32
	v_pk_mul_f32 v[110:111], v[110:111], v[110:111]
	s_nop 0
	v_pk_mul_f32 v[114:115], v[106:107], v[106:107]
	v_max_f32_e32 v106, 0, v0
	v_max_f32_e32 v0, v108, v108
	v_max_f32_e32 v108, 0, v0
	v_max_f32_e32 v0, v113, v113
	v_max_f32_e32 v107, 0, v0
	v_max_f32_e32 v0, v109, v109
	v_max_f32_e32 v109, 0, v0
	v_max_f32_e32 v0, v102, v102
	v_max_f32_e32 v102, 0, v0
	v_max_f32_e32 v0, v98, v98
	v_pk_mul_f32 v[112:113], v[106:107], v[106:107]
	v_pk_mul_f32 v[116:117], v[108:109], v[108:109]
	v_max_f32_e32 v98, 0, v0
	v_max_f32_e32 v0, v103, v103
	v_cvt_pk_bf16_f32 v106, v110, v111
	v_cvt_pk_bf16_f32 v107, v112, v113
	v_cvt_pk_bf16_f32 v108, v114, v115
	v_cvt_pk_bf16_f32 v109, v116, v117
	v_max_f32_e32 v103, 0, v0
	v_max_f32_e32 v0, v99, v99
	v_permlane16_swap_b32_e32 v106, v108
	v_permlane16_swap_b32_e32 v107, v109
	v_max_f32_e32 v99, 0, v0
	v_max_f32_e32 v0, v104, v104
	flat_store_dwordx4 v[124:125], v[106:109] offset:128
	v_pk_mul_f32 v[102:103], v[102:103], v[102:103]
	v_mfma_f32_16x16x32_bf16 v[90:93], v[200:203], v[38:41], v[146:149]
	v_mul_f32_e64 v106, v98, v98
	v_mul_f32_e64 v107, v99, v99
	v_max_f32_e32 v98, 0, v0
	v_max_f32_e32 v0, v100, v100
	v_max_f32_e32 v100, 0, v0
	v_max_f32_e32 v0, v105, v105
	v_max_f32_e32 v99, 0, v0
	v_max_f32_e32 v0, v101, v101
	v_max_f32_e32 v101, 0, v0
	v_pk_mul_f32 v[104:105], v[98:99], v[98:99]
	v_pk_mul_f32 v[108:109], v[100:101], v[100:101]
	v_cvt_pk_bf16_f32 v98, v102, v103
	v_cvt_pk_bf16_f32 v99, v104, v105
	v_cvt_pk_bf16_f32 v100, v106, v107
	v_cvt_pk_bf16_f32 v101, v108, v109
	s_nop 0
	v_permlane16_swap_b32_e32 v98, v100
	v_permlane16_swap_b32_e32 v99, v101
	v_mfma_f32_16x16x32_bf16 v[82:85], v[204:207], v[38:41], v[74:77]
; DI unsigned pack2(float a, float b) { float2_t v = {a, b}; bf16x2_t r = __builtin_convertvector(v, bf16x2_t); return __builtin_bit_cast(unsigned, r); }
; #define EPI_BEGIN const int lr1_ = launder_v(lr), lq1_ = launder_v(lq), wr1_ = launder_v(wr), wc1_ = launder_v(wc); { const int lr = lr1_, lq = lq1_, wr = wr1_, wc = wc1_; (void)lr; (void)lq; (void)wr; (void)wc;
; template <int MI, int NI>
; DI void gemm256(f32x4 (&acc)[MI][NI], const u16* __restrict__ A, int lda, const u16* __restrict__ Bt, int ldb, int K, int m0, int n0, char* smem) {
;     ...
;         acc[mi][ni] = __builtin_amdgcn_mfma_f32_16x16x32_bf16(bfr[ni], af[mi], acc[mi][ni], 0, 0, 0);
; DI void phase_mlp1(const Params& p, int l, int Mout, char* smem) {
;     ...
;     EPI_BEGIN
; #pragma unroll
;     for (int mi = 0; mi < 8; mi += 2) {
;       const int m = m0 + wr * 128 + (mi + (lq & 1)) * 16 + lr;
; #pragma unroll
;       for (int ni = 0; ni < 4; ++ni) {
;         const int n = n0 + wc * 64 + ni * 16 + (lq >> 1) * 8;
;         float va[4], vb[4];
; #pragma unroll
;         for (int j = 0; j < 4; ++j) { const float a = fmaxf(acc[mi][ni][j], 0.f); va[j] = a * a; const float b = fmaxf(acc[mi + 1][ni][j], 0.f); vb[j] = b * b; }
;         *(uint4*)(U + (size_t)m * DFF + n) = widen16(make_uint2(pack2(va[0], va[1]), pack2(va[2], va[3])), make_uint2(pack2(vb[0], vb[1]), pack2(vb[2], vb[3])));
;       }
;       __builtin_amdgcn_sched_barrier(0);
;     }
	flat_store_dwordx4 v[124:125], v[98:101] offset:160
	v_mfma_f32_16x16x32_bf16 v[74:77], v[208:211], v[38:41], v[192:195]
	v_mfma_f32_16x16x32_bf16 v[66:69], v[212:215], v[38:41], v[66:69]
	v_mfma_f32_16x16x32_bf16 v[62:65], v[200:203], v[168:171], v[62:65]
	v_mfma_f32_16x16x32_bf16 v[54:57], v[204:207], v[168:171], v[58:61]
	v_mfma_f32_16x16x32_bf16 v[46:49], v[208:211], v[168:171], v[150:153]
	v_mfma_f32_16x16x32_bf16 v[38:41], v[212:215], v[168:171], v[50:53]
	v_mfma_f32_16x16x32_bf16 v[58:61], v[200:203], v[172:175], v[154:157]
	v_mfma_f32_16x16x32_bf16 v[50:53], v[204:207], v[172:175], v[42:45]
	v_mfma_f32_16x16x32_bf16 v[42:45], v[208:211], v[172:175], v[196:199]
	v_mfma_f32_16x16x32_bf16 v[34:37], v[212:215], v[172:175], v[34:37]
	v_mfma_f32_16x16x32_bf16 v[30:33], v[200:203], v[176:179], v[30:33]
	v_mfma_f32_16x16x32_bf16 v[14:17], v[208:211], v[176:179], v[158:161]
	v_mfma_f32_16x16x32_bf16 v[6:9], v[212:215], v[176:179], v[18:21]
	v_mfma_f32_16x16x32_bf16 v[18:21], v[204:207], v[180:183], v[10:13]
	v_mfma_f32_16x16x32_bf16 v[10:13], v[208:211], v[180:183], v[164:167]
	v_mfma_f32_16x16x32_bf16 v[2:5], v[212:215], v[180:183], v[2:5]
	v_max_f32_e32 v0, v94, v94
	v_max_f32_e32 v94, 0, v0
	v_max_f32_e32 v0, v90, v90
	v_max_f32_e32 v90, 0, v0
	v_max_f32_e32 v0, v95, v95
	v_max_f32_e32 v95, 0, v0
	v_max_f32_e32 v0, v91, v91
	v_max_f32_e32 v91, 0, v0
	v_max_f32_e32 v0, v96, v96
	v_pk_mul_f32 v[100:101], v[90:91], v[90:91]
	v_max_f32_e32 v90, 0, v0
	v_max_f32_e32 v0, v92, v92
	v_max_f32_e32 v92, 0, v0
	v_max_f32_e32 v0, v97, v97
	v_max_f32_e32 v91, 0, v0
	v_max_f32_e32 v0, v93, v93
	v_add_u32_e32 v98, 32, v126
	v_max_f32_e32 v93, 0, v0
	v_max_f32_e32 v0, v86, v86
	v_ashrrev_i32_e32 v99, 31, v98
	v_max_f32_e32 v86, 0, v0
	v_max_f32_e32 v0, v82, v82
	v_and_b32_e32 v220, 1, v98
	v_lshrrev_b32_e32 v98, 1, v98
	v_mov_b32_e32 v99, 0
	v_lshlrev_b64 v[98:99], 14, v[98:99]
	v_lshl_or_b32 v98, v220, 6, v98
	v_pk_mul_f32 v[94:95], v[94:95], v[94:95]
	v_pk_mul_f32 v[96:97], v[90:91], v[90:91]
	v_pk_mul_f32 v[102:103], v[92:93], v[92:93]
	v_max_f32_e32 v82, 0, v0
	v_max_f32_e32 v0, v87, v87
	v_lshl_add_u64 v[98:99], s[60:61], 0, v[98:99]
	v_cvt_pk_bf16_f32 v90, v94, v95
	v_cvt_pk_bf16_f32 v91, v96, v97
	v_cvt_pk_bf16_f32 v92, v100, v101
	v_cvt_pk_bf16_f32 v93, v102, v103
	v_max_f32_e32 v87, 0, v0
	v_max_f32_e32 v0, v83, v83
	v_permlane16_swap_b32_e32 v90, v92
	v_permlane16_swap_b32_e32 v91, v93
	v_lshl_add_u64 v[94:95], v[98:99], 0, v[122:123]
	v_max_f32_e32 v83, 0, v0
	v_max_f32_e32 v0, v88, v88
	flat_store_dwordx4 v[94:95], v[90:93]
	v_pk_mul_f32 v[86:87], v[86:87], v[86:87]
	s_nop 0
	v_pk_mul_f32 v[90:91], v[82:83], v[82:83]
	v_max_f32_e32 v82, 0, v0
	v_max_f32_e32 v0, v84, v84
	v_max_f32_e32 v84, 0, v0
	v_max_f32_e32 v0, v89, v89
	v_max_f32_e32 v83, 0, v0
	v_max_f32_e32 v0, v85, v85
	v_max_f32_e32 v85, 0, v0
	v_max_f32_e32 v0, v78, v78
	v_max_f32_e32 v78, 0, v0
	v_max_f32_e32 v0, v74, v74
	v_pk_mul_f32 v[88:89], v[82:83], v[82:83]
	v_pk_mul_f32 v[92:93], v[84:85], v[84:85]
	v_max_f32_e32 v74, 0, v0
	v_max_f32_e32 v0, v79, v79
	v_cvt_pk_bf16_f32 v82, v86, v87
	v_cvt_pk_bf16_f32 v83, v88, v89
	v_cvt_pk_bf16_f32 v84, v90, v91
	v_cvt_pk_bf16_f32 v85, v92, v93
	v_max_f32_e32 v79, 0, v0
	v_max_f32_e32 v0, v75, v75
	v_permlane16_swap_b32_e32 v82, v84
	v_permlane16_swap_b32_e32 v83, v85
	v_max_f32_e32 v75, 0, v0
	v_max_f32_e32 v0, v80, v80
	flat_store_dwordx4 v[94:95], v[82:85] offset:32
	v_pk_mul_f32 v[78:79], v[78:79], v[78:79]
	s_nop 0
	v_pk_mul_f32 v[82:83], v[74:75], v[74:75]
	v_max_f32_e32 v74, 0, v0
	v_max_f32_e32 v0, v76, v76
	v_max_f32_e32 v76, 0, v0
	v_max_f32_e32 v0, v81, v81
	v_max_f32_e32 v75, 0, v0
	v_max_f32_e32 v0, v77, v77
	v_max_f32_e32 v77, 0, v0
	v_max_f32_e32 v0, v70, v70
	v_max_f32_e32 v70, 0, v0
	v_max_f32_e32 v0, v66, v66
	v_pk_mul_f32 v[80:81], v[74:75], v[74:75]
	v_pk_mul_f32 v[84:85], v[76:77], v[76:77]
	v_max_f32_e32 v66, 0, v0
	v_max_f32_e32 v0, v71, v71
	v_cvt_pk_bf16_f32 v74, v78, v79
	v_cvt_pk_bf16_f32 v75, v80, v81
	v_cvt_pk_bf16_f32 v76, v82, v83
	v_cvt_pk_bf16_f32 v77, v84, v85
	v_max_f32_e32 v71, 0, v0
	v_max_f32_e32 v0, v67, v67
	v_permlane16_swap_b32_e32 v74, v76
	v_permlane16_swap_b32_e32 v75, v77
	v_max_f32_e32 v67, 0, v0
	v_max_f32_e32 v0, v72, v72
	flat_store_dwordx4 v[94:95], v[74:77] offset:128
	v_pk_mul_f32 v[70:71], v[70:71], v[70:71]
	s_nop 0
	v_pk_mul_f32 v[74:75], v[66:67], v[66:67]
	v_max_f32_e32 v66, 0, v0
	v_max_f32_e32 v0, v68, v68
	v_max_f32_e32 v68, 0, v0
	v_max_f32_e32 v0, v73, v73
	v_max_f32_e32 v67, 0, v0
	v_max_f32_e32 v0, v69, v69
	v_max_f32_e32 v69, 0, v0
	v_pk_mul_f32 v[72:73], v[66:67], v[66:67]
	v_pk_mul_f32 v[76:77], v[68:69], v[68:69]
	v_cvt_pk_bf16_f32 v66, v70, v71
	v_cvt_pk_bf16_f32 v67, v72, v73
	v_cvt_pk_bf16_f32 v68, v74, v75
	v_cvt_pk_bf16_f32 v69, v76, v77
	s_nop 0
	v_permlane16_swap_b32_e32 v66, v68
	v_permlane16_swap_b32_e32 v67, v69
	flat_store_dwordx4 v[94:95], v[66:69] offset:160
	v_max_f32_e32 v0, v62, v62
	v_max_f32_e32 v62, 0, v0
	v_max_f32_e32 v0, v58, v58
	v_max_f32_e32 v58, 0, v0
	v_max_f32_e32 v0, v63, v63
	v_max_f32_e32 v63, 0, v0
	v_max_f32_e32 v0, v59, v59
	v_max_f32_e32 v59, 0, v0
	v_max_f32_e32 v0, v64, v64
	v_pk_mul_f32 v[68:69], v[58:59], v[58:59]
	v_max_f32_e32 v58, 0, v0
	v_max_f32_e32 v0, v60, v60
	v_max_f32_e32 v60, 0, v0
	v_max_f32_e32 v0, v65, v65
	v_max_f32_e32 v59, 0, v0
	v_max_f32_e32 v0, v61, v61
	v_add_u32_e32 v66, 64, v126
	v_max_f32_e32 v61, 0, v0
	v_max_f32_e32 v0, v54, v54
	v_ashrrev_i32_e32 v67, 31, v66
	v_max_f32_e32 v54, 0, v0
	v_max_f32_e32 v0, v50, v50
	v_and_b32_e32 v220, 1, v66
	v_lshrrev_b32_e32 v66, 1, v66
	v_mov_b32_e32 v67, 0
; DI unsigned pack2(float a, float b) { float2_t v = {a, b}; bf16x2_t r = __builtin_convertvector(v, bf16x2_t); return __builtin_bit_cast(unsigned, r); }
; #define EPI_BEGIN const int lr1_ = launder_v(lr), lq1_ = launder_v(lq), wr1_ = launder_v(wr), wc1_ = launder_v(wc); { const int lr = lr1_, lq = lq1_, wr = wr1_, wc = wc1_; (void)lr; (void)lq; (void)wr; (void)wc;
; DI void phase_mlp1(const Params& p, int l, int Mout, char* smem) {
;     ...
;   for (int it = 0;; ++it) {
;     int tm, tn;
;     if (!tile_map(it, ntm, 32, blk__, gridDim.x, tm, tn)) break;
;     ...
;     EPI_BEGIN
; #pragma unroll
;     for (int mi = 0; mi < 8; mi += 2) {
;       const int m = m0 + wr * 128 + (mi + (lq & 1)) * 16 + lr;
; #pragma unroll
;       for (int ni = 0; ni < 4; ++ni) {
;         const int n = n0 + wc * 64 + ni * 16 + (lq >> 1) * 8;
;         float va[4], vb[4];
; #pragma unroll
;         for (int j = 0; j < 4; ++j) { const float a = fmaxf(acc[mi][ni][j], 0.f); va[j] = a * a; const float b = fmaxf(acc[mi + 1][ni][j], 0.f); vb[j] = b * b; }
;         *(uint4*)(U + (size_t)m * DFF + n) = widen16(make_uint2(pack2(va[0], va[1]), pack2(va[2], va[3])), make_uint2(pack2(vb[0], vb[1]), pack2(vb[2], vb[3])));
;       }
;       __builtin_amdgcn_sched_barrier(0);
;     }
	v_lshlrev_b64 v[66:67], 14, v[66:67]
	v_lshl_or_b32 v66, v220, 6, v66
	v_pk_mul_f32 v[62:63], v[62:63], v[62:63]
	v_pk_mul_f32 v[64:65], v[58:59], v[58:59]
	v_pk_mul_f32 v[70:71], v[60:61], v[60:61]
	v_max_f32_e32 v50, 0, v0
	v_max_f32_e32 v0, v55, v55
	v_lshl_add_u64 v[66:67], s[60:61], 0, v[66:67]
	v_cvt_pk_bf16_f32 v58, v62, v63
	v_cvt_pk_bf16_f32 v59, v64, v65
	v_cvt_pk_bf16_f32 v60, v68, v69
	v_cvt_pk_bf16_f32 v61, v70, v71
	v_max_f32_e32 v55, 0, v0
	v_max_f32_e32 v0, v51, v51
	v_permlane16_swap_b32_e32 v58, v60
	v_permlane16_swap_b32_e32 v59, v61
	v_lshl_add_u64 v[62:63], v[66:67], 0, v[122:123]
	v_max_f32_e32 v51, 0, v0
	v_max_f32_e32 v0, v56, v56
	flat_store_dwordx4 v[62:63], v[58:61]
	v_pk_mul_f32 v[54:55], v[54:55], v[54:55]
	s_nop 0
	v_pk_mul_f32 v[58:59], v[50:51], v[50:51]
	v_max_f32_e32 v50, 0, v0
	v_max_f32_e32 v0, v52, v52
	v_max_f32_e32 v52, 0, v0
	v_max_f32_e32 v0, v57, v57
	v_max_f32_e32 v51, 0, v0
	v_max_f32_e32 v0, v53, v53
	v_max_f32_e32 v53, 0, v0
	v_max_f32_e32 v0, v46, v46
	v_max_f32_e32 v46, 0, v0
	v_max_f32_e32 v0, v42, v42
	v_pk_mul_f32 v[56:57], v[50:51], v[50:51]
	v_pk_mul_f32 v[60:61], v[52:53], v[52:53]
	v_max_f32_e32 v42, 0, v0
	v_max_f32_e32 v0, v47, v47
	v_cvt_pk_bf16_f32 v50, v54, v55
	v_cvt_pk_bf16_f32 v51, v56, v57
	v_cvt_pk_bf16_f32 v52, v58, v59
	v_cvt_pk_bf16_f32 v53, v60, v61
	v_max_f32_e32 v47, 0, v0
	v_max_f32_e32 v0, v43, v43
	v_permlane16_swap_b32_e32 v50, v52
	v_permlane16_swap_b32_e32 v51, v53
	v_max_f32_e32 v43, 0, v0
	v_max_f32_e32 v0, v48, v48
	flat_store_dwordx4 v[62:63], v[50:53] offset:32
	v_pk_mul_f32 v[46:47], v[46:47], v[46:47]
	s_nop 0
	v_pk_mul_f32 v[50:51], v[42:43], v[42:43]
	v_max_f32_e32 v42, 0, v0
	v_max_f32_e32 v0, v44, v44
	v_max_f32_e32 v44, 0, v0
	v_max_f32_e32 v0, v49, v49
	v_max_f32_e32 v43, 0, v0
	v_max_f32_e32 v0, v45, v45
	v_max_f32_e32 v45, 0, v0
	v_max_f32_e32 v0, v38, v38
	v_max_f32_e32 v38, 0, v0
	v_max_f32_e32 v0, v34, v34
	v_pk_mul_f32 v[48:49], v[42:43], v[42:43]
	v_pk_mul_f32 v[52:53], v[44:45], v[44:45]
	v_max_f32_e32 v34, 0, v0
	v_max_f32_e32 v0, v39, v39
	v_cvt_pk_bf16_f32 v42, v46, v47
	v_cvt_pk_bf16_f32 v43, v48, v49
	v_cvt_pk_bf16_f32 v44, v50, v51
	v_cvt_pk_bf16_f32 v45, v52, v53
	v_max_f32_e32 v39, 0, v0
	v_max_f32_e32 v0, v35, v35
	v_permlane16_swap_b32_e32 v42, v44
	v_permlane16_swap_b32_e32 v43, v45
	v_max_f32_e32 v35, 0, v0
	v_max_f32_e32 v0, v40, v40
	flat_store_dwordx4 v[62:63], v[42:45] offset:128
	v_pk_mul_f32 v[38:39], v[38:39], v[38:39]
	s_nop 0
	v_pk_mul_f32 v[42:43], v[34:35], v[34:35]
	v_max_f32_e32 v34, 0, v0
	v_max_f32_e32 v0, v36, v36
	v_max_f32_e32 v36, 0, v0
	v_max_f32_e32 v0, v41, v41
	v_max_f32_e32 v35, 0, v0
	v_max_f32_e32 v0, v37, v37
	v_max_f32_e32 v37, 0, v0
	v_pk_mul_f32 v[40:41], v[34:35], v[34:35]
	v_pk_mul_f32 v[44:45], v[36:37], v[36:37]
	v_cvt_pk_bf16_f32 v34, v38, v39
	v_cvt_pk_bf16_f32 v35, v40, v41
	v_cvt_pk_bf16_f32 v36, v42, v43
	v_cvt_pk_bf16_f32 v37, v44, v45
	s_nop 0
	v_permlane16_swap_b32_e32 v34, v36
	v_permlane16_swap_b32_e32 v35, v37
	flat_store_dwordx4 v[62:63], v[34:37] offset:160
	v_max_f32_e32 v0, v30, v30
	v_max_f32_e32 v30, 0, v0
	v_max_f32_e32 v0, v26, v26
	v_max_f32_e32 v26, 0, v0
	v_max_f32_e32 v0, v31, v31
	v_max_f32_e32 v31, 0, v0
	v_max_f32_e32 v0, v27, v27
	v_max_f32_e32 v27, 0, v0
	v_max_f32_e32 v0, v32, v32
	v_pk_mul_f32 v[36:37], v[26:27], v[26:27]
	v_max_f32_e32 v26, 0, v0
	v_max_f32_e32 v0, v28, v28
	v_max_f32_e32 v28, 0, v0
	v_max_f32_e32 v0, v33, v33
	v_max_f32_e32 v27, 0, v0
	v_max_f32_e32 v0, v29, v29
	v_add_u32_e32 v34, 0x60, v126
	v_max_f32_e32 v29, 0, v0
	v_max_f32_e32 v0, v22, v22
	v_ashrrev_i32_e32 v35, 31, v34
	v_max_f32_e32 v22, 0, v0
	v_max_f32_e32 v0, v18, v18
	v_and_b32_e32 v220, 1, v34
	v_lshrrev_b32_e32 v34, 1, v34
	v_mov_b32_e32 v35, 0
	v_lshlrev_b64 v[34:35], 14, v[34:35]
	v_lshl_or_b32 v34, v220, 6, v34
	v_pk_mul_f32 v[30:31], v[30:31], v[30:31]
	v_pk_mul_f32 v[32:33], v[26:27], v[26:27]
	v_pk_mul_f32 v[38:39], v[28:29], v[28:29]
	v_max_f32_e32 v18, 0, v0
	v_max_f32_e32 v0, v23, v23
	v_lshl_add_u64 v[34:35], s[60:61], 0, v[34:35]
	v_cvt_pk_bf16_f32 v26, v30, v31
	v_cvt_pk_bf16_f32 v27, v32, v33
	v_cvt_pk_bf16_f32 v28, v36, v37
	v_cvt_pk_bf16_f32 v29, v38, v39
	v_max_f32_e32 v23, 0, v0
	v_max_f32_e32 v0, v19, v19
	v_permlane16_swap_b32_e32 v26, v28
	v_permlane16_swap_b32_e32 v27, v29
	v_lshl_add_u64 v[30:31], v[34:35], 0, v[122:123]
	v_max_f32_e32 v19, 0, v0
	v_max_f32_e32 v0, v24, v24
	flat_store_dwordx4 v[30:31], v[26:29]
	v_pk_mul_f32 v[22:23], v[22:23], v[22:23]
	s_nop 0
	v_pk_mul_f32 v[26:27], v[18:19], v[18:19]
	v_max_f32_e32 v18, 0, v0
	v_max_f32_e32 v0, v20, v20
	v_max_f32_e32 v20, 0, v0
	v_max_f32_e32 v0, v25, v25
	v_max_f32_e32 v19, 0, v0
	v_max_f32_e32 v0, v21, v21
	v_max_f32_e32 v21, 0, v0
	v_max_f32_e32 v0, v14, v14
	v_max_f32_e32 v14, 0, v0
	v_max_f32_e32 v0, v10, v10
	v_pk_mul_f32 v[24:25], v[18:19], v[18:19]
	v_pk_mul_f32 v[28:29], v[20:21], v[20:21]
	v_max_f32_e32 v10, 0, v0
	v_max_f32_e32 v0, v15, v15
	v_cvt_pk_bf16_f32 v18, v22, v23
	v_cvt_pk_bf16_f32 v19, v24, v25
	v_cvt_pk_bf16_f32 v20, v26, v27
	v_cvt_pk_bf16_f32 v21, v28, v29
	v_max_f32_e32 v15, 0, v0
	v_max_f32_e32 v0, v11, v11
	v_permlane16_swap_b32_e32 v18, v20
	v_permlane16_swap_b32_e32 v19, v21
	v_max_f32_e32 v11, 0, v0
	v_max_f32_e32 v0, v16, v16
	flat_store_dwordx4 v[30:31], v[18:21] offset:32
	v_pk_mul_f32 v[14:15], v[14:15], v[14:15]
	s_nop 0
	v_pk_mul_f32 v[18:19], v[10:11], v[10:11]
	v_max_f32_e32 v10, 0, v0
	v_max_f32_e32 v0, v12, v12
	v_max_f32_e32 v12, 0, v0
	v_max_f32_e32 v0, v17, v17
	v_max_f32_e32 v11, 0, v0
	v_max_f32_e32 v0, v13, v13
	v_max_f32_e32 v13, 0, v0
	v_max_f32_e32 v0, v6, v6
	v_max_f32_e32 v6, 0, v0
	v_max_f32_e32 v0, v2, v2
	v_pk_mul_f32 v[16:17], v[10:11], v[10:11]
	v_pk_mul_f32 v[20:21], v[12:13], v[12:13]
	v_max_f32_e32 v2, 0, v0
	v_max_f32_e32 v0, v7, v7
	v_cvt_pk_bf16_f32 v10, v14, v15
	v_cvt_pk_bf16_f32 v11, v16, v17
	v_cvt_pk_bf16_f32 v12, v18, v19
	v_cvt_pk_bf16_f32 v13, v20, v21
	v_max_f32_e32 v7, 0, v0
	v_max_f32_e32 v0, v3, v3
	v_permlane16_swap_b32_e32 v10, v12
	v_permlane16_swap_b32_e32 v11, v13
	v_max_f32_e32 v3, 0, v0
	v_max_f32_e32 v0, v8, v8
	flat_store_dwordx4 v[30:31], v[10:13] offset:128
	v_pk_mul_f32 v[6:7], v[6:7], v[6:7]
	s_nop 0
	v_pk_mul_f32 v[10:11], v[2:3], v[2:3]
	v_max_f32_e32 v2, 0, v0
	v_max_f32_e32 v0, v4, v4
	v_max_f32_e32 v4, 0, v0
	v_max_f32_e32 v0, v9, v9
	v_max_f32_e32 v3, 0, v0
	v_max_f32_e32 v0, v5, v5
	v_max_f32_e32 v5, 0, v0
	v_pk_mul_f32 v[8:9], v[2:3], v[2:3]
	v_pk_mul_f32 v[12:13], v[4:5], v[4:5]
	v_cvt_pk_bf16_f32 v2, v6, v7
	v_cvt_pk_bf16_f32 v3, v8, v9
	v_cvt_pk_bf16_f32 v4, v10, v11
	v_cvt_pk_bf16_f32 v5, v12, v13
	s_nop 0
	v_permlane16_swap_b32_e32 v2, v4
	v_permlane16_swap_b32_e32 v3, v5
	flat_store_dwordx4 v[30:31], v[2:5] offset:160
	s_add_i32 s8, s8, 1
	s_mul_i32 s4, s8, s39
	s_add_i32 s9, s4, s6
	v_readlane_b32 s4, v253, 41
	s_cmp_ge_i32 s9, s4
	s_cbranch_scc0 .LBB0_441

; DI unsigned pack2(float a, float b) { float2_t v = {a, b}; bf16x2_t r = __builtin_convertvector(v, bf16x2_t); return __builtin_bit_cast(unsigned, r); }
; DI void phase_norm(const float* xl, const float* xc, const float* tab  , u16* hb, int M) {
;     ...
;   const int nw = gridDim.x * 4, rpw = (M + nw - 1) / nw;
;   const int rbeg = (blk__ * 4 + wave) * rpw, rend = min(rbeg + rpw, M);
;   int cur_b9 = -1;
;   float4 g[4], sh[4];
; #pragma unroll
;   for (int i = 0; i < 4; ++i) { g[i] = make_float4(0.f, 0.f, 0.f, 0.f); sh[i] = g[i]; }
;   float4 vn[4];
;   if (rbeg < rend) {
;     const float* xp0 = xrow(xl, xc, rbeg);
; #pragma unroll
;     for (int i = 0; i < 4; ++i) vn[i] = *(const float4*)(xp0 + i * 256 + lane * 4);
;   }
;     ...
; #pragma unroll
;     for (int i = 0; i < 4; ++i) {
;       const int k = i * 256 + lane * 4;
;       *(uint2*)(hb + (size_t)r * 1024 + k) = make_uint2(pack2(v[i].x * rs * g[i].x + sh[i].x, v[i].y * rs * g[i].y + sh[i].y), pack2(v[i].z * rs * g[i].z + sh[i].z, v[i].w * rs * g[i].w + sh[i].w));
;     }
.LBB0_451:
	s_mov_b64 s[6:7], 0
	v_writelane_b32 v255, s6, 9
	s_nop 1
	v_writelane_b32 v255, s7, 10
	s_cbranch_execz .LBB0_458
	v_mov_b32_e32 v18, v163
	s_mov_b32 s4, s2
	s_nop 0
	v_ashrrev_i32_e32 v0, 6, v18
	v_lshl_add_u32 v0, s4, 2, v0
	v_readlane_b32 s4, v254, 56
	s_nop 1
	v_mul_lo_u32 v66, v0, s4
	v_add_u32_e32 v0, s4, v66
	v_readlane_b32 s4, v253, 48
	s_nop 1
	v_min_i32_e32 v69, s4, v0
	v_cmp_lt_i32_e32 vcc, v66, v69
	s_and_saveexec_b64 s[4:5], vcc
	s_cbranch_execz .LBB0_457
	v_add_u32_e32 v0, 0xffff8000, v66
	v_cmp_gt_i32_e32 vcc, s58, v66
	s_waitcnt vmcnt(0)
	v_mov_b32_e32 v4, s49
	v_ashrrev_i32_e32 v67, 31, v66
	v_cndmask_b32_e32 v2, v0, v66, vcc
	v_mov_b32_e32 v0, s95
	v_cndmask_b32_e32 v5, v0, v4, vcc
	v_mov_b32_e32 v0, s94
	v_mov_b32_e32 v4, s48
	v_cndmask_b32_e32 v3, 0, v67, vcc
	v_cndmask_b32_e32 v4, v0, v4, vcc
	v_lshlrev_b32_e32 v0, 2, v18
	v_lshlrev_b64 v[2:3], 12, v[2:3]
	v_and_b32_e32 v68, 0xfc, v0
	v_lshl_add_u64 v[2:3], v[4:5], 0, v[2:3]
	v_lshlrev_b32_e32 v0, 2, v68
	v_lshl_add_u64 v[14:15], v[2:3], 0, v[0:1]
	flat_load_dwordx4 v[2:5], v[14:15]
	flat_load_dwordx4 v[6:9], v[14:15] offset:1024
	flat_load_dwordx4 v[10:13], v[14:15] offset:2048
	s_nop 0
	flat_load_dwordx4 v[14:17], v[14:15] offset:3072
	v_lshrrev_b32_e32 v20, 1, v66
	v_mov_b32_e32 v21, 0
	v_lshlrev_b64 v[20:21], 12, v[20:21]
	v_and_b32_e32 v90, 1, v66
	v_lshl_or_b32 v20, v90, 6, v20
	v_bfe_u32 v0, v18, 3, 3
	v_lshl_or_b32 v20, v0, 7, v20
	v_and_b32_e32 v0, 7, v18
	v_readlane_b32 s6, v253, 39
	v_lshl_or_b32 v20, v0, 3, v20
	v_readlane_b32 s7, v253, 40
	v_mov_b32_e32 v0, v1
	v_mov_b32_e32 v73, -1
	v_add_u32_e32 v72, -1, v69
	v_lshl_add_u64 v[70:71], s[6:7], 0, v[20:21]
	s_mov_b64 s[6:7], 0
	v_mov_b64_e32 v[44:45], v[0:1]
	s_waitcnt lgkmcnt(0)
	v_mov_b64_e32 v[42:43], v[0:1]
	v_mov_b64_e32 v[32:33], v[0:1]
	v_mov_b64_e32 v[30:31], v[0:1]
	v_mov_b64_e32 v[28:29], v[0:1]
	v_mov_b64_e32 v[26:27], v[0:1]
	v_mov_b64_e32 v[40:41], v[0:1]
	v_mov_b64_e32 v[38:39], v[0:1]
	v_mov_b64_e32 v[18:19], v[0:1]
	v_mov_b64_e32 v[20:21], v[0:1]
	v_mov_b64_e32 v[22:23], v[0:1]
	v_mov_b64_e32 v[24:25], v[0:1]
	v_mov_b64_e32 v[34:35], v[0:1]
	v_mov_b64_e32 v[36:37], v[0:1]
	v_mov_b64_e32 v[46:47], v[0:1]
	v_mov_b64_e32 v[48:49], v[0:1]
	s_branch .LBB0_455

; template <int MI, int NI>
; DI void gemm256(f32x4 (&acc)[MI][NI], const u16* __restrict__ A, int lda, const u16* __restrict__ Bt, int ldb, int K, int m0, int n0, char* smem) {
;     ...
;   const int srow = lane >> 2, scol = ((lane & 3) ^ ((lane >> 5) << 1)) * 8;
;   const u16* Ag = A + (size_t)(m0 + wave * NAW * 16 + srow) * lda + scol;
;   const u16* Bg = Bt + (size_t)(n0 + wave * NBW * 16 + srow) * ldb + scol;
;   char* la = smem + (wave * NAW) * 1024 + lane * 16;
;   char* lb = smem + ABYTES + (wave * NBW) * 1024 + lane * 16;
;     ...
;   const int nk = K >> 5;
;   G256_ISSUE(0, 0);
;   if (nk > 1) G256_ISSUE(1, 32);
; DI void phase_zgemm(const Params& p, int l, char* smem) {
;     ...
;   for (int it = 0;; ++it) {
;     int tm, tn;
;     if (!tile_map(it, NT / 256, 17, blk__, gridDim.x, tm, tn)) break;
;     const int m0 = tm * 256, n0 = tn * 128;
;     f32x4 acc[8][4]; zero_accm<8, 4>(acc);
;     gemm256<8, 4>(acc, hb, 1024, Wt, 1024, 1024, m0, n0, smem);
.LBB0_856:
	s_lshl_b32 s7, s0, 3
	v_cvt_f32_ubyte0_e32 v0, s7
	v_rcp_iflag_f32_e32 v0, v0
	s_sub_i32 s9, 0, s7
	s_add_i32 s4, s5, s4
	s_abs_i32 s5, s4
	v_mul_f32_e32 v0, 0x4f7ffffe, v0
	v_cvt_u32_f32_e32 v0, v0
	s_ashr_i32 s8, s4, 31
	v_mov_b32_e32 v8, v163
	v_readfirstlane_b32 s10, v0
	s_mul_i32 s9, s9, s10
	s_mul_hi_u32 s9, s10, s9
	s_add_i32 s10, s10, s9
	s_mul_hi_u32 s9, s5, s10
	v_cvt_f32_ubyte0_e32 v0, s0
	s_mul_i32 s10, s9, s7
	v_rcp_iflag_f32_e32 v0, v0
	s_sub_i32 s5, s5, s10
	s_add_i32 s11, s9, 1
	s_sub_i32 s10, s5, s7
	s_cmp_ge_u32 s5, s7
	s_cselect_b32 s9, s11, s9
	v_mul_f32_e32 v0, 0x4f7ffffe, v0
	s_cselect_b32 s5, s10, s5
	s_add_i32 s10, s9, 1
	v_cvt_u32_f32_e32 v0, v0
	s_cmp_ge_u32 s5, s7
	s_cselect_b32 s5, s10, s9
	s_xor_b32 s9, s5, s8
	s_sub_i32 s10, s9, s8
	s_sub_i32 s11, 0, s0
	v_readfirstlane_b32 s12, v0
	s_mul_i32 s5, s10, s7
	s_mul_i32 s11, s11, s12
	s_sub_i32 s4, s4, s5
	s_mul_hi_u32 s11, s12, s11
	s_abs_i32 s5, s4
	s_add_i32 s12, s12, s11
	s_mul_hi_u32 s11, s5, s12
	s_mul_i32 s12, s11, s0
	s_sub_i32 s5, s5, s12
	s_ashr_i32 s7, s4, 31
	s_add_i32 s12, s11, 1
	s_sub_i32 s13, s5, s0
	s_cmp_ge_u32 s5, s0
	s_cselect_b32 s11, s12, s11
	s_cselect_b32 s5, s13, s5
	s_add_i32 s12, s11, 1
	s_cmp_ge_u32 s5, s0
	s_cselect_b32 s5, s12, s11
	s_xor_b32 s11, s5, s7
	s_sub_i32 s12, s11, s7
	s_mul_i32 s0, s12, s0
	s_add_i32 s1, s1, s15
	s_sub_i32 s0, s4, s0
	s_add_i32 s1, s1, s0
	s_lshl_b32 s5, s1, 8
	v_and_b32_e32 v0, 3, v8
	v_lshrrev_b32_e32 v2, 4, v8
	v_and_b32_e32 v10, 0xffffffc0, v8
	v_bfe_u32 v9, v8, 2, 4
	v_bitop3_b32 v0, v2, v0, 2 bitop3:0x6c
	v_add_u32_e32 v2, s5, v10
	s_lshl_b32 s0, s10, 10
	s_lshl_b32 s4, s12, 7
	v_and_b32_e32 v6, 63, v8
	v_ashrrev_i32_e32 v7, 6, v8
	v_or_b32_e32 v2, v2, v9
	s_add_i32 s4, s4, s0
	s_mov_b32 s0, s2
	v_ashrrev_i32_e32 v3, 31, v2
	v_lshlrev_b32_e32 v12, 12, v7
	v_lshlrev_b32_e32 v6, 4, v6
	v_lshlrev_b64 v[2:3], 11, v[2:3]
	v_or_b32_e32 v138, v12, v6
	v_lshl_add_u64 v[2:3], s[22:23], 0, v[2:3]
	v_lshlrev_b32_e32 v0, 4, v0
	v_readfirstlane_b32 s0, v138
	v_or_b32_e32 v14, 0x400, v138
	v_lshl_add_u64 v[2:3], v[2:3], 0, v[0:1]
	v_bfe_i32 v199, v163, 2, 1
	v_and_b32_e32 v198, 0xfffff840, v199
	v_lshl_add_u64 v[2:3], v[2:3], 0, v[198:199]
	v_lshlrev_b32_e32 v11, 5, v7
	s_mov_b32 m0, s0
	v_readfirstlane_b32 s0, v14
	v_add_u32_e32 v4, s4, v11
	v_lshl_or_b32 v139, v7, 11, v6
	global_load_lds_dwordx4 v[2:3], off
	v_lshl_add_u64 v[6:7], v[2:3], 0, s[68:69]
	s_mov_b32 m0, s0
	s_mov_b64 s[0:1], 0x10000
	v_or_b32_e32 v14, 0x800, v138
	v_or_b32_e32 v4, v4, v9
	global_load_lds_dwordx4 v[6:7], off
	v_lshl_add_u64 v[6:7], v[2:3], 0, s[0:1]
	v_readfirstlane_b32 s0, v14
	v_ashrrev_i32_e32 v5, 31, v4
	s_mov_b32 m0, s0
	s_mov_b64 s[0:1], 0x18000
	v_or_b32_e32 v14, 0xc00, v138
	v_lshlrev_b64 v[4:5], 11, v[4:5]
	v_add_u32_e32 v13, 0x4000, v139
	global_load_lds_dwordx4 v[6:7], off
	v_lshl_add_u64 v[6:7], v[2:3], 0, s[0:1]
	v_readfirstlane_b32 s0, v14
	v_lshl_add_u64 v[4:5], s[44:45], 0, v[4:5]
	s_mov_b32 m0, s0
	v_readfirstlane_b32 s0, v13
	v_add_u32_e32 v13, 0x4400, v139
	global_load_lds_dwordx4 v[6:7], off
	v_lshl_add_u64 v[4:5], v[4:5], 0, v[0:1]
	s_mov_b32 m0, s0
	v_readfirstlane_b32 s0, v13
	v_add_u32_e32 v13, 0x6000, v138
	global_load_lds_dwordx4 v[4:5], off
	v_lshl_add_u64 v[6:7], v[4:5], 0, s[68:69]
	s_mov_b32 m0, s0
	v_readfirstlane_b32 s0, v13
	v_add_u32_e32 v13, 0x6400, v138
	global_load_lds_dwordx4 v[6:7], off
	s_mov_b64 s[98:99], 0x80
	v_lshl_add_u64 v[6:7], v[2:3], 0, s[98:99]
	s_mov_b32 m0, s0
	v_readfirstlane_b32 s0, v13
	global_load_lds_dwordx4 v[6:7], off
	s_mov_b64 s[98:99], 0x8080
	v_lshl_add_u64 v[6:7], v[2:3], 0, s[98:99]
	s_mov_b32 m0, s0
	s_mov_b64 s[0:1], 0x10080
	v_add_u32_e32 v13, 0x6800, v138
	global_load_lds_dwordx4 v[6:7], off
	v_lshl_add_u64 v[6:7], v[2:3], 0, s[0:1]
	v_readfirstlane_b32 s0, v13
	s_mov_b32 m0, s0
	s_mov_b64 s[0:1], 0x18080
	global_load_lds_dwordx4 v[6:7], off
	v_add_u32_e32 v6, 0x6c00, v138
	v_lshl_add_u64 v[2:3], v[2:3], 0, s[0:1]
	v_readfirstlane_b32 s0, v6
	v_add_u32_e32 v6, 0xa000, v139
	s_mov_b32 m0, s0
	v_readfirstlane_b32 s0, v6
	global_load_lds_dwordx4 v[2:3], off
	v_lshl_add_u64 v[2:3], v[4:5], 0, 64
	s_mov_b32 m0, s0
	s_lshl_b32 s1, s11, 7
	global_load_lds_dwordx4 v[2:3], off
	v_lshl_add_u64 v[2:3], v[4:5], 0, s[74:75]
	v_add_u32_e32 v4, 0xa400, v139
	s_mov_b32 s6, 0
	v_readfirstlane_b32 s0, v4
	s_mov_b32 m0, s0
	v_and_b32_e32 v4, 48, v8
	global_load_lds_dwordx4 v[2:3], off
	v_lshlrev_b32_e32 v3, 2, v8
	s_lshl_b32 s0, s9, 10
	v_lshlrev_b32_e32 v2, 6, v8
	v_bitop3_b32 v3, v3, v4, 32 bitop3:0x6c
	s_add_i32 s1, s1, s0
	v_and_or_b32 v140, v2, s59, v3
	v_and_b32_e32 v142, 0xffffe000, v2
	v_or_b32_e32 v2, s1, v9
	v_add_u32_e32 v2, v2, v11
	s_lshl_b32 s0, s7, 7
	v_subrev_u32_e32 v2, s0, v2
	s_lshl_b32 s0, s8, 10
	v_subrev_u32_e32 v2, s0, v2
	v_ashrrev_i32_e32 v3, 31, v2
	v_lshlrev_b64 v[2:3], 11, v[2:3]
	v_readlane_b32 s0, v254, 52
	v_or_b32_e32 v2, v2, v0
	v_readlane_b32 s1, v254, 53
	v_and_b32_e32 v141, 0x1000, v12
	s_nop 0
	v_lshl_add_u64 v[130:131], s[0:1], 0, v[2:3]
	v_or_b32_e32 v2, s5, v9
	v_add_u32_e32 v2, v2, v10
	v_ashrrev_i32_e32 v3, 31, v2
	v_lshlrev_b64 v[2:3], 11, v[2:3]
	v_or_b32_e32 v2, v2, v0
	v_lshl_add_u64 v[132:133], s[62:63], 0, v[2:3]
	v_mov_b32_e32 v2, 0
	s_mov_b64 s[0:1], 0
	v_mov_b32_e32 v3, v2
	v_mov_b32_e32 v4, v2
	v_mov_b32_e32 v5, v2
	v_mov_b32_e32 v6, v2
	v_mov_b32_e32 v7, v2
	v_mov_b32_e32 v8, v2
	v_mov_b32_e32 v9, v2
	v_mov_b32_e32 v10, v2
	v_mov_b32_e32 v11, v2
	v_mov_b32_e32 v12, v2
	v_mov_b32_e32 v13, v2
	v_mov_b32_e32 v14, v2
	v_mov_b32_e32 v15, v2
	v_mov_b32_e32 v16, v2
	v_mov_b32_e32 v17, v2
	v_mov_b32_e32 v18, v2
	v_mov_b32_e32 v19, v2
	v_mov_b32_e32 v20, v2
	v_mov_b32_e32 v21, v2
	v_mov_b32_e32 v22, v2
	v_mov_b32_e32 v23, v2
	v_mov_b32_e32 v24, v2
	v_mov_b32_e32 v25, v2
	s_waitcnt lgkmcnt(0)
; template <int MI, int NI>
; DI void gemm256(f32x4 (&acc)[MI][NI], const u16* __restrict__ A, int lda, const u16* __restrict__ Bt, int ldb, int K, int m0, int n0, char* smem) {
;     ...
;   const int nk = K >> 5;
;   G256_ISSUE(0, 0);
;   if (nk > 1) G256_ISSUE(1, 32);
;   const int foff = lr * 64 + ((lq ^ ((lr >> 3) << 1)) * 16);
;   int st = 0;
;   for (int kt = 0; kt < nk; ++kt) {
;     if (kt + 1 < nk) asm volatile("s_waitcnt vmcnt(%0) lgkmcnt(0)" :: "n"(LPS) : "memory");
;     else asm volatile("s_waitcnt vmcnt(0) lgkmcnt(0)" ::: "memory");
;     __builtin_amdgcn_s_barrier();
;     __builtin_amdgcn_s_setprio(1);
;     const char* sb = smem + st * STAGE + foff;
;     bf16x8 af[MI], bfr[NI];
; #pragma unroll
;     for (int mi = 0; mi < MI; ++mi) af[mi] = *(const bf16x8*)(sb + (wr * MI + mi) * 1024);
; #pragma unroll
;     for (int ni = 0; ni < NI; ++ni) bfr[ni] = *(const bf16x8*)(sb + ABYTES + (wc * NI + ni) * 1024);
;     __builtin_amdgcn_sched_barrier(0x0);
;     if (kt + 2 < nk) { const int s2 = st >= 1 ? st - 1 : 2; G256_ISSUE(s2, (kt + 2) * 32); }
;     __builtin_amdgcn_s_setprio(0);
; #pragma unroll
;     for (int mi = 0; mi < MI; ++mi)
; #pragma unroll
;       for (int ni = 0; ni < NI; ++ni)
;         acc[mi][ni] = __builtin_amdgcn_mfma_f32_16x16x32_bf16(bfr[ni], af[mi], acc[mi][ni], 0, 0, 0);
;     st = st == 2 ? 0 : st + 1;
;   }
; DI void phase_zgemm(const Params& p, int l, char* smem) {
;     ...
;     f32x4 acc[8][4]; zero_accm<8, 4>(acc);
	v_mov_b32_e32 v26, v2
	v_mov_b32_e32 v27, v2
	v_mov_b32_e32 v28, v2
	v_mov_b32_e32 v29, v2
	v_mov_b32_e32 v30, v2
	v_mov_b32_e32 v31, v2
	v_mov_b32_e32 v32, v2
	v_mov_b32_e32 v33, v2
	v_mov_b32_e32 v34, v2
	v_mov_b32_e32 v35, v2
	v_mov_b32_e32 v36, v2
	v_mov_b32_e32 v37, v2
	v_mov_b32_e32 v38, v2
	v_mov_b32_e32 v39, v2
	v_mov_b32_e32 v40, v2
	v_mov_b32_e32 v41, v2
	v_mov_b32_e32 v42, v2
	v_mov_b32_e32 v43, v2
	v_mov_b32_e32 v44, v2
	v_mov_b32_e32 v45, v2
	v_mov_b32_e32 v46, v2
	v_mov_b32_e32 v47, v2
	v_mov_b32_e32 v48, v2
	v_mov_b32_e32 v49, v2
	v_mov_b32_e32 v50, v2
	v_mov_b32_e32 v51, v2
	v_mov_b32_e32 v52, v2
	v_mov_b32_e32 v53, v2
	v_mov_b32_e32 v54, v2
	v_mov_b32_e32 v55, v2
	v_mov_b32_e32 v56, v2
	v_mov_b32_e32 v57, v2
	v_mov_b32_e32 v58, v2
	v_mov_b32_e32 v59, v2
	v_mov_b32_e32 v60, v2
	v_mov_b32_e32 v61, v2
	v_mov_b32_e32 v62, v2
	v_mov_b32_e32 v63, v2
	v_mov_b32_e32 v64, v2
	v_mov_b32_e32 v65, v2
	v_mov_b32_e32 v66, v2
	v_mov_b32_e32 v67, v2
	v_mov_b32_e32 v68, v2
	v_mov_b32_e32 v69, v2
	v_mov_b32_e32 v70, v2
	v_mov_b32_e32 v71, v2
	v_mov_b32_e32 v72, v2
	v_mov_b32_e32 v73, v2
	v_mov_b32_e32 v74, v2
	v_mov_b32_e32 v75, v2
	v_mov_b32_e32 v76, v2
	v_mov_b32_e32 v77, v2
	v_mov_b32_e32 v78, v2
	v_mov_b32_e32 v79, v2
	v_mov_b32_e32 v80, v2
	v_mov_b32_e32 v81, v2
	v_mov_b32_e32 v82, v2
	v_mov_b32_e32 v83, v2
	v_mov_b32_e32 v84, v2
	v_mov_b32_e32 v85, v2
	v_mov_b32_e32 v86, v2
	v_mov_b32_e32 v87, v2
	v_mov_b32_e32 v88, v2
	v_mov_b32_e32 v89, v2
	v_mov_b32_e32 v90, v2
	v_mov_b32_e32 v91, v2
	v_mov_b32_e32 v92, v2
	v_mov_b32_e32 v93, v2
	v_mov_b32_e32 v94, v2
	v_mov_b32_e32 v95, v2
	v_mov_b32_e32 v96, v2
	v_mov_b32_e32 v97, v2
	v_mov_b32_e32 v98, v2
	v_mov_b32_e32 v99, v2
	v_mov_b32_e32 v100, v2
	v_mov_b32_e32 v101, v2
	v_mov_b32_e32 v102, v2
	v_mov_b32_e32 v103, v2
	v_mov_b32_e32 v104, v2
	v_mov_b32_e32 v105, v2
	v_mov_b32_e32 v106, v2
	v_mov_b32_e32 v107, v2
	v_mov_b32_e32 v108, v2
	v_mov_b32_e32 v109, v2
	v_mov_b32_e32 v110, v2
	v_mov_b32_e32 v111, v2
	v_mov_b32_e32 v112, v2
	v_mov_b32_e32 v113, v2
	v_mov_b32_e32 v114, v2
	v_mov_b32_e32 v115, v2
	v_mov_b32_e32 v116, v2
	v_mov_b32_e32 v117, v2
	v_mov_b32_e32 v118, v2
	v_mov_b32_e32 v119, v2
	v_mov_b32_e32 v120, v2
	v_mov_b32_e32 v121, v2
	v_mov_b32_e32 v122, v2
	v_mov_b32_e32 v123, v2
	v_mov_b32_e32 v124, v2
	v_mov_b32_e32 v125, v2
	v_mov_b32_e32 v126, v2
	v_mov_b32_e32 v127, v2
	v_mov_b32_e32 v128, v2
	v_mov_b32_e32 v129, v2
	s_mov_b64 s[8:9], 0x10d81100
	v_lshl_add_u64 v[198:199], v[132:133], 0, s[8:9]
	s_mov_b64 s[8:9], 0x10d89100
	v_lshl_add_u64 v[200:201], v[132:133], 0, s[8:9]
	s_mov_b64 s[8:9], 0x10d91100
	v_lshl_add_u64 v[202:203], v[132:133], 0, s[8:9]
	s_mov_b64 s[8:9], 0x10d99100
	v_lshl_add_u64 v[204:205], v[132:133], 0, s[8:9]
	s_mov_b64 s[8:9], 0x941080
	v_lshl_add_u64 v[206:207], v[130:131], 0, s[8:9]
	s_mov_b64 s[8:9], 0x949080
	v_lshl_add_u64 v[208:209], v[130:131], 0, s[8:9]
	v_bfe_i32 v197, v163, 2, 1
	v_and_b32_e32 v196, 0xfffff840, v197
	v_lshl_add_u64 v[198:199], v[198:199], 0, v[196:197]
	v_lshl_add_u64 v[200:201], v[200:201], 0, v[196:197]
	v_lshl_add_u64 v[202:203], v[202:203], 0, v[196:197]
	v_lshl_add_u64 v[204:205], v[204:205], 0, v[196:197]
	s_mov_b64 s[98:99], 0x80
	v_add_u32_e32 v143, v140, v142
	v_add_u32_e32 v0, v140, v141
	v_readfirstlane_b32 s7, v138
	v_readfirstlane_b32 s0, v139
	s_mov_b32 s6, 0
	s_movk_i32 s1, 29
	s_add_i32 s0, s0, 0x4000
	s_waitcnt vmcnt(6) lgkmcnt(0)
	s_barrier
	ds_read_b128 v[144:147], v143
	ds_read_b128 v[148:151], v143 offset:1024
	ds_read_b128 v[152:155], v143 offset:2048
	ds_read_b128 v[156:159], v143 offset:3072
	ds_read_b128 v[180:183], v0 offset:16384
	ds_read_b128 v[184:187], v0 offset:17408
	ds_read_b128 v[188:191], v0 offset:18432
	ds_read_b128 v[192:195], v0 offset:19456
.Lpipe_zgemm:
	v_add_u32_e32 v160, s6, v143
	ds_read_b128 v[164:167], v160 offset:4096
	ds_read_b128 v[168:171], v160 offset:5120
	ds_read_b128 v[172:175], v160 offset:6144
	ds_read_b128 v[176:179], v160 offset:7168
	s_add_i32 s8, s6, 0xffffa000
	s_cmp_eq_u32 s6, 0
	s_cselect_b32 s8, 0xc000, s8
	s_add_i32 s9, s8, s7
	s_add_i32 s8, s8, s0
	s_mov_b32 m0, s9
	s_waitcnt lgkmcnt(7)
	v_mfma_f32_16x16x32_bf16 v[126:129], v[180:183], v[144:147], v[126:129]
	global_load_lds_dwordx4 v[198:199], off
	v_mfma_f32_16x16x32_bf16 v[110:113], v[180:183], v[148:151], v[110:113]
	v_lshl_add_u64 v[198:199], v[198:199], 0, s[98:99]
	s_add_i32 m0, s9, 0x400
	v_mfma_f32_16x16x32_bf16 v[94:97], v[180:183], v[152:155], v[94:97]
	global_load_lds_dwordx4 v[200:201], off
	v_mfma_f32_16x16x32_bf16 v[78:81], v[180:183], v[156:159], v[78:81]
	v_lshl_add_u64 v[200:201], v[200:201], 0, s[98:99]
	s_add_i32 m0, s9, 0x800
	s_waitcnt lgkmcnt(6)
	v_mfma_f32_16x16x32_bf16 v[122:125], v[184:187], v[144:147], v[122:125]
	global_load_lds_dwordx4 v[202:203], off
	v_mfma_f32_16x16x32_bf16 v[106:109], v[184:187], v[148:151], v[106:109]
	v_lshl_add_u64 v[202:203], v[202:203], 0, s[98:99]
	s_add_i32 m0, s9, 0xc00
	v_mfma_f32_16x16x32_bf16 v[90:93], v[184:187], v[152:155], v[90:93]
	global_load_lds_dwordx4 v[204:205], off
	v_mfma_f32_16x16x32_bf16 v[74:77], v[184:187], v[156:159], v[74:77]
	v_lshl_add_u64 v[204:205], v[204:205], 0, s[98:99]
	s_mov_b32 m0, s8
	s_waitcnt lgkmcnt(5)
	v_mfma_f32_16x16x32_bf16 v[118:121], v[188:191], v[144:147], v[118:121]
	global_load_lds_dwordx4 v[206:207], off
	v_mfma_f32_16x16x32_bf16 v[102:105], v[188:191], v[148:151], v[102:105]
	v_lshl_add_u64 v[206:207], v[206:207], 0, 64
	s_add_i32 m0, s8, 0x400
	v_mfma_f32_16x16x32_bf16 v[86:89], v[188:191], v[152:155], v[86:89]
	global_load_lds_dwordx4 v[208:209], off
	v_mfma_f32_16x16x32_bf16 v[70:73], v[188:191], v[156:159], v[70:73]
	v_lshl_add_u64 v[208:209], v[208:209], 0, 64
	s_waitcnt lgkmcnt(4)
	v_mfma_f32_16x16x32_bf16 v[114:117], v[192:195], v[144:147], v[114:117]
	v_mfma_f32_16x16x32_bf16 v[98:101], v[192:195], v[148:151], v[98:101]
	v_mfma_f32_16x16x32_bf16 v[82:85], v[192:195], v[152:155], v[82:85]
	v_mfma_f32_16x16x32_bf16 v[66:69], v[192:195], v[156:159], v[66:69]
	s_waitcnt vmcnt(6) lgkmcnt(0)
	s_barrier
; template <int MI, int NI>
; DI void gemm256(f32x4 (&acc)[MI][NI], const u16* __restrict__ A, int lda, const u16* __restrict__ Bt, int ldb, int K, int m0, int n0, char* smem) {
;     ...
;   for (int kt = 0; kt < nk; ++kt) {
;     if (kt + 1 < nk) asm volatile("s_waitcnt vmcnt(%0) lgkmcnt(0)" :: "n"(LPS) : "memory");
;     else asm volatile("s_waitcnt vmcnt(0) lgkmcnt(0)" ::: "memory");
;     __builtin_amdgcn_s_barrier();
;     __builtin_amdgcn_s_setprio(1);
;     const char* sb = smem + st * STAGE + foff;
;     bf16x8 af[MI], bfr[NI];
; #pragma unroll
;     for (int mi = 0; mi < MI; ++mi) af[mi] = *(const bf16x8*)(sb + (wr * MI + mi) * 1024);
; #pragma unroll
;     for (int ni = 0; ni < NI; ++ni) bfr[ni] = *(const bf16x8*)(sb + ABYTES + (wc * NI + ni) * 1024);
;     __builtin_amdgcn_sched_barrier(0x0);
;     if (kt + 2 < nk) { const int s2 = st >= 1 ? st - 1 : 2; G256_ISSUE(s2, (kt + 2) * 32); }
;     __builtin_amdgcn_s_setprio(0);
; #pragma unroll
;     for (int mi = 0; mi < MI; ++mi)
; #pragma unroll
;       for (int ni = 0; ni < NI; ++ni)
;         acc[mi][ni] = __builtin_amdgcn_mfma_f32_16x16x32_bf16(bfr[ni], af[mi], acc[mi][ni], 0, 0, 0);
;     st = st == 2 ? 0 : st + 1;
;   }
	s_add_i32 s9, s6, 0x6000
	s_cmp_eq_u32 s6, 0xc000
	s_cselect_b32 s6, 0, s9
	v_add_u32_e32 v196, s6, v143
	v_add_u32_e32 v197, s6, v0
	v_mfma_f32_16x16x32_bf16 v[62:65], v[180:183], v[164:167], v[62:65]
	ds_read_b128 v[144:147], v196
	v_mfma_f32_16x16x32_bf16 v[46:49], v[180:183], v[168:171], v[46:49]
	ds_read_b128 v[148:151], v196 offset:1024
	v_mfma_f32_16x16x32_bf16 v[30:33], v[180:183], v[172:175], v[30:33]
	ds_read_b128 v[152:155], v196 offset:2048
	v_mfma_f32_16x16x32_bf16 v[14:17], v[180:183], v[176:179], v[14:17]
	ds_read_b128 v[156:159], v196 offset:3072
	ds_read_b128 v[180:183], v197 offset:16384
	v_mfma_f32_16x16x32_bf16 v[58:61], v[184:187], v[164:167], v[58:61]
	v_mfma_f32_16x16x32_bf16 v[42:45], v[184:187], v[168:171], v[42:45]
	v_mfma_f32_16x16x32_bf16 v[26:29], v[184:187], v[172:175], v[26:29]
	v_mfma_f32_16x16x32_bf16 v[10:13], v[184:187], v[176:179], v[10:13]
	ds_read_b128 v[184:187], v197 offset:17408
	v_mfma_f32_16x16x32_bf16 v[54:57], v[188:191], v[164:167], v[54:57]
	v_mfma_f32_16x16x32_bf16 v[38:41], v[188:191], v[168:171], v[38:41]
	v_mfma_f32_16x16x32_bf16 v[22:25], v[188:191], v[172:175], v[22:25]
	v_mfma_f32_16x16x32_bf16 v[6:9], v[188:191], v[176:179], v[6:9]
	ds_read_b128 v[188:191], v197 offset:18432
	v_mfma_f32_16x16x32_bf16 v[50:53], v[192:195], v[164:167], v[50:53]
	v_mfma_f32_16x16x32_bf16 v[34:37], v[192:195], v[168:171], v[34:37]
	v_mfma_f32_16x16x32_bf16 v[18:21], v[192:195], v[172:175], v[18:21]
	v_mfma_f32_16x16x32_bf16 v[2:5], v[192:195], v[176:179], v[2:5]
	ds_read_b128 v[192:195], v197 offset:19456
	s_sub_i32 s1, s1, 1
	s_cmp_lg_u32 s1, 0
	s_cbranch_scc1 .Lpipe_zgemm
	v_add_u32_e32 v160, s6, v143
	ds_read_b128 v[164:167], v160 offset:4096
	ds_read_b128 v[168:171], v160 offset:5120
	ds_read_b128 v[172:175], v160 offset:6144
	ds_read_b128 v[176:179], v160 offset:7168
	s_add_i32 s8, s6, 0xffffa000
	s_cmp_eq_u32 s6, 0
	s_cselect_b32 s8, 0xc000, s8
	s_add_i32 s9, s8, s7
	s_add_i32 s8, s8, s0
	s_mov_b32 m0, s9
	s_waitcnt lgkmcnt(7)
	v_mfma_f32_16x16x32_bf16 v[126:129], v[180:183], v[144:147], v[126:129]
	global_load_lds_dwordx4 v[198:199], off
	v_mfma_f32_16x16x32_bf16 v[110:113], v[180:183], v[148:151], v[110:113]
	v_lshl_add_u64 v[198:199], v[198:199], 0, s[98:99]
	s_add_i32 m0, s9, 0x400
	v_mfma_f32_16x16x32_bf16 v[94:97], v[180:183], v[152:155], v[94:97]
	global_load_lds_dwordx4 v[200:201], off
	v_mfma_f32_16x16x32_bf16 v[78:81], v[180:183], v[156:159], v[78:81]
	v_lshl_add_u64 v[200:201], v[200:201], 0, s[98:99]
	s_add_i32 m0, s9, 0x800
	s_waitcnt lgkmcnt(6)
	v_mfma_f32_16x16x32_bf16 v[122:125], v[184:187], v[144:147], v[122:125]
	global_load_lds_dwordx4 v[202:203], off
	v_mfma_f32_16x16x32_bf16 v[106:109], v[184:187], v[148:151], v[106:109]
	v_lshl_add_u64 v[202:203], v[202:203], 0, s[98:99]
	s_add_i32 m0, s9, 0xc00
	v_mfma_f32_16x16x32_bf16 v[90:93], v[184:187], v[152:155], v[90:93]
	global_load_lds_dwordx4 v[204:205], off
	v_mfma_f32_16x16x32_bf16 v[74:77], v[184:187], v[156:159], v[74:77]
	v_lshl_add_u64 v[204:205], v[204:205], 0, s[98:99]
	s_mov_b32 m0, s8
	s_waitcnt lgkmcnt(5)
	v_mfma_f32_16x16x32_bf16 v[118:121], v[188:191], v[144:147], v[118:121]
	global_load_lds_dwordx4 v[206:207], off
	v_mfma_f32_16x16x32_bf16 v[102:105], v[188:191], v[148:151], v[102:105]
	v_lshl_add_u64 v[206:207], v[206:207], 0, 64
	s_add_i32 m0, s8, 0x400
	v_mfma_f32_16x16x32_bf16 v[86:89], v[188:191], v[152:155], v[86:89]
	global_load_lds_dwordx4 v[208:209], off
	v_mfma_f32_16x16x32_bf16 v[70:73], v[188:191], v[156:159], v[70:73]
	v_lshl_add_u64 v[208:209], v[208:209], 0, 64
	s_waitcnt lgkmcnt(4)
	v_mfma_f32_16x16x32_bf16 v[114:117], v[192:195], v[144:147], v[114:117]
	v_mfma_f32_16x16x32_bf16 v[98:101], v[192:195], v[148:151], v[98:101]
	v_mfma_f32_16x16x32_bf16 v[82:85], v[192:195], v[152:155], v[82:85]
	v_mfma_f32_16x16x32_bf16 v[66:69], v[192:195], v[156:159], v[66:69]
	s_waitcnt lgkmcnt(0)
	v_mfma_f32_16x16x32_bf16 v[62:65], v[180:183], v[164:167], v[62:65]
	v_mfma_f32_16x16x32_bf16 v[46:49], v[180:183], v[168:171], v[46:49]
	v_mfma_f32_16x16x32_bf16 v[30:33], v[180:183], v[172:175], v[30:33]
	v_mfma_f32_16x16x32_bf16 v[14:17], v[180:183], v[176:179], v[14:17]
	v_mfma_f32_16x16x32_bf16 v[58:61], v[184:187], v[164:167], v[58:61]
	v_mfma_f32_16x16x32_bf16 v[42:45], v[184:187], v[168:171], v[42:45]
	v_mfma_f32_16x16x32_bf16 v[26:29], v[184:187], v[172:175], v[26:29]
	v_mfma_f32_16x16x32_bf16 v[10:13], v[184:187], v[176:179], v[10:13]
	v_mfma_f32_16x16x32_bf16 v[54:57], v[188:191], v[164:167], v[54:57]
	v_mfma_f32_16x16x32_bf16 v[38:41], v[188:191], v[168:171], v[38:41]
	v_mfma_f32_16x16x32_bf16 v[22:25], v[188:191], v[172:175], v[22:25]
	v_mfma_f32_16x16x32_bf16 v[6:9], v[188:191], v[176:179], v[6:9]
	v_mfma_f32_16x16x32_bf16 v[50:53], v[192:195], v[164:167], v[50:53]
	v_mfma_f32_16x16x32_bf16 v[34:37], v[192:195], v[168:171], v[34:37]
	v_mfma_f32_16x16x32_bf16 v[18:21], v[192:195], v[172:175], v[18:21]
	v_mfma_f32_16x16x32_bf16 v[2:5], v[192:195], v[176:179], v[2:5]
	s_waitcnt vmcnt(6) lgkmcnt(0)
	s_barrier
	s_setprio 1
	v_add_u32_e32 v0, v140, v142
	s_waitcnt vmcnt(0)
	ds_read_b128 v[130:133], v0
	ds_read_b128 v[142:145], v0 offset:1024
	ds_read_b128 v[146:149], v0 offset:2048
	ds_read_b128 v[150:153], v0 offset:3072
	ds_read_b128 v[154:157], v0 offset:4096
	ds_read_b128 v[158:161], v0 offset:5120
	ds_read_b128 v[164:167], v0 offset:6144
	ds_read_b128 v[168:171], v0 offset:7168
	v_add_u32_e32 v220, v140, v141
	ds_read_b128 v[138:141], v220 offset:16384
	ds_read_b128 v[172:175], v220 offset:17408
	ds_read_b128 v[176:179], v220 offset:18432
	ds_read_b128 v[180:183], v220 offset:19456
	s_setprio 0
	s_waitcnt lgkmcnt(3)
	v_mfma_f32_16x16x32_bf16 v[126:129], v[138:141], v[130:133], v[126:129]
	s_waitcnt vmcnt(0) lgkmcnt(0)
	s_barrier
; DI unsigned pack2(float a, float b) { float2_t v = {a, b}; bf16x2_t r = __builtin_convertvector(v, bf16x2_t); return __builtin_bit_cast(unsigned, r); }
; #define EPI_BEGIN const int lr1_ = launder_v(lr), lq1_ = launder_v(lq), wr1_ = launder_v(wr), wc1_ = launder_v(wc); { const int lr = lr1_, lq = lq1_, wr = wr1_, wc = wc1_; (void)lr; (void)lq; (void)wr; (void)wc;
; template <int MI, int NI>
; DI void gemm256(f32x4 (&acc)[MI][NI], const u16* __restrict__ A, int lda, const u16* __restrict__ Bt, int ldb, int K, int m0, int n0, char* smem) {
;     ...
;         acc[mi][ni] = __builtin_amdgcn_mfma_f32_16x16x32_bf16(bfr[ni], af[mi], acc[mi][ni], 0, 0, 0);
; DI void phase_zgemm(const Params& p, int l, char* smem) {
;     ...
;     EPI_BEGIN
; #pragma unroll
;     for (int mi = 0; mi < 8; mi += 2) {
;       const int m = m0 + wr * 128 + (mi + (lq & 1)) * 16 + lr;
; #pragma unroll
;       for (int ni = 0; ni < 4; ++ni) {
;         const int n = n0 + wc * 64 + ni * 16 + (lq >> 1) * 8;
;         const uint4 v = widen16(make_uint2(pack2(acc[mi][ni][0], acc[mi][ni][1]), pack2(acc[mi][ni][2], acc[mi][ni][3])),
;                                 make_uint2(pack2(acc[mi + 1][ni][0], acc[mi + 1][ni][1]), pack2(acc[mi + 1][ni][2], acc[mi + 1][ni][3])));
;         if (n < ZA) *(uint4*)(za + (size_t)m * ZA + n) = v;
;         else if (n < ZA + ZR) *(uint4*)(zr + (size_t)m * ZR + (n - ZA)) = v;
;       }
;     }
;     EPI_END
	s_waitcnt lgkmcnt(2)
	v_mfma_f32_16x16x32_bf16 v[122:125], v[172:175], v[130:133], v[122:125]
	s_waitcnt lgkmcnt(1)
	v_mfma_f32_16x16x32_bf16 v[118:121], v[176:179], v[130:133], v[118:121]
	s_waitcnt lgkmcnt(0)
	v_mfma_f32_16x16x32_bf16 v[130:133], v[180:183], v[130:133], v[114:117]
	v_mfma_f32_16x16x32_bf16 v[110:113], v[138:141], v[142:145], v[110:113]
	v_mfma_f32_16x16x32_bf16 v[102:105], v[176:179], v[142:145], v[102:105]
	v_mfma_f32_16x16x32_bf16 v[94:97], v[138:141], v[146:149], v[94:97]
	v_mfma_f32_16x16x32_bf16 v[86:89], v[176:179], v[146:149], v[86:89]
	v_mfma_f32_16x16x32_bf16 v[78:81], v[138:141], v[150:153], v[78:81]
	v_mfma_f32_16x16x32_bf16 v[70:73], v[176:179], v[150:153], v[70:73]
	v_mfma_f32_16x16x32_bf16 v[62:65], v[138:141], v[154:157], v[62:65]
	v_mfma_f32_16x16x32_bf16 v[54:57], v[176:179], v[154:157], v[54:57]
	v_mfma_f32_16x16x32_bf16 v[46:49], v[138:141], v[158:161], v[46:49]
	v_mfma_f32_16x16x32_bf16 v[38:41], v[176:179], v[158:161], v[38:41]
	v_mfma_f32_16x16x32_bf16 v[30:33], v[138:141], v[164:167], v[30:33]
	v_mfma_f32_16x16x32_bf16 v[22:25], v[176:179], v[164:167], v[22:25]
	v_mfma_f32_16x16x32_bf16 v[14:17], v[138:141], v[168:171], v[14:17]
	v_mfma_f32_16x16x32_bf16 v[6:9], v[176:179], v[168:171], v[6:9]
	v_mfma_f32_16x16x32_bf16 v[184:187], v[172:175], v[142:145], v[106:109]
	v_mfma_f32_16x16x32_bf16 v[142:145], v[180:183], v[142:145], v[98:101]
	v_mfma_f32_16x16x32_bf16 v[188:191], v[172:175], v[146:149], v[90:93]
	v_mfma_f32_16x16x32_bf16 v[146:149], v[180:183], v[146:149], v[82:85]
	v_mfma_f32_16x16x32_bf16 v[192:195], v[172:175], v[150:153], v[74:77]
	v_mfma_f32_16x16x32_bf16 v[150:153], v[180:183], v[150:153], v[66:69]
	v_mfma_f32_16x16x32_bf16 v[196:199], v[172:175], v[154:157], v[58:61]
	v_mfma_f32_16x16x32_bf16 v[154:157], v[180:183], v[154:157], v[50:53]
	v_mfma_f32_16x16x32_bf16 v[200:203], v[172:175], v[158:161], v[42:45]
	v_mfma_f32_16x16x32_bf16 v[158:161], v[180:183], v[158:161], v[34:37]
	v_mfma_f32_16x16x32_bf16 v[204:207], v[172:175], v[164:167], v[26:29]
	v_mfma_f32_16x16x32_bf16 v[164:167], v[180:183], v[164:167], v[18:21]
	v_mfma_f32_16x16x32_bf16 v[138:141], v[172:175], v[168:171], v[10:13]
	v_mfma_f32_16x16x32_bf16 v[168:171], v[180:183], v[168:171], v[2:5]
	s_setprio 1
	s_nop 1
	ds_read_b128 v[2:5], v0 offset:24576
	ds_read_b128 v[10:13], v0 offset:25600
	ds_read_b128 v[18:21], v0 offset:26624
	ds_read_b128 v[26:29], v0 offset:27648
	ds_read_b128 v[34:37], v0 offset:28672
	ds_read_b128 v[172:175], v0 offset:29696
	ds_read_b128 v[176:179], v0 offset:30720
	ds_read_b128 v[180:183], v0 offset:31744
	ds_read_b128 v[208:211], v220 offset:40960
	ds_read_b128 v[212:215], v220 offset:41984
	ds_read_b128 v[216:219], v220 offset:43008
	ds_read_b128 v[220:223], v220 offset:44032
	s_setprio 0
	s_waitcnt lgkmcnt(3)
	v_mfma_f32_16x16x32_bf16 v[224:227], v[208:211], v[2:5], v[126:129]
	v_mov_b32_e32 v0, v136
	s_waitcnt lgkmcnt(0)
	s_barrier
	s_waitcnt lgkmcnt(2)
	v_mfma_f32_16x16x32_bf16 v[114:117], v[212:215], v[2:5], v[122:125]
	s_movk_i32 s0, 0x900
	s_waitcnt lgkmcnt(1)
	v_mfma_f32_16x16x32_bf16 v[106:109], v[216:219], v[2:5], v[118:121]
	s_nop 0
	v_cvt_pk_bf16_f32 v122, v224, v225
	v_cvt_pk_bf16_f32 v123, v226, v227
	s_waitcnt lgkmcnt(0)
	v_mfma_f32_16x16x32_bf16 v[98:101], v[220:223], v[2:5], v[130:133]
	v_mov_b32_e32 v2, v137
	v_mov_b32_e32 v3, v134
	v_mov_b32_e32 v4, v135
	v_lshlrev_b32_e32 v3, 7, v3
	v_add3_u32 v132, v0, s5, v3
	v_lshlrev_b32_e32 v3, 2, v2
	v_and_b32_e32 v3, -8, v3
	v_lshlrev_b32_e32 v0, 6, v4
	v_add3_u32 v126, v3, s4, v0
	v_lshlrev_b32_e32 v0, 4, v2
	v_mfma_f32_16x16x32_bf16 v[228:231], v[208:211], v[10:13], v[110:113]
	v_and_b32_e32 v133, 16, v0
	v_add_u32_e32 v0, v132, v133
	v_mfma_f32_16x16x32_bf16 v[118:121], v[212:215], v[10:13], v[184:187]
	v_mfma_f32_16x16x32_bf16 v[110:113], v[216:219], v[10:13], v[102:105]
	s_nop 3
	v_cvt_pk_bf16_f32 v124, v228, v229
	v_cvt_pk_bf16_f32 v125, v230, v231
	s_nop 0
	v_permlane16_swap_b32_e32 v122, v124
	v_mfma_f32_16x16x32_bf16 v[102:105], v[220:223], v[10:13], v[142:145]
	v_permlane16_swap_b32_e32 v123, v125
	v_mfma_f32_16x16x32_bf16 v[10:13], v[216:219], v[176:179], v[22:25]
	s_nop 2
	v_mov_b64_e32 v[22:23], s[62:63]
	v_mfma_f32_16x16x32_bf16 v[90:93], v[208:211], v[18:21], v[94:97]
	v_mad_i64_i32 v[128:129], s[0:1], v0, s0, v[22:23]
	s_movk_i32 s0, 0x39f
	v_mfma_f32_16x16x32_bf16 v[82:85], v[212:215], v[18:21], v[188:191]
	v_cmp_lt_i32_e64 s[0:1], s0, v126
	v_mfma_f32_16x16x32_bf16 v[74:77], v[216:219], v[18:21], v[86:89]
	v_mfma_f32_16x16x32_bf16 v[66:69], v[220:223], v[18:21], v[146:149]
	v_mfma_f32_16x16x32_bf16 v[94:97], v[208:211], v[26:29], v[78:81]
	v_mfma_f32_16x16x32_bf16 v[86:89], v[212:215], v[26:29], v[192:195]
	v_mfma_f32_16x16x32_bf16 v[78:81], v[216:219], v[26:29], v[70:73]
	v_mfma_f32_16x16x32_bf16 v[70:73], v[220:223], v[26:29], v[150:153]
	v_mfma_f32_16x16x32_bf16 v[58:61], v[208:211], v[34:37], v[62:65]
	v_mfma_f32_16x16x32_bf16 v[50:53], v[212:215], v[34:37], v[196:199]
	v_mfma_f32_16x16x32_bf16 v[42:45], v[216:219], v[34:37], v[54:57]
	v_mfma_f32_16x16x32_bf16 v[34:37], v[220:223], v[34:37], v[154:157]
	v_mfma_f32_16x16x32_bf16 v[62:65], v[208:211], v[172:175], v[46:49]
	v_mfma_f32_16x16x32_bf16 v[54:57], v[212:215], v[172:175], v[200:203]
	v_mfma_f32_16x16x32_bf16 v[46:49], v[216:219], v[172:175], v[38:41]
	v_mfma_f32_16x16x32_bf16 v[38:41], v[220:223], v[172:175], v[158:161]
	v_mfma_f32_16x16x32_bf16 v[26:29], v[208:211], v[176:179], v[30:33]
	v_mfma_f32_16x16x32_bf16 v[18:21], v[212:215], v[176:179], v[204:207]
	v_mfma_f32_16x16x32_bf16 v[2:5], v[220:223], v[176:179], v[164:167]
	v_mfma_f32_16x16x32_bf16 v[30:33], v[208:211], v[180:183], v[14:17]
	v_mfma_f32_16x16x32_bf16 v[22:25], v[212:215], v[180:183], v[138:141]
	v_mfma_f32_16x16x32_bf16 v[14:17], v[216:219], v[180:183], v[6:9]
	v_mfma_f32_16x16x32_bf16 v[6:9], v[220:223], v[180:183], v[168:171]
	s_and_saveexec_b64 s[4:5], s[0:1]
	s_xor_b64 s[4:5], exec, s[4:5]
	s_cbranch_execz .LBB0_862
	s_movk_i32 s6, 0x820
	v_cmp_gt_u32_e32 vcc, s6, v126
	s_and_saveexec_b64 s[6:7], vcc
	s_cbranch_execz .LBB0_861
	v_mov_b32_e32 v127, v1
	v_lshl_add_u64 v[130:131], v[126:127], 1, v[128:129]
	v_add_co_u32_e32 v130, vcc, 0x47e0000, v130
	s_nop 1
	v_addc_co_u32_e32 v131, vcc, 0, v131, vcc
	flat_store_dwordx4 v[130:131], v[122:125] offset:2240

; #define LAUNDER_IDS const int tid__ = launder_v((int)threadIdx.x); const int blk__ = launder_s((int)blockIdx.x); (void)tid__; (void)blk__;
; template <int MI, int NI>
; DI void gemm256(f32x4 (&acc)[MI][NI], const u16* __restrict__ A, int lda, const u16* __restrict__ Bt, int ldb, int K, int m0, int n0, char* smem) {
;     ...
;   const int srow = lane >> 2, scol = ((lane & 3) ^ ((lane >> 5) << 1)) * 8;
;   const u16* Ag = A + (size_t)(m0 + wave * NAW * 16 + srow) * lda + scol;
;   const u16* Bg = Bt + (size_t)(n0 + wave * NBW * 16 + srow) * ldb + scol;
;   char* la = smem + (wave * NAW) * 1024 + lane * 16;
;   char* lb = smem + ABYTES + (wave * NBW) * 1024 + lane * 16;
;     ...
;   const int nk = K >> 5;
;   G256_ISSUE(0, 0);
;   if (nk > 1) G256_ISSUE(1, 32);
; template <int MI, int NI>
; DI void resid_tile(const u16* A, int K, const u16* Bt, const float* gate, const float* xl_in, const float* xc_in, float* xl_out, float* xc_out,
;                    int m0, int n0, char* smem) {
;   LAUNDER_IDS
;   WAVE_COORDS
;   f32x4 acc[MI][NI]; zero_accm<MI, NI>(acc);
;   gemm256<MI, NI>(acc, A, K, Bt, K, K, m0, n0, smem);
; DI void phase_resid(const Params& p, const u16* A, int K, const u16* Bt, const float* gate  ,
;                     const float* xl_in, const float* xc_in, float* xl_out, float* xc_out, int Mout, char* smem) {
;     ...
;   for (int it = 0;; ++it) {
;     int tm, tn;
;     if (!tile_map(it, NTL / 256, 8, blk__, gridDim.x, tm, tn)) break;
;     resid_tile<8, 4>(A, K, Bt, gate, xl_in, xc_in, xl_out, xc_out, tm * 256, tn * 128, smem);
.LBB0_961:
	s_ashr_i32 s1, s0, 31
	s_lshr_b32 s1, s1, 26
	s_add_i32 s1, s0, s1
	s_and_b32 s8, s1, 0xffffffc0
	s_sub_i32 s0, s0, s8
	s_ashr_i32 s8, s0, 31
	s_lshr_b32 s8, s8, 26
	s_add_i32 s9, s0, s8
	s_and_b32 s8, s9, 0xffffffc0
	s_sub_i32 s0, s0, s8
	s_ashr_i32 s8, s0, 31
	s_lshr_b32 s8, s8, 29
	s_lshr_b32 s1, s1, 3
	s_add_i32 s10, s0, s8
	s_and_b32 s1, s1, 0x1ffffff8
	s_and_b32 s8, s10, 0xfffff8
	s_sub_i32 s0, s0, s8
	s_add_i32 s1, s1, s6
	s_add_i32 s1, s1, s0
	s_lshl_b32 s8, s1, 8
	s_lshl_b32 s0, s9, 4
	s_lshl_b32 s1, s10, 4
	s_and_b32 s0, s0, 0xfffffc00
	s_and_b32 s9, s1, 0xffffff80
	s_add_i32 s9, s9, s0
	v_mov_b32_e32 v134, v163
	s_mov_b32 s0, s2
	s_waitcnt vmcnt(0)
	v_mov_b32_e32 v10, v163
	s_mov_b32 s0, s2
	v_ashrrev_i32_e32 v9, 6, v10
	v_and_b32_e32 v0, 3, v10
	v_lshrrev_b32_e32 v2, 4, v10
	v_bitop3_b32 v0, v2, v0, 2 bitop3:0x6c
	v_and_b32_e32 v2, 0xffffffc0, v10
	v_lshlrev_b32_e32 v12, 5, v9
	v_bfe_u32 v11, v10, 2, 4
	v_add_u32_e32 v2, s8, v2
	v_add_u32_e32 v6, s9, v12
	v_and_b32_e32 v8, 63, v10
	v_or_b32_e32 v2, v2, v11
	v_or_b32_e32 v6, v6, v11
	v_ashrrev_i32_e32 v3, 31, v2
	v_ashrrev_i32_e32 v7, 31, v6
	v_readlane_b32 s0, v254, 54
	v_lshlrev_b32_e32 v13, 12, v9
	v_lshlrev_b32_e32 v8, 4, v8
	v_lshlrev_b64 v[2:3], 13, v[2:3]
	v_lshlrev_b64 v[6:7], 13, v[6:7]
	v_readlane_b32 s1, v254, 55
	v_or_b32_e32 v136, v13, v8
	v_lshl_add_u64 v[4:5], s[60:61], 0, v[2:3]
	v_lshlrev_b32_e32 v0, 4, v0
	v_lshl_add_u64 v[6:7], s[0:1], 0, v[6:7]
	v_readfirstlane_b32 s0, v136
	v_or_b32_e32 v15, 0x400, v136
	v_lshl_add_u64 v[4:5], v[4:5], 0, v[0:1]
	v_bfe_i32 v199, v163, 2, 1
	v_and_b32_e32 v198, 0xffffe040, v199
	v_lshl_add_u64 v[4:5], v[4:5], 0, v[198:199]
	s_mov_b32 m0, s0
	s_mov_b64 s[10:11], 0x20000
	v_readfirstlane_b32 s0, v15
	v_lshl_or_b32 v137, v9, 11, v8
	global_load_lds_dwordx4 v[4:5], off
	v_lshl_add_u64 v[8:9], v[4:5], 0, s[10:11]
	s_mov_b32 m0, s0
	s_mov_b64 s[0:1], 0x40000
	v_or_b32_e32 v15, 0x800, v136
	global_load_lds_dwordx4 v[8:9], off
	v_lshl_add_u64 v[8:9], v[4:5], 0, s[0:1]
	v_readfirstlane_b32 s0, v15
	s_mov_b32 m0, s0
	s_mov_b64 s[0:1], 0x60000
	v_or_b32_e32 v15, 0xc00, v136
	v_add_u32_e32 v14, 0x4000, v137
	global_load_lds_dwordx4 v[8:9], off
	v_lshl_add_u64 v[8:9], v[4:5], 0, s[0:1]
	v_readfirstlane_b32 s0, v15
	s_mov_b32 m0, s0
	v_readfirstlane_b32 s0, v14
	v_add_u32_e32 v14, 0x4400, v137
	global_load_lds_dwordx4 v[8:9], off
	v_lshl_add_u64 v[6:7], v[6:7], 0, v[0:1]
	s_mov_b32 m0, s0
	v_readfirstlane_b32 s0, v14
	v_add_u32_e32 v14, 0x6000, v136
	global_load_lds_dwordx4 v[6:7], off
	v_lshl_add_u64 v[8:9], v[6:7], 0, s[10:11]
	s_mov_b32 m0, s0
	v_readfirstlane_b32 s0, v14
	v_add_u32_e32 v14, 0x6400, v136
	global_load_lds_dwordx4 v[8:9], off
	s_mov_b64 s[98:99], 0x80
	v_lshl_add_u64 v[8:9], v[4:5], 0, s[98:99]
	s_mov_b32 m0, s0
	s_mov_b64 s[10:11], 0x20040
	v_readfirstlane_b32 s0, v14
	global_load_lds_dwordx4 v[8:9], off
	s_mov_b64 s[98:99], 0x20080
	v_lshl_add_u64 v[8:9], v[4:5], 0, s[98:99]
	s_mov_b32 m0, s0
	s_mov_b64 s[0:1], 0x40080
	v_add_u32_e32 v14, 0x6800, v136
	global_load_lds_dwordx4 v[8:9], off
	v_lshl_add_u64 v[8:9], v[4:5], 0, s[0:1]
	v_readfirstlane_b32 s0, v14
	s_mov_b32 m0, s0
	s_mov_b64 s[0:1], 0x60080
	global_load_lds_dwordx4 v[8:9], off
	v_add_u32_e32 v8, 0x6c00, v136
	v_lshl_add_u64 v[4:5], v[4:5], 0, s[0:1]
	v_readfirstlane_b32 s0, v8
	v_add_u32_e32 v8, 0xa000, v137
	s_mov_b32 m0, s0
	v_readfirstlane_b32 s0, v8
	global_load_lds_dwordx4 v[4:5], off
	v_lshl_add_u64 v[4:5], v[6:7], 0, 64
	s_mov_b32 m0, s0
	v_or_b32_e32 v2, v2, v0
	global_load_lds_dwordx4 v[4:5], off
	v_lshl_add_u64 v[4:5], v[6:7], 0, s[10:11]
	v_add_u32_e32 v6, 0xa400, v137
	v_lshl_add_u64 v[132:133], s[62:63], 0, v[2:3]
	v_readfirstlane_b32 s0, v6
	s_mov_b32 m0, s0
	v_and_b32_e32 v6, 48, v10
	global_load_lds_dwordx4 v[4:5], off
	v_lshlrev_b32_e32 v5, 2, v10
	v_lshlrev_b32_e32 v4, 6, v10
	v_bitop3_b32 v5, v5, v6, 32 bitop3:0x6c
	v_and_or_b32 v138, v4, s59, v5
	v_and_b32_e32 v139, 0xffffe000, v4
	v_or_b32_e32 v4, s9, v11
	v_add_u32_e32 v4, v4, v12
	v_ashrrev_i32_e32 v5, 31, v4
	v_lshlrev_b64 v[4:5], 13, v[4:5]
	v_readlane_b32 s0, v254, 52
	v_or_b32_e32 v4, v4, v0
	v_readlane_b32 s1, v254, 53
	v_mov_b32_e32 v2, 0
	v_and_b32_e32 v135, 0x1000, v13
	v_lshl_add_u64 v[130:131], s[0:1], 0, v[4:5]
	s_mov_b64 s[0:1], 0
	s_mov_b32 s10, 0
	v_mov_b32_e32 v3, v2
	v_mov_b32_e32 v4, v2
	v_mov_b32_e32 v5, v2
	v_mov_b32_e32 v6, v2
	v_mov_b32_e32 v7, v2
	v_mov_b32_e32 v8, v2
	v_mov_b32_e32 v9, v2
	v_mov_b32_e32 v10, v2
	v_mov_b32_e32 v11, v2
	v_mov_b32_e32 v12, v2
	v_mov_b32_e32 v13, v2
	v_mov_b32_e32 v14, v2
	v_mov_b32_e32 v15, v2
	v_mov_b32_e32 v16, v2
	v_mov_b32_e32 v17, v2
	v_mov_b32_e32 v18, v2
	v_mov_b32_e32 v19, v2
	v_mov_b32_e32 v20, v2
	v_mov_b32_e32 v21, v2
	v_mov_b32_e32 v22, v2
	v_mov_b32_e32 v23, v2
	v_mov_b32_e32 v24, v2
	v_mov_b32_e32 v25, v2
	s_waitcnt lgkmcnt(0)
; template <int MI, int NI>
; DI void gemm256(f32x4 (&acc)[MI][NI], const u16* __restrict__ A, int lda, const u16* __restrict__ Bt, int ldb, int K, int m0, int n0, char* smem) {
;     ...
;   const int nk = K >> 5;
;   G256_ISSUE(0, 0);
;   if (nk > 1) G256_ISSUE(1, 32);
;   const int foff = lr * 64 + ((lq ^ ((lr >> 3) << 1)) * 16);
;   int st = 0;
;   for (int kt = 0; kt < nk; ++kt) {
;     if (kt + 1 < nk) asm volatile("s_waitcnt vmcnt(%0) lgkmcnt(0)" :: "n"(LPS) : "memory");
;     else asm volatile("s_waitcnt vmcnt(0) lgkmcnt(0)" ::: "memory");
;     __builtin_amdgcn_s_barrier();
;     __builtin_amdgcn_s_setprio(1);
;     const char* sb = smem + st * STAGE + foff;
;     bf16x8 af[MI], bfr[NI];
; #pragma unroll
;     for (int mi = 0; mi < MI; ++mi) af[mi] = *(const bf16x8*)(sb + (wr * MI + mi) * 1024);
; #pragma unroll
;     for (int ni = 0; ni < NI; ++ni) bfr[ni] = *(const bf16x8*)(sb + ABYTES + (wc * NI + ni) * 1024);
;     __builtin_amdgcn_sched_barrier(0x0);
;     if (kt + 2 < nk) { const int s2 = st >= 1 ? st - 1 : 2; G256_ISSUE(s2, (kt + 2) * 32); }
;     __builtin_amdgcn_s_setprio(0);
; #pragma unroll
;     for (int mi = 0; mi < MI; ++mi)
; #pragma unroll
;       for (int ni = 0; ni < NI; ++ni)
;         acc[mi][ni] = __builtin_amdgcn_mfma_f32_16x16x32_bf16(bfr[ni], af[mi], acc[mi][ni], 0, 0, 0);
;     st = st == 2 ? 0 : st + 1;
;   }
; template <int MI, int NI>
; DI void resid_tile(const u16* A, int K, const u16* Bt, const float* gate, const float* xl_in, const float* xc_in, float* xl_out, float* xc_out,
;                    int m0, int n0, char* smem) {
;     ...
;   f32x4 acc[MI][NI]; zero_accm<MI, NI>(acc);
;   gemm256<MI, NI>(acc, A, K, Bt, K, K, m0, n0, smem);
	v_mov_b32_e32 v26, v2
	v_mov_b32_e32 v27, v2
	v_mov_b32_e32 v28, v2
	v_mov_b32_e32 v29, v2
	v_mov_b32_e32 v30, v2
	v_mov_b32_e32 v31, v2
	v_mov_b32_e32 v32, v2
	v_mov_b32_e32 v33, v2
	v_mov_b32_e32 v34, v2
	v_mov_b32_e32 v35, v2
	v_mov_b32_e32 v36, v2
	v_mov_b32_e32 v37, v2
	v_mov_b32_e32 v38, v2
	v_mov_b32_e32 v39, v2
	v_mov_b32_e32 v40, v2
	v_mov_b32_e32 v41, v2
	v_mov_b32_e32 v42, v2
	v_mov_b32_e32 v43, v2
	v_mov_b32_e32 v44, v2
	v_mov_b32_e32 v45, v2
	v_mov_b32_e32 v46, v2
	v_mov_b32_e32 v47, v2
	v_mov_b32_e32 v48, v2
	v_mov_b32_e32 v49, v2
	v_mov_b32_e32 v50, v2
	v_mov_b32_e32 v51, v2
	v_mov_b32_e32 v52, v2
	v_mov_b32_e32 v53, v2
	v_mov_b32_e32 v54, v2
	v_mov_b32_e32 v55, v2
	v_mov_b32_e32 v56, v2
	v_mov_b32_e32 v57, v2
	v_mov_b32_e32 v58, v2
	v_mov_b32_e32 v59, v2
	v_mov_b32_e32 v60, v2
	v_mov_b32_e32 v61, v2
	v_mov_b32_e32 v62, v2
	v_mov_b32_e32 v63, v2
	v_mov_b32_e32 v64, v2
	v_mov_b32_e32 v65, v2
	v_mov_b32_e32 v66, v2
	v_mov_b32_e32 v67, v2
	v_mov_b32_e32 v68, v2
	v_mov_b32_e32 v69, v2
	v_mov_b32_e32 v70, v2
	v_mov_b32_e32 v71, v2
	v_mov_b32_e32 v72, v2
	v_mov_b32_e32 v73, v2
	v_mov_b32_e32 v74, v2
	v_mov_b32_e32 v75, v2
	v_mov_b32_e32 v76, v2
	v_mov_b32_e32 v77, v2
	v_mov_b32_e32 v78, v2
	v_mov_b32_e32 v79, v2
	v_mov_b32_e32 v80, v2
	v_mov_b32_e32 v81, v2
	v_mov_b32_e32 v82, v2
	v_mov_b32_e32 v83, v2
	v_mov_b32_e32 v84, v2
	v_mov_b32_e32 v85, v2
	v_mov_b32_e32 v86, v2
	v_mov_b32_e32 v87, v2
	v_mov_b32_e32 v88, v2
	v_mov_b32_e32 v89, v2
	v_mov_b32_e32 v90, v2
	v_mov_b32_e32 v91, v2
	v_mov_b32_e32 v92, v2
	v_mov_b32_e32 v93, v2
	v_mov_b32_e32 v94, v2
	v_mov_b32_e32 v95, v2
	v_mov_b32_e32 v96, v2
	v_mov_b32_e32 v97, v2
	v_mov_b32_e32 v98, v2
	v_mov_b32_e32 v99, v2
	v_mov_b32_e32 v100, v2
	v_mov_b32_e32 v101, v2
	v_mov_b32_e32 v102, v2
	v_mov_b32_e32 v103, v2
	v_mov_b32_e32 v104, v2
	v_mov_b32_e32 v105, v2
	v_mov_b32_e32 v106, v2
	v_mov_b32_e32 v107, v2
	v_mov_b32_e32 v108, v2
	v_mov_b32_e32 v109, v2
	v_mov_b32_e32 v110, v2
	v_mov_b32_e32 v111, v2
	v_mov_b32_e32 v112, v2
	v_mov_b32_e32 v113, v2
	v_mov_b32_e32 v114, v2
	v_mov_b32_e32 v115, v2
	v_mov_b32_e32 v116, v2
	v_mov_b32_e32 v117, v2
	v_mov_b32_e32 v118, v2
	v_mov_b32_e32 v119, v2
	v_mov_b32_e32 v120, v2
	v_mov_b32_e32 v121, v2
	v_mov_b32_e32 v122, v2
	v_mov_b32_e32 v123, v2
	v_mov_b32_e32 v124, v2
	v_mov_b32_e32 v125, v2
	v_mov_b32_e32 v126, v2
	v_mov_b32_e32 v127, v2
	v_mov_b32_e32 v128, v2
	v_mov_b32_e32 v129, v2
	s_mov_b64 s[12:13], 0x47e1100
	v_lshl_add_u64 v[196:197], v[132:133], 0, s[12:13]
	s_mov_b64 s[12:13], 0x4801100
	v_lshl_add_u64 v[198:199], v[132:133], 0, s[12:13]
	s_mov_b64 s[12:13], 0x4821100
	v_lshl_add_u64 v[200:201], v[132:133], 0, s[12:13]
	s_mov_b64 s[12:13], 0x4841100
	v_lshl_add_u64 v[202:203], v[132:133], 0, s[12:13]
	s_mov_b64 s[12:13], 0x2061080
	v_lshl_add_u64 v[204:205], v[130:131], 0, s[12:13]
	s_mov_b64 s[12:13], 0x2081080
	v_lshl_add_u64 v[206:207], v[130:131], 0, s[12:13]
	v_bfe_i32 v193, v163, 2, 1
	v_and_b32_e32 v192, 0xffffe040, v193
	v_lshl_add_u64 v[196:197], v[196:197], 0, v[192:193]
	v_lshl_add_u64 v[198:199], v[198:199], 0, v[192:193]
	v_lshl_add_u64 v[200:201], v[200:201], 0, v[192:193]
	v_lshl_add_u64 v[202:203], v[202:203], 0, v[192:193]
	s_mov_b64 s[98:99], 0x80
	v_add_u32_e32 v160, v138, v139
	v_add_u32_e32 v0, v138, v135
	v_readfirstlane_b32 s0, v136
	v_readfirstlane_b32 s1, v137
	s_mov_b32 s11, 0
	s_movk_i32 s100, 125
	s_add_i32 s1, s1, 0x4000
	s_waitcnt vmcnt(6) lgkmcnt(0)
	s_barrier
	ds_read_b128 v[140:143], v160
	ds_read_b128 v[144:147], v160 offset:1024
	ds_read_b128 v[148:151], v160 offset:2048
	ds_read_b128 v[152:155], v160 offset:3072
	ds_read_b128 v[176:179], v0 offset:16384
	ds_read_b128 v[180:183], v0 offset:17408
	ds_read_b128 v[184:187], v0 offset:18432
	ds_read_b128 v[188:191], v0 offset:19456
.Lpipe_mlp2:
	v_add_u32_e32 v161, s11, v160
	ds_read_b128 v[156:159], v161 offset:4096
	ds_read_b128 v[164:167], v161 offset:5120
	ds_read_b128 v[168:171], v161 offset:6144
	ds_read_b128 v[172:175], v161 offset:7168
	s_add_i32 s12, s11, 0xffffa000
	s_cmp_eq_u32 s11, 0
	s_cselect_b32 s12, 0xc000, s12
	s_add_i32 s13, s12, s0
	s_add_i32 s12, s12, s1
	s_mov_b32 m0, s13
	s_waitcnt lgkmcnt(7)
	v_mfma_f32_16x16x32_bf16 v[126:129], v[176:179], v[140:143], v[126:129]
	global_load_lds_dwordx4 v[196:197], off
	v_mfma_f32_16x16x32_bf16 v[110:113], v[176:179], v[144:147], v[110:113]
	v_lshl_add_u64 v[196:197], v[196:197], 0, s[98:99]
	s_add_i32 m0, s13, 0x400
	v_mfma_f32_16x16x32_bf16 v[94:97], v[176:179], v[148:151], v[94:97]
	global_load_lds_dwordx4 v[198:199], off
	v_mfma_f32_16x16x32_bf16 v[78:81], v[176:179], v[152:155], v[78:81]
	v_lshl_add_u64 v[198:199], v[198:199], 0, s[98:99]
	s_add_i32 m0, s13, 0x800
	s_waitcnt lgkmcnt(6)
	v_mfma_f32_16x16x32_bf16 v[122:125], v[180:183], v[140:143], v[122:125]
	global_load_lds_dwordx4 v[200:201], off
	v_mfma_f32_16x16x32_bf16 v[106:109], v[180:183], v[144:147], v[106:109]
	v_lshl_add_u64 v[200:201], v[200:201], 0, s[98:99]
	s_add_i32 m0, s13, 0xc00
	v_mfma_f32_16x16x32_bf16 v[90:93], v[180:183], v[148:151], v[90:93]
	global_load_lds_dwordx4 v[202:203], off
	v_mfma_f32_16x16x32_bf16 v[74:77], v[180:183], v[152:155], v[74:77]
	v_lshl_add_u64 v[202:203], v[202:203], 0, s[98:99]
	s_mov_b32 m0, s12
	s_waitcnt lgkmcnt(5)
	v_mfma_f32_16x16x32_bf16 v[118:121], v[184:187], v[140:143], v[118:121]
	global_load_lds_dwordx4 v[204:205], off
	v_mfma_f32_16x16x32_bf16 v[102:105], v[184:187], v[144:147], v[102:105]
	v_lshl_add_u64 v[204:205], v[204:205], 0, 64
	s_add_i32 m0, s12, 0x400
	v_mfma_f32_16x16x32_bf16 v[86:89], v[184:187], v[148:151], v[86:89]
	global_load_lds_dwordx4 v[206:207], off
	v_mfma_f32_16x16x32_bf16 v[70:73], v[184:187], v[152:155], v[70:73]
	v_lshl_add_u64 v[206:207], v[206:207], 0, 64
	s_waitcnt lgkmcnt(4)
	v_mfma_f32_16x16x32_bf16 v[114:117], v[188:191], v[140:143], v[114:117]
	v_mfma_f32_16x16x32_bf16 v[98:101], v[188:191], v[144:147], v[98:101]
	v_mfma_f32_16x16x32_bf16 v[82:85], v[188:191], v[148:151], v[82:85]
	v_mfma_f32_16x16x32_bf16 v[66:69], v[188:191], v[152:155], v[66:69]
	s_waitcnt vmcnt(6) lgkmcnt(0)
	s_barrier
; template <int MI, int NI>
; DI void gemm256(f32x4 (&acc)[MI][NI], const u16* __restrict__ A, int lda, const u16* __restrict__ Bt, int ldb, int K, int m0, int n0, char* smem) {
;     ...
;   for (int kt = 0; kt < nk; ++kt) {
;     if (kt + 1 < nk) asm volatile("s_waitcnt vmcnt(%0) lgkmcnt(0)" :: "n"(LPS) : "memory");
;     else asm volatile("s_waitcnt vmcnt(0) lgkmcnt(0)" ::: "memory");
;     __builtin_amdgcn_s_barrier();
;     __builtin_amdgcn_s_setprio(1);
;     const char* sb = smem + st * STAGE + foff;
;     bf16x8 af[MI], bfr[NI];
; #pragma unroll
;     for (int mi = 0; mi < MI; ++mi) af[mi] = *(const bf16x8*)(sb + (wr * MI + mi) * 1024);
; #pragma unroll
;     for (int ni = 0; ni < NI; ++ni) bfr[ni] = *(const bf16x8*)(sb + ABYTES + (wc * NI + ni) * 1024);
;     __builtin_amdgcn_sched_barrier(0x0);
;     if (kt + 2 < nk) { const int s2 = st >= 1 ? st - 1 : 2; G256_ISSUE(s2, (kt + 2) * 32); }
;     __builtin_amdgcn_s_setprio(0);
; #pragma unroll
;     for (int mi = 0; mi < MI; ++mi)
; #pragma unroll
;       for (int ni = 0; ni < NI; ++ni)
;         acc[mi][ni] = __builtin_amdgcn_mfma_f32_16x16x32_bf16(bfr[ni], af[mi], acc[mi][ni], 0, 0, 0);
;     st = st == 2 ? 0 : st + 1;
;   }
	s_add_i32 s13, s11, 0x6000
	s_cmp_eq_u32 s11, 0xc000
	s_cselect_b32 s11, 0, s13
	v_add_u32_e32 v192, s11, v160
	v_add_u32_e32 v193, s11, v0
	v_mfma_f32_16x16x32_bf16 v[62:65], v[176:179], v[156:159], v[62:65]
	ds_read_b128 v[140:143], v192
	v_mfma_f32_16x16x32_bf16 v[46:49], v[176:179], v[164:167], v[46:49]
	ds_read_b128 v[144:147], v192 offset:1024
	v_mfma_f32_16x16x32_bf16 v[30:33], v[176:179], v[168:171], v[30:33]
	ds_read_b128 v[148:151], v192 offset:2048
	v_mfma_f32_16x16x32_bf16 v[14:17], v[176:179], v[172:175], v[14:17]
	ds_read_b128 v[152:155], v192 offset:3072
	ds_read_b128 v[176:179], v193 offset:16384
	v_mfma_f32_16x16x32_bf16 v[58:61], v[180:183], v[156:159], v[58:61]
	v_mfma_f32_16x16x32_bf16 v[42:45], v[180:183], v[164:167], v[42:45]
	v_mfma_f32_16x16x32_bf16 v[26:29], v[180:183], v[168:171], v[26:29]
	v_mfma_f32_16x16x32_bf16 v[10:13], v[180:183], v[172:175], v[10:13]
	ds_read_b128 v[180:183], v193 offset:17408
	v_mfma_f32_16x16x32_bf16 v[54:57], v[184:187], v[156:159], v[54:57]
	v_mfma_f32_16x16x32_bf16 v[38:41], v[184:187], v[164:167], v[38:41]
	v_mfma_f32_16x16x32_bf16 v[22:25], v[184:187], v[168:171], v[22:25]
	v_mfma_f32_16x16x32_bf16 v[6:9], v[184:187], v[172:175], v[6:9]
	ds_read_b128 v[184:187], v193 offset:18432
	v_mfma_f32_16x16x32_bf16 v[50:53], v[188:191], v[156:159], v[50:53]
	v_mfma_f32_16x16x32_bf16 v[34:37], v[188:191], v[164:167], v[34:37]
	v_mfma_f32_16x16x32_bf16 v[18:21], v[188:191], v[168:171], v[18:21]
	v_mfma_f32_16x16x32_bf16 v[2:5], v[188:191], v[172:175], v[2:5]
	ds_read_b128 v[188:191], v193 offset:19456
	s_sub_i32 s100, s100, 1
	s_cmp_lg_u32 s100, 0
	s_cbranch_scc1 .Lpipe_mlp2
	v_add_u32_e32 v161, s11, v160
	ds_read_b128 v[156:159], v161 offset:4096
	ds_read_b128 v[164:167], v161 offset:5120
	ds_read_b128 v[168:171], v161 offset:6144
	ds_read_b128 v[172:175], v161 offset:7168
	s_add_i32 s12, s11, 0xffffa000
	s_cmp_eq_u32 s11, 0
	s_cselect_b32 s12, 0xc000, s12
	s_add_i32 s13, s12, s0
	s_add_i32 s12, s12, s1
	s_mov_b32 m0, s13
	s_waitcnt lgkmcnt(7)
	v_mfma_f32_16x16x32_bf16 v[126:129], v[176:179], v[140:143], v[126:129]
	global_load_lds_dwordx4 v[196:197], off
	v_mfma_f32_16x16x32_bf16 v[110:113], v[176:179], v[144:147], v[110:113]
	v_lshl_add_u64 v[196:197], v[196:197], 0, s[98:99]
	s_add_i32 m0, s13, 0x400
	v_mfma_f32_16x16x32_bf16 v[94:97], v[176:179], v[148:151], v[94:97]
	global_load_lds_dwordx4 v[198:199], off
	v_mfma_f32_16x16x32_bf16 v[78:81], v[176:179], v[152:155], v[78:81]
	v_lshl_add_u64 v[198:199], v[198:199], 0, s[98:99]
	s_add_i32 m0, s13, 0x800
	s_waitcnt lgkmcnt(6)
	v_mfma_f32_16x16x32_bf16 v[122:125], v[180:183], v[140:143], v[122:125]
	global_load_lds_dwordx4 v[200:201], off
	v_mfma_f32_16x16x32_bf16 v[106:109], v[180:183], v[144:147], v[106:109]
	v_lshl_add_u64 v[200:201], v[200:201], 0, s[98:99]
	s_add_i32 m0, s13, 0xc00
	v_mfma_f32_16x16x32_bf16 v[90:93], v[180:183], v[148:151], v[90:93]
	global_load_lds_dwordx4 v[202:203], off
	v_mfma_f32_16x16x32_bf16 v[74:77], v[180:183], v[152:155], v[74:77]
	v_lshl_add_u64 v[202:203], v[202:203], 0, s[98:99]
	s_mov_b32 m0, s12
	s_waitcnt lgkmcnt(5)
	v_mfma_f32_16x16x32_bf16 v[118:121], v[184:187], v[140:143], v[118:121]
	global_load_lds_dwordx4 v[204:205], off
	v_mfma_f32_16x16x32_bf16 v[102:105], v[184:187], v[144:147], v[102:105]
	v_lshl_add_u64 v[204:205], v[204:205], 0, 64
	s_add_i32 m0, s12, 0x400
	v_mfma_f32_16x16x32_bf16 v[86:89], v[184:187], v[148:151], v[86:89]
	global_load_lds_dwordx4 v[206:207], off
	v_mfma_f32_16x16x32_bf16 v[70:73], v[184:187], v[152:155], v[70:73]
	v_lshl_add_u64 v[206:207], v[206:207], 0, 64
	s_waitcnt lgkmcnt(4)
	v_mfma_f32_16x16x32_bf16 v[114:117], v[188:191], v[140:143], v[114:117]
	v_mfma_f32_16x16x32_bf16 v[98:101], v[188:191], v[144:147], v[98:101]
	v_mfma_f32_16x16x32_bf16 v[82:85], v[188:191], v[148:151], v[82:85]
	v_mfma_f32_16x16x32_bf16 v[66:69], v[188:191], v[152:155], v[66:69]
	s_waitcnt lgkmcnt(0)
	v_mfma_f32_16x16x32_bf16 v[62:65], v[176:179], v[156:159], v[62:65]
	v_mfma_f32_16x16x32_bf16 v[46:49], v[176:179], v[164:167], v[46:49]
	v_mfma_f32_16x16x32_bf16 v[30:33], v[176:179], v[168:171], v[30:33]
	v_mfma_f32_16x16x32_bf16 v[14:17], v[176:179], v[172:175], v[14:17]
	v_mfma_f32_16x16x32_bf16 v[58:61], v[180:183], v[156:159], v[58:61]
	v_mfma_f32_16x16x32_bf16 v[42:45], v[180:183], v[164:167], v[42:45]
	v_mfma_f32_16x16x32_bf16 v[26:29], v[180:183], v[168:171], v[26:29]
	v_mfma_f32_16x16x32_bf16 v[10:13], v[180:183], v[172:175], v[10:13]
	v_mfma_f32_16x16x32_bf16 v[54:57], v[184:187], v[156:159], v[54:57]
	v_mfma_f32_16x16x32_bf16 v[38:41], v[184:187], v[164:167], v[38:41]
	v_mfma_f32_16x16x32_bf16 v[22:25], v[184:187], v[168:171], v[22:25]
	v_mfma_f32_16x16x32_bf16 v[6:9], v[184:187], v[172:175], v[6:9]
	v_mfma_f32_16x16x32_bf16 v[50:53], v[188:191], v[156:159], v[50:53]
	v_mfma_f32_16x16x32_bf16 v[34:37], v[188:191], v[164:167], v[34:37]
	v_mfma_f32_16x16x32_bf16 v[18:21], v[188:191], v[168:171], v[18:21]
	v_mfma_f32_16x16x32_bf16 v[2:5], v[188:191], v[172:175], v[2:5]
	s_mov_b32 s10, 0
	s_waitcnt vmcnt(6) lgkmcnt(0)
	s_barrier
	s_setprio 1
	s_mul_i32 s0, s10, 0x6000
	v_or_b32_e32 v0, s0, v138
	v_add_u32_e32 v136, v0, v139
	s_waitcnt vmcnt(0)
	ds_read_b128 v[130:133], v136
	ds_read_b128 v[140:143], v136 offset:1024
	ds_read_b128 v[144:147], v136 offset:2048
	ds_read_b128 v[148:151], v136 offset:3072
	ds_read_b128 v[152:155], v136 offset:4096
	ds_read_b128 v[156:159], v136 offset:5120
	ds_read_b128 v[164:167], v136 offset:6144
	ds_read_b128 v[168:171], v136 offset:7168
	v_add_u32_e32 v0, v0, v135
	ds_read_b128 v[172:175], v0 offset:16384
	ds_read_b128 v[176:179], v0 offset:17408
	ds_read_b128 v[180:183], v0 offset:18432
	ds_read_b128 v[184:187], v0 offset:19456
	v_bfe_u32 v0, v134, 6, 1
	s_setprio 0
	s_waitcnt vmcnt(0) lgkmcnt(0)
	s_waitcnt lgkmcnt(3)
	v_mfma_f32_16x16x32_bf16 v[126:129], v[172:175], v[130:133], v[126:129]
	v_ashrrev_i32_e32 v160, 7, v134
	v_and_b32_e32 v161, 15, v134
	v_bfe_u32 v134, v134, 4, 2
	s_waitcnt lgkmcnt(2)
	v_mfma_f32_16x16x32_bf16 v[122:125], v[176:179], v[130:133], v[122:125]
	s_barrier
; #define EPI_BEGIN const int lr1_ = launder_v(lr), lq1_ = launder_v(lq), wr1_ = launder_v(wr), wc1_ = launder_v(wc); { const int lr = lr1_, lq = lq1_, wr = wr1_, wc = wc1_; (void)lr; (void)lq; (void)wr; (void)wc;
; template <int MI, int NI>
; DI void gemm256(f32x4 (&acc)[MI][NI], const u16* __restrict__ A, int lda, const u16* __restrict__ Bt, int ldb, int K, int m0, int n0, char* smem) {
;     ...
;         acc[mi][ni] = __builtin_amdgcn_mfma_f32_16x16x32_bf16(bfr[ni], af[mi], acc[mi][ni], 0, 0, 0);
; template <int MI, int NI>
; DI void resid_tile(const u16* A, int K, const u16* Bt, const float* gate, const float* xl_in, const float* xc_in, float* xl_out, float* xc_out,
;                    int m0, int n0, char* smem) {
;     ...
;   EPI_BEGIN
; #pragma unroll
;   for (int mi = 0; mi < MI; ++mi) {
;     const int m = m0 + wr * 16 * MI + mi * 16 + lr;
;     const int b9 = m < NTL ? m >> 12 : 8;
;     const float* xi = xrow(xl_in, xc_in, m);
;     float* xo = m < NTL ? xl_out + (size_t)m * D : xc_out + (size_t)(m - NTL) * D;
; #pragma unroll
;     for (int ni = 0; ni < NI; ++ni) {
;       const int n = n0 + wc * 16 * NI + ni * 16 + lq * 4;
;       const float4 g = *(const float4*)(gate + (size_t)b9 * 6144 + n);
;       const float4 xv = *(const float4*)(xi + n);
;       float4 ov;
;       ov.x = xv.x + g.x * acc[mi][ni][0]; ov.y = xv.y + g.y * acc[mi][ni][1]; ov.z = xv.z + g.z * acc[mi][ni][2]; ov.w = xv.w + g.w * acc[mi][ni][3];
;       *(float4*)(xo + n) = ov;
;     }
	s_waitcnt lgkmcnt(1)
	v_mfma_f32_16x16x32_bf16 v[118:121], v[180:183], v[130:133], v[118:121]
	s_waitcnt lgkmcnt(0)
	v_mfma_f32_16x16x32_bf16 v[114:117], v[184:187], v[130:133], v[114:117]
	v_mfma_f32_16x16x32_bf16 v[110:113], v[172:175], v[140:143], v[110:113]
	v_mfma_f32_16x16x32_bf16 v[106:109], v[176:179], v[140:143], v[106:109]
	v_mfma_f32_16x16x32_bf16 v[102:105], v[180:183], v[140:143], v[102:105]
	v_mfma_f32_16x16x32_bf16 v[98:101], v[184:187], v[140:143], v[98:101]
	v_mfma_f32_16x16x32_bf16 v[94:97], v[172:175], v[144:147], v[94:97]
	v_mfma_f32_16x16x32_bf16 v[90:93], v[176:179], v[144:147], v[90:93]
	v_mfma_f32_16x16x32_bf16 v[86:89], v[180:183], v[144:147], v[86:89]
	v_mfma_f32_16x16x32_bf16 v[82:85], v[184:187], v[144:147], v[82:85]
	v_mfma_f32_16x16x32_bf16 v[78:81], v[172:175], v[148:151], v[78:81]
	v_mfma_f32_16x16x32_bf16 v[130:133], v[176:179], v[148:151], v[74:77]
	v_mfma_f32_16x16x32_bf16 v[70:73], v[180:183], v[148:151], v[70:73]
	v_mfma_f32_16x16x32_bf16 v[66:69], v[184:187], v[148:151], v[66:69]
	v_mfma_f32_16x16x32_bf16 v[62:65], v[172:175], v[152:155], v[62:65]
	v_mfma_f32_16x16x32_bf16 v[58:61], v[176:179], v[152:155], v[58:61]
	v_mfma_f32_16x16x32_bf16 v[54:57], v[180:183], v[152:155], v[54:57]
	v_mfma_f32_16x16x32_bf16 v[50:53], v[184:187], v[152:155], v[50:53]
	v_mfma_f32_16x16x32_bf16 v[46:49], v[172:175], v[156:159], v[46:49]
	v_mfma_f32_16x16x32_bf16 v[42:45], v[176:179], v[156:159], v[42:45]
	v_mfma_f32_16x16x32_bf16 v[38:41], v[180:183], v[156:159], v[38:41]
	v_mfma_f32_16x16x32_bf16 v[34:37], v[184:187], v[156:159], v[34:37]
	v_mfma_f32_16x16x32_bf16 v[30:33], v[172:175], v[164:167], v[30:33]
	v_mfma_f32_16x16x32_bf16 v[26:29], v[176:179], v[164:167], v[26:29]
	v_mfma_f32_16x16x32_bf16 v[22:25], v[180:183], v[164:167], v[22:25]
	v_mfma_f32_16x16x32_bf16 v[18:21], v[184:187], v[164:167], v[18:21]
	v_mfma_f32_16x16x32_bf16 v[14:17], v[172:175], v[168:171], v[14:17]
	v_mfma_f32_16x16x32_bf16 v[10:13], v[176:179], v[168:171], v[10:13]
	v_mfma_f32_16x16x32_bf16 v[6:9], v[180:183], v[168:171], v[6:9]
	v_mfma_f32_16x16x32_bf16 v[140:143], v[184:187], v[168:171], v[2:5]
	s_setprio 1
	s_addk_i32 s0, 0x6000
	s_cmp_lg_u32 s10, 2
	s_cselect_b32 s0, s0, 0
	v_or_b32_e32 v168, s0, v138
	v_add_u32_e32 v164, v168, v139
	ds_read_b128 v[2:5], v164
	ds_read_b128 v[74:77], v164 offset:1024
	ds_read_b128 v[136:139], v164 offset:2048
	ds_read_b128 v[144:147], v164 offset:3072
	ds_read_b128 v[148:151], v164 offset:4096
	ds_read_b128 v[152:155], v164 offset:5120
	ds_read_b128 v[156:159], v164 offset:6144
	ds_read_b128 v[164:167], v164 offset:7168
	v_add_u32_e32 v135, v168, v135
	ds_read_b128 v[168:171], v135 offset:16384
	ds_read_b128 v[172:175], v135 offset:17408
	ds_read_b128 v[176:179], v135 offset:18432
	ds_read_b128 v[180:183], v135 offset:19456
	s_setprio 0
	s_waitcnt lgkmcnt(3)
	v_mfma_f32_16x16x32_bf16 v[126:129], v[168:171], v[2:5], v[126:129]
	s_waitcnt lgkmcnt(0)
	s_barrier
	s_waitcnt lgkmcnt(2)
	v_mfma_f32_16x16x32_bf16 v[122:125], v[172:175], v[2:5], v[122:125]
	s_waitcnt lgkmcnt(1)
	v_mfma_f32_16x16x32_bf16 v[184:187], v[176:179], v[2:5], v[118:121]
	v_lshlrev_b32_e32 v0, 6, v0
	s_waitcnt lgkmcnt(0)
	v_mfma_f32_16x16x32_bf16 v[188:191], v[180:183], v[2:5], v[114:117]
	v_lshlrev_b32_e32 v2, 7, v160
	v_mov_b32_e32 v118, s95
	v_mov_b32_e32 v119, s49
	v_add3_u32 v116, v161, s8, v2
	v_lshlrev_b32_e32 v2, 2, v134
	v_add3_u32 v2, v2, s9, v0
	v_min_i32_e32 v0, 0x8000, v116
	v_mfma_f32_16x16x32_bf16 v[110:113], v[168:171], v[74:77], v[110:113]
	v_ashrrev_i32_e32 v117, 31, v116
	v_cmp_gt_i32_e32 vcc, s58, v116
	v_mov_b32_e32 v120, s94
	v_mfma_f32_16x16x32_bf16 v[106:109], v[172:175], v[74:77], v[106:109]
	v_cndmask_b32_e32 v5, 0, v117, vcc
	v_mov_b32_e32 v121, s48
	v_cndmask_b32_e32 v115, v118, v119, vcc
	v_mfma_f32_16x16x32_bf16 v[102:105], v[176:179], v[74:77], v[102:105]
	v_cndmask_b32_e32 v114, v120, v121, vcc
	v_ashrrev_i32_e32 v3, 31, v2
	v_mfma_f32_16x16x32_bf16 v[98:101], v[180:183], v[74:77], v[98:101]
	v_mfma_f32_16x16x32_bf16 v[74:77], v[168:171], v[144:147], v[78:81]
	v_mfma_f32_16x16x32_bf16 v[78:81], v[172:175], v[144:147], v[130:133]
	s_nop 2
	v_ashrrev_i32_e32 v130, 12, v0
	v_add_u32_e32 v0, 0xffff8000, v116
	v_cndmask_b32_e32 v4, v0, v116, vcc
	v_lshlrev_b64 v[4:5], 12, v[4:5]
	v_lshl_add_u64 v[4:5], v[114:115], 0, v[4:5]
	v_mul_hi_i32_i24_e32 v115, 0x6000, v130
	v_mul_i32_i24_e32 v114, 0x6000, v130
	v_lshl_add_u64 v[130:131], s[82:83], 0, v[114:115]
	v_lshlrev_b64 v[114:115], 2, v[2:3]
	v_mfma_f32_16x16x32_bf16 v[94:97], v[168:171], v[136:139], v[94:97]
	v_lshl_add_u64 v[134:135], v[130:131], 0, v[114:115]
	v_mfma_f32_16x16x32_bf16 v[90:93], v[172:175], v[136:139], v[90:93]
	v_mfma_f32_16x16x32_bf16 v[86:89], v[176:179], v[136:139], v[86:89]
	v_mfma_f32_16x16x32_bf16 v[82:85], v[180:183], v[136:139], v[82:85]
	v_lshl_add_u64 v[136:137], v[4:5], 0, v[114:115]
	flat_load_dwordx4 v[2:5], v[134:135]
	flat_load_dwordx4 v[130:133], v[136:137]
	v_mfma_f32_16x16x32_bf16 v[70:73], v[176:179], v[144:147], v[70:73]
	v_lshlrev_b64 v[138:139], 12, v[116:117]
	v_lshl_add_u64 v[138:139], s[48:49], 0, v[138:139]
	s_waitcnt vmcnt(0) lgkmcnt(0)
	v_pk_fma_f32 v[2:3], v[126:127], v[2:3], v[130:131]
	v_mfma_f32_16x16x32_bf16 v[66:69], v[180:183], v[144:147], v[66:69]
	v_lshlrev_b64 v[144:145], 12, v[0:1]
	v_lshl_add_u64 v[144:145], s[94:95], 0, v[144:145]
	v_cndmask_b32_e32 v139, v145, v139, vcc
	v_cndmask_b32_e32 v138, v144, v138, vcc
	v_lshl_add_u64 v[138:139], v[138:139], 0, v[114:115]
	v_pk_fma_f32 v[4:5], v[128:129], v[4:5], v[132:133]
	flat_store_dwordx4 v[138:139], v[2:5]
	flat_load_dwordx4 v[126:129], v[134:135] offset:64
	flat_load_dwordx4 v[130:133], v[136:137] offset:64
	v_mfma_f32_16x16x32_bf16 v[2:5], v[172:175], v[164:167], v[10:13]
	v_mfma_f32_16x16x32_bf16 v[62:65], v[168:171], v[148:151], v[62:65]
	s_waitcnt vmcnt(0) lgkmcnt(0)
; template <int MI, int NI>
; DI void resid_tile(const u16* A, int K, const u16* Bt, const float* gate, const float* xl_in, const float* xc_in, float* xl_out, float* xc_out,
;                    int m0, int n0, char* smem) {
;     ...
; #pragma unroll
;   for (int mi = 0; mi < MI; ++mi) {
;     const int m = m0 + wr * 16 * MI + mi * 16 + lr;
;     const int b9 = m < NTL ? m >> 12 : 8;
;     const float* xi = xrow(xl_in, xc_in, m);
;     float* xo = m < NTL ? xl_out + (size_t)m * D : xc_out + (size_t)(m - NTL) * D;
; #pragma unroll
;     for (int ni = 0; ni < NI; ++ni) {
;       const int n = n0 + wc * 16 * NI + ni * 16 + lq * 4;
;       const float4 g = *(const float4*)(gate + (size_t)b9 * 6144 + n);
;       const float4 xv = *(const float4*)(xi + n);
;       float4 ov;
;       ov.x = xv.x + g.x * acc[mi][ni][0]; ov.y = xv.y + g.y * acc[mi][ni][1]; ov.z = xv.z + g.z * acc[mi][ni][2]; ov.w = xv.w + g.w * acc[mi][ni][3];
;       *(float4*)(xo + n) = ov;
;     }
;     __builtin_amdgcn_sched_barrier(0);
;   }
	s_nop 0
	v_pk_fma_f32 v[10:11], v[122:123], v[126:127], v[130:131]
	v_pk_fma_f32 v[12:13], v[124:125], v[128:129], v[132:133]
	flat_store_dwordx4 v[138:139], v[10:13] offset:64
	flat_load_dwordx4 v[10:13], v[134:135] offset:128
	s_nop 0
	flat_load_dwordx4 v[122:125], v[136:137] offset:128
	v_mfma_f32_16x16x32_bf16 v[58:61], v[172:175], v[148:151], v[58:61]
	s_waitcnt vmcnt(0) lgkmcnt(0)
	v_pk_fma_f32 v[10:11], v[184:185], v[10:11], v[122:123]
	v_pk_fma_f32 v[12:13], v[186:187], v[12:13], v[124:125]
	flat_store_dwordx4 v[138:139], v[10:13] offset:128
	flat_load_dwordx4 v[122:125], v[134:135] offset:192
	flat_load_dwordx4 v[126:129], v[136:137] offset:192
	v_mfma_f32_16x16x32_bf16 v[54:57], v[176:179], v[148:151], v[54:57]
	s_waitcnt vmcnt(0) lgkmcnt(0)
	v_pk_fma_f32 v[122:123], v[188:189], v[122:123], v[126:127]
	v_pk_fma_f32 v[124:125], v[190:191], v[124:125], v[128:129]
	v_mfma_f32_16x16x32_bf16 v[50:53], v[180:183], v[148:151], v[50:53]
	flat_store_dwordx4 v[138:139], v[122:125] offset:192
	v_mfma_f32_16x16x32_bf16 v[46:49], v[168:171], v[152:155], v[46:49]
	v_mfma_f32_16x16x32_bf16 v[42:45], v[172:175], v[152:155], v[42:45]
	v_mfma_f32_16x16x32_bf16 v[38:41], v[176:179], v[152:155], v[38:41]
	v_mfma_f32_16x16x32_bf16 v[34:37], v[180:183], v[152:155], v[34:37]
	v_mfma_f32_16x16x32_bf16 v[30:33], v[168:171], v[156:159], v[30:33]
	v_mfma_f32_16x16x32_bf16 v[26:29], v[172:175], v[156:159], v[26:29]
	v_mfma_f32_16x16x32_bf16 v[22:25], v[176:179], v[156:159], v[22:25]
	v_mfma_f32_16x16x32_bf16 v[18:21], v[180:183], v[156:159], v[18:21]
	v_mfma_f32_16x16x32_bf16 v[14:17], v[168:171], v[164:167], v[14:17]
	v_mfma_f32_16x16x32_bf16 v[6:9], v[176:179], v[164:167], v[6:9]
	v_mfma_f32_16x16x32_bf16 v[10:13], v[180:183], v[164:167], v[140:143]
	v_add_u32_e32 v122, 16, v116
	v_min_i32_e32 v0, 0x8000, v122
	v_cmp_gt_i32_e32 vcc, s58, v122
	v_ashrrev_i32_e32 v117, 12, v0
	v_add_u32_e32 v0, 0xffff8010, v116
	v_ashrrev_i32_e32 v123, 31, v122
	v_cndmask_b32_e32 v125, 0, v123, vcc
	v_cndmask_b32_e32 v124, v0, v122, vcc
	v_cndmask_b32_e32 v127, v118, v119, vcc
	v_cndmask_b32_e32 v126, v120, v121, vcc
	v_lshlrev_b64 v[124:125], 12, v[124:125]
	v_lshl_add_u64 v[124:125], v[126:127], 0, v[124:125]
	v_lshlrev_b64 v[122:123], 12, v[122:123]
	v_lshlrev_b64 v[126:127], 12, v[0:1]
	v_lshl_add_u64 v[122:123], s[48:49], 0, v[122:123]
	v_lshl_add_u64 v[126:127], s[94:95], 0, v[126:127]
	v_cndmask_b32_e32 v123, v127, v123, vcc
	v_cndmask_b32_e32 v122, v126, v122, vcc
	v_mul_hi_i32_i24_e32 v127, 0x6000, v117
	v_mul_i32_i24_e32 v126, 0x6000, v117
	v_lshl_add_u64 v[126:127], s[82:83], 0, v[126:127]
	v_lshl_add_u64 v[130:131], v[126:127], 0, v[114:115]
	v_lshl_add_u64 v[132:133], v[124:125], 0, v[114:115]
	v_lshl_add_u64 v[134:135], v[122:123], 0, v[114:115]
	flat_load_dwordx4 v[122:125], v[130:131]
	flat_load_dwordx4 v[126:129], v[132:133]
	s_waitcnt vmcnt(0) lgkmcnt(0)
	v_pk_fma_f32 v[110:111], v[110:111], v[122:123], v[126:127]
	v_pk_fma_f32 v[112:113], v[112:113], v[124:125], v[128:129]
	flat_store_dwordx4 v[134:135], v[110:113]
	flat_load_dwordx4 v[110:113], v[130:131] offset:64
	s_nop 0
	flat_load_dwordx4 v[122:125], v[132:133] offset:64
	s_waitcnt vmcnt(0) lgkmcnt(0)
	v_pk_fma_f32 v[106:107], v[106:107], v[110:111], v[122:123]
	v_pk_fma_f32 v[108:109], v[108:109], v[112:113], v[124:125]
	flat_store_dwordx4 v[134:135], v[106:109] offset:64
	flat_load_dwordx4 v[106:109], v[130:131] offset:128
	s_nop 0
	flat_load_dwordx4 v[110:113], v[132:133] offset:128
	s_waitcnt vmcnt(0) lgkmcnt(0)
	v_pk_fma_f32 v[102:103], v[102:103], v[106:107], v[110:111]
	v_pk_fma_f32 v[104:105], v[104:105], v[108:109], v[112:113]
	flat_store_dwordx4 v[134:135], v[102:105] offset:128
	flat_load_dwordx4 v[102:105], v[130:131] offset:192
	s_nop 0
	flat_load_dwordx4 v[106:109], v[132:133] offset:192
	s_waitcnt vmcnt(0) lgkmcnt(0)
	v_pk_fma_f32 v[98:99], v[98:99], v[102:103], v[106:107]
	v_pk_fma_f32 v[100:101], v[100:101], v[104:105], v[108:109]
	flat_store_dwordx4 v[134:135], v[98:101] offset:192
	s_nop 1
	v_add_u32_e32 v98, 32, v116
	v_min_i32_e32 v0, 0x8000, v98
	v_cmp_gt_i32_e32 vcc, s58, v98
	v_ashrrev_i32_e32 v104, 12, v0
	v_add_u32_e32 v0, 0xffff8020, v116
	v_ashrrev_i32_e32 v99, 31, v98
	v_cndmask_b32_e32 v101, 0, v99, vcc
	v_cndmask_b32_e32 v100, v0, v98, vcc
	v_cndmask_b32_e32 v103, v118, v119, vcc
	v_cndmask_b32_e32 v102, v120, v121, vcc
	v_lshlrev_b64 v[100:101], 12, v[100:101]
	v_lshl_add_u64 v[100:101], v[102:103], 0, v[100:101]
	v_lshlrev_b64 v[98:99], 12, v[98:99]
	v_lshlrev_b64 v[102:103], 12, v[0:1]
	v_lshl_add_u64 v[98:99], s[48:49], 0, v[98:99]
	v_lshl_add_u64 v[102:103], s[94:95], 0, v[102:103]
	v_cndmask_b32_e32 v99, v103, v99, vcc
	v_cndmask_b32_e32 v98, v102, v98, vcc
	v_mul_hi_i32_i24_e32 v103, 0x6000, v104
	v_mul_i32_i24_e32 v102, 0x6000, v104
	v_lshl_add_u64 v[102:103], s[82:83], 0, v[102:103]
	v_lshl_add_u64 v[106:107], v[102:103], 0, v[114:115]
	v_lshl_add_u64 v[108:109], v[100:101], 0, v[114:115]
	v_lshl_add_u64 v[110:111], v[98:99], 0, v[114:115]
	flat_load_dwordx4 v[98:101], v[106:107]
	flat_load_dwordx4 v[102:105], v[108:109]
	s_waitcnt vmcnt(0) lgkmcnt(0)
	v_pk_fma_f32 v[94:95], v[94:95], v[98:99], v[102:103]
	v_pk_fma_f32 v[96:97], v[96:97], v[100:101], v[104:105]
	flat_store_dwordx4 v[110:111], v[94:97]
	flat_load_dwordx4 v[94:97], v[106:107] offset:64
	s_nop 0
	flat_load_dwordx4 v[98:101], v[108:109] offset:64
	s_waitcnt vmcnt(0) lgkmcnt(0)
	v_pk_fma_f32 v[90:91], v[90:91], v[94:95], v[98:99]
	v_pk_fma_f32 v[92:93], v[92:93], v[96:97], v[100:101]
	flat_store_dwordx4 v[110:111], v[90:93] offset:64
	flat_load_dwordx4 v[90:93], v[106:107] offset:128
	s_nop 0
	flat_load_dwordx4 v[94:97], v[108:109] offset:128
	s_waitcnt vmcnt(0) lgkmcnt(0)
; template <int MI, int NI>
; DI void resid_tile(const u16* A, int K, const u16* Bt, const float* gate, const float* xl_in, const float* xc_in, float* xl_out, float* xc_out,
;                    int m0, int n0, char* smem) {
;     ...
; #pragma unroll
;   for (int mi = 0; mi < MI; ++mi) {
;     const int m = m0 + wr * 16 * MI + mi * 16 + lr;
;     const int b9 = m < NTL ? m >> 12 : 8;
;     const float* xi = xrow(xl_in, xc_in, m);
;     float* xo = m < NTL ? xl_out + (size_t)m * D : xc_out + (size_t)(m - NTL) * D;
; #pragma unroll
;     for (int ni = 0; ni < NI; ++ni) {
;       const int n = n0 + wc * 16 * NI + ni * 16 + lq * 4;
;       const float4 g = *(const float4*)(gate + (size_t)b9 * 6144 + n);
;       const float4 xv = *(const float4*)(xi + n);
;       float4 ov;
;       ov.x = xv.x + g.x * acc[mi][ni][0]; ov.y = xv.y + g.y * acc[mi][ni][1]; ov.z = xv.z + g.z * acc[mi][ni][2]; ov.w = xv.w + g.w * acc[mi][ni][3];
;       *(float4*)(xo + n) = ov;
;     }
;     __builtin_amdgcn_sched_barrier(0);
;   }
	v_pk_fma_f32 v[86:87], v[86:87], v[90:91], v[94:95]
	v_pk_fma_f32 v[88:89], v[88:89], v[92:93], v[96:97]
	flat_store_dwordx4 v[110:111], v[86:89] offset:128
	flat_load_dwordx4 v[86:89], v[106:107] offset:192
	s_nop 0
	flat_load_dwordx4 v[90:93], v[108:109] offset:192
	s_waitcnt vmcnt(0) lgkmcnt(0)
	v_pk_fma_f32 v[82:83], v[82:83], v[86:87], v[90:91]
	v_pk_fma_f32 v[84:85], v[84:85], v[88:89], v[92:93]
	flat_store_dwordx4 v[110:111], v[82:85] offset:192
	s_nop 1
	v_add_u32_e32 v82, 48, v116
	v_min_i32_e32 v0, 0x8000, v82
	v_cmp_gt_i32_e32 vcc, s58, v82
	v_ashrrev_i32_e32 v88, 12, v0
	v_add_u32_e32 v0, 0xffff8030, v116
	v_ashrrev_i32_e32 v83, 31, v82
	v_cndmask_b32_e32 v85, 0, v83, vcc
	v_cndmask_b32_e32 v84, v0, v82, vcc
	v_cndmask_b32_e32 v87, v118, v119, vcc
	v_cndmask_b32_e32 v86, v120, v121, vcc
	v_lshlrev_b64 v[84:85], 12, v[84:85]
	v_lshl_add_u64 v[84:85], v[86:87], 0, v[84:85]
	v_lshlrev_b64 v[82:83], 12, v[82:83]
	v_lshlrev_b64 v[86:87], 12, v[0:1]
	v_lshl_add_u64 v[82:83], s[48:49], 0, v[82:83]
	v_lshl_add_u64 v[86:87], s[94:95], 0, v[86:87]
	v_cndmask_b32_e32 v83, v87, v83, vcc
	v_cndmask_b32_e32 v82, v86, v82, vcc
	v_mul_hi_i32_i24_e32 v87, 0x6000, v88
	v_mul_i32_i24_e32 v86, 0x6000, v88
	v_lshl_add_u64 v[86:87], s[82:83], 0, v[86:87]
	v_lshl_add_u64 v[90:91], v[86:87], 0, v[114:115]
	v_lshl_add_u64 v[92:93], v[84:85], 0, v[114:115]
	v_lshl_add_u64 v[94:95], v[82:83], 0, v[114:115]
	flat_load_dwordx4 v[82:85], v[90:91]
	flat_load_dwordx4 v[86:89], v[92:93]
	s_waitcnt vmcnt(0) lgkmcnt(0)
	v_pk_fma_f32 v[74:75], v[74:75], v[82:83], v[86:87]
	v_pk_fma_f32 v[76:77], v[76:77], v[84:85], v[88:89]
	flat_store_dwordx4 v[94:95], v[74:77]
	flat_load_dwordx4 v[74:77], v[90:91] offset:64
	s_nop 0
	flat_load_dwordx4 v[82:85], v[92:93] offset:64
	s_waitcnt vmcnt(0) lgkmcnt(0)
	v_pk_fma_f32 v[74:75], v[78:79], v[74:75], v[82:83]
	v_pk_fma_f32 v[76:77], v[80:81], v[76:77], v[84:85]
	flat_store_dwordx4 v[94:95], v[74:77] offset:64
	flat_load_dwordx4 v[74:77], v[90:91] offset:128
	s_nop 0
	flat_load_dwordx4 v[78:81], v[92:93] offset:128
	s_waitcnt vmcnt(0) lgkmcnt(0)
	v_pk_fma_f32 v[70:71], v[70:71], v[74:75], v[78:79]
	v_pk_fma_f32 v[72:73], v[72:73], v[76:77], v[80:81]
	flat_store_dwordx4 v[94:95], v[70:73] offset:128
	flat_load_dwordx4 v[70:73], v[90:91] offset:192
	s_nop 0
	flat_load_dwordx4 v[74:77], v[92:93] offset:192
	s_waitcnt vmcnt(0) lgkmcnt(0)
	v_pk_fma_f32 v[66:67], v[66:67], v[70:71], v[74:75]
	v_pk_fma_f32 v[68:69], v[68:69], v[72:73], v[76:77]
	flat_store_dwordx4 v[94:95], v[66:69] offset:192
	s_nop 1
	v_add_u32_e32 v66, 64, v116
	v_min_i32_e32 v0, 0x8000, v66
	v_cmp_gt_i32_e32 vcc, s58, v66
	v_ashrrev_i32_e32 v72, 12, v0
	v_add_u32_e32 v0, 0xffff8040, v116
	v_ashrrev_i32_e32 v67, 31, v66
	v_cndmask_b32_e32 v69, 0, v67, vcc
	v_cndmask_b32_e32 v68, v0, v66, vcc
	v_cndmask_b32_e32 v71, v118, v119, vcc
	v_cndmask_b32_e32 v70, v120, v121, vcc
	v_lshlrev_b64 v[68:69], 12, v[68:69]
	v_lshl_add_u64 v[68:69], v[70:71], 0, v[68:69]
	v_lshlrev_b64 v[66:67], 12, v[66:67]
	v_lshlrev_b64 v[70:71], 12, v[0:1]
	v_lshl_add_u64 v[66:67], s[48:49], 0, v[66:67]
	v_lshl_add_u64 v[70:71], s[94:95], 0, v[70:71]
	v_cndmask_b32_e32 v67, v71, v67, vcc
	v_cndmask_b32_e32 v66, v70, v66, vcc
	v_mul_hi_i32_i24_e32 v71, 0x6000, v72
	v_mul_i32_i24_e32 v70, 0x6000, v72
	v_lshl_add_u64 v[70:71], s[82:83], 0, v[70:71]
	v_lshl_add_u64 v[74:75], v[70:71], 0, v[114:115]
	v_lshl_add_u64 v[76:77], v[68:69], 0, v[114:115]
	v_lshl_add_u64 v[78:79], v[66:67], 0, v[114:115]
	flat_load_dwordx4 v[66:69], v[74:75]
	flat_load_dwordx4 v[70:73], v[76:77]
	s_waitcnt vmcnt(0) lgkmcnt(0)
	v_pk_fma_f32 v[62:63], v[62:63], v[66:67], v[70:71]
	v_pk_fma_f32 v[64:65], v[64:65], v[68:69], v[72:73]
	flat_store_dwordx4 v[78:79], v[62:65]
	flat_load_dwordx4 v[62:65], v[74:75] offset:64
	s_nop 0
	flat_load_dwordx4 v[66:69], v[76:77] offset:64
	s_waitcnt vmcnt(0) lgkmcnt(0)
	v_pk_fma_f32 v[58:59], v[58:59], v[62:63], v[66:67]
	v_pk_fma_f32 v[60:61], v[60:61], v[64:65], v[68:69]
	flat_store_dwordx4 v[78:79], v[58:61] offset:64
	flat_load_dwordx4 v[58:61], v[74:75] offset:128
	s_nop 0
	flat_load_dwordx4 v[62:65], v[76:77] offset:128
	s_waitcnt vmcnt(0) lgkmcnt(0)
	v_pk_fma_f32 v[54:55], v[54:55], v[58:59], v[62:63]
	v_pk_fma_f32 v[56:57], v[56:57], v[60:61], v[64:65]
	flat_store_dwordx4 v[78:79], v[54:57] offset:128
	flat_load_dwordx4 v[54:57], v[74:75] offset:192
	s_nop 0
	flat_load_dwordx4 v[58:61], v[76:77] offset:192
	s_waitcnt vmcnt(0) lgkmcnt(0)
	v_pk_fma_f32 v[50:51], v[50:51], v[54:55], v[58:59]
	v_pk_fma_f32 v[52:53], v[52:53], v[56:57], v[60:61]
	flat_store_dwordx4 v[78:79], v[50:53] offset:192
	s_nop 1
	v_add_u32_e32 v50, 0x50, v116
	v_min_i32_e32 v0, 0x8000, v50
	v_cmp_gt_i32_e32 vcc, s58, v50
	v_ashrrev_i32_e32 v56, 12, v0
	v_add_u32_e32 v0, 0xffff8050, v116
	v_ashrrev_i32_e32 v51, 31, v50
	v_cndmask_b32_e32 v53, 0, v51, vcc
	v_cndmask_b32_e32 v52, v0, v50, vcc
	v_cndmask_b32_e32 v55, v118, v119, vcc
	v_cndmask_b32_e32 v54, v120, v121, vcc
	v_lshlrev_b64 v[52:53], 12, v[52:53]
	v_lshl_add_u64 v[52:53], v[54:55], 0, v[52:53]
	v_lshlrev_b64 v[50:51], 12, v[50:51]
	v_lshlrev_b64 v[54:55], 12, v[0:1]
	v_lshl_add_u64 v[50:51], s[48:49], 0, v[50:51]
	v_lshl_add_u64 v[54:55], s[94:95], 0, v[54:55]
	v_cndmask_b32_e32 v51, v55, v51, vcc
	v_cndmask_b32_e32 v50, v54, v50, vcc
	v_mul_hi_i32_i24_e32 v55, 0x6000, v56
	v_mul_i32_i24_e32 v54, 0x6000, v56
	v_lshl_add_u64 v[54:55], s[82:83], 0, v[54:55]
	v_lshl_add_u64 v[58:59], v[54:55], 0, v[114:115]
	v_lshl_add_u64 v[60:61], v[52:53], 0, v[114:115]
	v_lshl_add_u64 v[62:63], v[50:51], 0, v[114:115]
	flat_load_dwordx4 v[50:53], v[58:59]
	flat_load_dwordx4 v[54:57], v[60:61]
	s_waitcnt vmcnt(0) lgkmcnt(0)
; template <int MI, int NI>
; DI void resid_tile(const u16* A, int K, const u16* Bt, const float* gate, const float* xl_in, const float* xc_in, float* xl_out, float* xc_out,
;                    int m0, int n0, char* smem) {
;     ...
; #pragma unroll
;   for (int mi = 0; mi < MI; ++mi) {
;     const int m = m0 + wr * 16 * MI + mi * 16 + lr;
;     const int b9 = m < NTL ? m >> 12 : 8;
;     const float* xi = xrow(xl_in, xc_in, m);
;     float* xo = m < NTL ? xl_out + (size_t)m * D : xc_out + (size_t)(m - NTL) * D;
; #pragma unroll
;     for (int ni = 0; ni < NI; ++ni) {
;       const int n = n0 + wc * 16 * NI + ni * 16 + lq * 4;
;       const float4 g = *(const float4*)(gate + (size_t)b9 * 6144 + n);
;       const float4 xv = *(const float4*)(xi + n);
;       float4 ov;
;       ov.x = xv.x + g.x * acc[mi][ni][0]; ov.y = xv.y + g.y * acc[mi][ni][1]; ov.z = xv.z + g.z * acc[mi][ni][2]; ov.w = xv.w + g.w * acc[mi][ni][3];
;       *(float4*)(xo + n) = ov;
;     }
;     __builtin_amdgcn_sched_barrier(0);
;   }
; DI void phase_resid(const Params& p, const u16* A, int K, const u16* Bt, const float* gate  ,
;                     const float* xl_in, const float* xc_in, float* xl_out, float* xc_out, int Mout, char* smem) {
;     ...
;   for (int it = 0;; ++it) {
;     int tm, tn;
;     if (!tile_map(it, NTL / 256, 8, blk__, gridDim.x, tm, tn)) break;
;     resid_tile<8, 4>(A, K, Bt, gate, xl_in, xc_in, xl_out, xc_out, tm * 256, tn * 128, smem);
	v_pk_fma_f32 v[46:47], v[46:47], v[50:51], v[54:55]
	v_pk_fma_f32 v[48:49], v[48:49], v[52:53], v[56:57]
	flat_store_dwordx4 v[62:63], v[46:49]
	flat_load_dwordx4 v[46:49], v[58:59] offset:64
	s_nop 0
	flat_load_dwordx4 v[50:53], v[60:61] offset:64
	s_waitcnt vmcnt(0) lgkmcnt(0)
	v_pk_fma_f32 v[42:43], v[42:43], v[46:47], v[50:51]
	v_pk_fma_f32 v[44:45], v[44:45], v[48:49], v[52:53]
	flat_store_dwordx4 v[62:63], v[42:45] offset:64
	flat_load_dwordx4 v[42:45], v[58:59] offset:128
	s_nop 0
	flat_load_dwordx4 v[46:49], v[60:61] offset:128
	s_waitcnt vmcnt(0) lgkmcnt(0)
	v_pk_fma_f32 v[38:39], v[38:39], v[42:43], v[46:47]
	v_pk_fma_f32 v[40:41], v[40:41], v[44:45], v[48:49]
	flat_store_dwordx4 v[62:63], v[38:41] offset:128
	flat_load_dwordx4 v[38:41], v[58:59] offset:192
	s_nop 0
	flat_load_dwordx4 v[42:45], v[60:61] offset:192
	s_waitcnt vmcnt(0) lgkmcnt(0)
	v_pk_fma_f32 v[34:35], v[34:35], v[38:39], v[42:43]
	v_pk_fma_f32 v[36:37], v[36:37], v[40:41], v[44:45]
	flat_store_dwordx4 v[62:63], v[34:37] offset:192
	s_nop 1
	v_add_u32_e32 v34, 0x60, v116
	v_min_i32_e32 v0, 0x8000, v34
	v_cmp_gt_i32_e32 vcc, s58, v34
	v_ashrrev_i32_e32 v40, 12, v0
	v_add_u32_e32 v0, 0xffff8060, v116
	v_ashrrev_i32_e32 v35, 31, v34
	v_cndmask_b32_e32 v37, 0, v35, vcc
	v_cndmask_b32_e32 v36, v0, v34, vcc
	v_cndmask_b32_e32 v39, v118, v119, vcc
	v_cndmask_b32_e32 v38, v120, v121, vcc
	v_lshlrev_b64 v[36:37], 12, v[36:37]
	v_lshl_add_u64 v[36:37], v[38:39], 0, v[36:37]
	v_lshlrev_b64 v[34:35], 12, v[34:35]
	v_lshlrev_b64 v[38:39], 12, v[0:1]
	v_lshl_add_u64 v[34:35], s[48:49], 0, v[34:35]
	v_lshl_add_u64 v[38:39], s[94:95], 0, v[38:39]
	v_cndmask_b32_e32 v35, v39, v35, vcc
	v_cndmask_b32_e32 v34, v38, v34, vcc
	v_mul_hi_i32_i24_e32 v39, 0x6000, v40
	v_mul_i32_i24_e32 v38, 0x6000, v40
	v_lshl_add_u64 v[38:39], s[82:83], 0, v[38:39]
	v_lshl_add_u64 v[42:43], v[38:39], 0, v[114:115]
	v_lshl_add_u64 v[44:45], v[36:37], 0, v[114:115]
	v_lshl_add_u64 v[46:47], v[34:35], 0, v[114:115]
	flat_load_dwordx4 v[34:37], v[42:43]
	flat_load_dwordx4 v[38:41], v[44:45]
	s_waitcnt vmcnt(0) lgkmcnt(0)
	v_pk_fma_f32 v[30:31], v[30:31], v[34:35], v[38:39]
	v_pk_fma_f32 v[32:33], v[32:33], v[36:37], v[40:41]
	flat_store_dwordx4 v[46:47], v[30:33]
	flat_load_dwordx4 v[30:33], v[42:43] offset:64
	s_nop 0
	flat_load_dwordx4 v[34:37], v[44:45] offset:64
	s_waitcnt vmcnt(0) lgkmcnt(0)
	v_pk_fma_f32 v[26:27], v[26:27], v[30:31], v[34:35]
	v_pk_fma_f32 v[28:29], v[28:29], v[32:33], v[36:37]
	flat_store_dwordx4 v[46:47], v[26:29] offset:64
	flat_load_dwordx4 v[26:29], v[42:43] offset:128
	s_nop 0
	flat_load_dwordx4 v[30:33], v[44:45] offset:128
	s_waitcnt vmcnt(0) lgkmcnt(0)
	v_pk_fma_f32 v[22:23], v[22:23], v[26:27], v[30:31]
	v_pk_fma_f32 v[24:25], v[24:25], v[28:29], v[32:33]
	flat_store_dwordx4 v[46:47], v[22:25] offset:128
	flat_load_dwordx4 v[22:25], v[42:43] offset:192
	s_nop 0
	flat_load_dwordx4 v[26:29], v[44:45] offset:192
	s_waitcnt vmcnt(0) lgkmcnt(0)
	v_pk_fma_f32 v[18:19], v[18:19], v[22:23], v[26:27]
	v_pk_fma_f32 v[20:21], v[20:21], v[24:25], v[28:29]
	flat_store_dwordx4 v[46:47], v[18:21] offset:192
	s_nop 1
	v_add_u32_e32 v18, 0x70, v116
	v_min_i32_e32 v0, 0x8000, v18
	v_cmp_gt_i32_e32 vcc, s58, v18
	v_ashrrev_i32_e32 v24, 12, v0
	v_add_u32_e32 v0, 0xffff8070, v116
	v_ashrrev_i32_e32 v19, 31, v18
	v_cndmask_b32_e32 v21, 0, v19, vcc
	v_cndmask_b32_e32 v20, v0, v18, vcc
	v_cndmask_b32_e32 v23, v118, v119, vcc
	v_cndmask_b32_e32 v22, v120, v121, vcc
	v_lshlrev_b64 v[20:21], 12, v[20:21]
	v_lshl_add_u64 v[20:21], v[22:23], 0, v[20:21]
	v_lshlrev_b64 v[18:19], 12, v[18:19]
	v_lshlrev_b64 v[22:23], 12, v[0:1]
	v_lshl_add_u64 v[18:19], s[48:49], 0, v[18:19]
	v_lshl_add_u64 v[22:23], s[94:95], 0, v[22:23]
	v_cndmask_b32_e32 v19, v23, v19, vcc
	v_cndmask_b32_e32 v18, v22, v18, vcc
	v_mul_hi_i32_i24_e32 v23, 0x6000, v24
	v_mul_i32_i24_e32 v22, 0x6000, v24
	v_lshl_add_u64 v[22:23], s[82:83], 0, v[22:23]
	v_lshl_add_u64 v[26:27], v[22:23], 0, v[114:115]
	v_lshl_add_u64 v[28:29], v[20:21], 0, v[114:115]
	v_lshl_add_u64 v[30:31], v[18:19], 0, v[114:115]
	flat_load_dwordx4 v[18:21], v[26:27]
	flat_load_dwordx4 v[22:25], v[28:29]
	s_waitcnt vmcnt(0) lgkmcnt(0)
	v_pk_fma_f32 v[14:15], v[14:15], v[18:19], v[22:23]
	v_pk_fma_f32 v[16:17], v[16:17], v[20:21], v[24:25]
	flat_store_dwordx4 v[30:31], v[14:17]
	flat_load_dwordx4 v[14:17], v[26:27] offset:64
	s_nop 0
	flat_load_dwordx4 v[18:21], v[28:29] offset:64
	s_waitcnt vmcnt(0) lgkmcnt(0)
	v_pk_fma_f32 v[2:3], v[2:3], v[14:15], v[18:19]
	v_pk_fma_f32 v[4:5], v[4:5], v[16:17], v[20:21]
	flat_store_dwordx4 v[30:31], v[2:5] offset:64
	flat_load_dwordx4 v[2:5], v[26:27] offset:128
	s_nop 0
	flat_load_dwordx4 v[14:17], v[28:29] offset:128
	s_waitcnt vmcnt(0) lgkmcnt(0)
	v_pk_fma_f32 v[2:3], v[6:7], v[2:3], v[14:15]
	v_pk_fma_f32 v[4:5], v[8:9], v[4:5], v[16:17]
	flat_store_dwordx4 v[30:31], v[2:5] offset:128
	flat_load_dwordx4 v[2:5], v[26:27] offset:192
	s_nop 0
	flat_load_dwordx4 v[6:9], v[28:29] offset:192
	s_waitcnt vmcnt(0) lgkmcnt(0)
	v_pk_fma_f32 v[2:3], v[10:11], v[2:3], v[6:7]
	v_pk_fma_f32 v[4:5], v[12:13], v[4:5], v[8:9]
	flat_store_dwordx4 v[30:31], v[2:5] offset:192
	s_add_i32 s7, s7, 1
	s_mul_i32 s0, s7, s39
	s_add_i32 s0, s0, s5
	s_cmpk_gt_i32 s0, 0x7f
	s_cbranch_scc0 .LBB0_961

; #define LAUNDER_IDS const int tid__ = launder_v((int)threadIdx.x); const int blk__ = launder_s((int)blockIdx.x); (void)tid__; (void)blk__;
; template <int MI, int NI>
; DI void gemm256(f32x4 (&acc)[MI][NI], const u16* __restrict__ A, int lda, const u16* __restrict__ Bt, int ldb, int K, int m0, int n0, char* smem) {
;     ...
;   const int srow = lane >> 2, scol = ((lane & 3) ^ ((lane >> 5) << 1)) * 8;
;   const u16* Ag = A + (size_t)(m0 + wave * NAW * 16 + srow) * lda + scol;
;   const u16* Bg = Bt + (size_t)(n0 + wave * NBW * 16 + srow) * ldb + scol;
;   char* la = smem + (wave * NAW) * 1024 + lane * 16;
;   char* lb = smem + ABYTES + (wave * NBW) * 1024 + lane * 16;
;     ...
;   const int nk = K >> 5;
;   G256_ISSUE(0, 0);
;   if (nk > 1) G256_ISSUE(1, 32);
;   const int foff = lr * 64 + ((lq ^ ((lr >> 3) << 1)) * 16);
;   int st = 0;
;   for (int kt = 0; kt < nk; ++kt) {
;     if (kt + 1 < nk) asm volatile("s_waitcnt vmcnt(%0) lgkmcnt(0)" :: "n"(LPS) : "memory");
;     else asm volatile("s_waitcnt vmcnt(0) lgkmcnt(0)" ::: "memory");
;     __builtin_amdgcn_s_barrier();
;     __builtin_amdgcn_s_setprio(1);
;     const char* sb = smem + st * STAGE + foff;
;     bf16x8 af[MI], bfr[NI];
; #pragma unroll
;     for (int mi = 0; mi < MI; ++mi) af[mi] = *(const bf16x8*)(sb + (wr * MI + mi) * 1024);
; #pragma unroll
;     for (int ni = 0; ni < NI; ++ni) bfr[ni] = *(const bf16x8*)(sb + ABYTES + (wc * NI + ni) * 1024);
;     __builtin_amdgcn_sched_barrier(0x0);
;     if (kt + 2 < nk) { const int s2 = st >= 1 ? st - 1 : 2; G256_ISSUE(s2, (kt + 2) * 32); }
; template <int MI, int NI>
; DI void resid_tile(const u16* A, int K, const u16* Bt, const float* gate, const float* xl_in, const float* xc_in, float* xl_out, float* xc_out,
;                    int m0, int n0, char* smem) {
;   LAUNDER_IDS
;   WAVE_COORDS
;   f32x4 acc[MI][NI]; zero_accm<MI, NI>(acc);
;   gemm256<MI, NI>(acc, A, K, Bt, K, K, m0, n0, smem);
; DI void phase_resid(const Params& p, const u16* A, int K, const u16* Bt, const float* gate  ,
;                     const float* xl_in, const float* xc_in, float* xl_out, float* xc_out, int Mout, char* smem) {
;     ...
;     for (int t = blk__; t < (NTC / 64) * 16; t += gridDim.x) {
;       const int tm = t >> 4, tn = t & 15;
;       resid_tile<2, 2>(A, K, Bt, gate, xl_in, xc_in, xl_out, xc_out, NTL + tm * 64, tn * 64, smem);
;     }
.LBB0_966:
	s_lshl_b32 s0, s4, 2
	s_and_b32 s8, s0, 0xffffffc0
	s_lshl_b32 s0, s4, 6
	s_and_b32 s7, s0, 0x3c0
	v_mov_b32_e32 v22, v163
	s_mov_b32 s0, s2
	s_waitcnt vmcnt(0)
	v_mov_b32_e32 v6, v163
	s_add_i32 s8, s8, 0x8000
	v_ashrrev_i32_e32 v8, 6, v6
	v_bfe_u32 v9, v6, 2, 4
	v_lshlrev_b32_e32 v10, 4, v8
	s_mov_b32 s0, s2
	v_and_b32_e32 v0, 3, v6
	v_lshrrev_b32_e32 v2, 4, v6
	v_or_b32_e32 v4, v9, v10
	v_bitop3_b32 v0, v2, v0, 2 bitop3:0x6c
	v_add_u32_e32 v2, s8, v4
	v_add_u32_e32 v4, s7, v4
	v_and_b32_e32 v7, 63, v6
	v_ashrrev_i32_e32 v3, 31, v2
	v_ashrrev_i32_e32 v5, 31, v4
	v_readlane_b32 s0, v254, 54
	v_lshlrev_b32_e32 v11, 10, v8
	v_lshlrev_b64 v[2:3], 13, v[2:3]
	v_lshlrev_b64 v[4:5], 13, v[4:5]
	v_readlane_b32 s1, v254, 55
	v_lshl_or_b32 v27, v7, 4, v11
	v_lshl_add_u64 v[2:3], s[60:61], 0, v[2:3]
	v_lshlrev_b32_e32 v0, 4, v0
	v_lshl_add_u64 v[4:5], s[0:1], 0, v[4:5]
	v_add_u32_e32 v7, 0x1000, v27
	v_readfirstlane_b32 s0, v27
	v_lshl_add_u64 v[2:3], v[2:3], 0, v[0:1]
	v_bfe_i32 v199, v163, 2, 1
	v_and_b32_e32 v198, 0xffffe040, v199
	v_lshl_add_u64 v[2:3], v[2:3], 0, v[198:199]
	s_mov_b32 m0, s0
	v_readfirstlane_b32 s0, v7
	v_add_u32_e32 v7, 0x2000, v27
	v_lshl_add_u64 v[4:5], v[4:5], 0, v[0:1]
	global_load_lds_dwordx4 v[2:3], off
	s_mov_b32 m0, s0
	v_readfirstlane_b32 s0, v7
	global_load_lds_dwordx4 v[4:5], off
	s_mov_b64 s[98:99], 0x80
	v_lshl_add_u64 v[2:3], v[2:3], 0, s[98:99]
	s_mov_b32 m0, s0
	s_and_b32 s1, s6, 0x3c0
	global_load_lds_dwordx4 v[2:3], off
	v_lshl_add_u64 v[2:3], v[4:5], 0, 64
	v_add_u32_e32 v4, 0x3000, v27
	s_waitcnt lgkmcnt(0)
	v_and_b32_e32 v26, 0xfffff800, v11
	v_readfirstlane_b32 s0, v4
	s_mov_b32 m0, s0
	v_and_b32_e32 v4, 48, v6
	global_load_lds_dwordx4 v[2:3], off
	v_lshlrev_b32_e32 v3, 2, v6
	v_lshlrev_b32_e32 v2, 6, v6
	v_bitop3_b32 v3, v3, v4, 32 bitop3:0x6c
	s_and_b32 s0, s5, 0xffffffc0
	v_and_or_b32 v24, v2, s59, v3
	v_lshlrev_b32_e32 v2, 11, v8
	v_and_b32_e32 v23, 0x800, v2
	v_or_b32_e32 v2, s0, v9
	v_add3_u32 v2, v2, v10, s58
	v_ashrrev_i32_e32 v3, 31, v2
	v_lshlrev_b64 v[2:3], 13, v[2:3]
	v_or_b32_e32 v2, v2, v0
	v_lshl_add_u64 v[18:19], s[62:63], 0, v[2:3]
	v_bfe_i32 v199, v163, 2, 1
	v_and_b32_e32 v198, 0xffffe040, v199
	v_lshl_add_u64 v[18:19], v[18:19], 0, v[198:199]
	v_or_b32_e32 v2, s1, v9
	v_add_u32_e32 v2, v2, v10
	v_ashrrev_i32_e32 v3, 31, v2
	v_lshlrev_b64 v[2:3], 13, v[2:3]
	v_readlane_b32 s0, v254, 52
	v_or_b32_e32 v2, v2, v0
	v_readlane_b32 s1, v254, 53
	v_mov_b32_e32 v6, 0
	v_or_b32_e32 v25, 0x400, v11
	v_lshl_add_u64 v[20:21], s[0:1], 0, v[2:3]
	s_mov_b32 s9, 0
	s_mov_b64 s[0:1], 0
	v_mov_b32_e32 v7, v6
	v_mov_b32_e32 v8, v6
	v_mov_b32_e32 v9, v6
	v_mov_b32_e32 v2, v6
	v_mov_b32_e32 v3, v6
	v_mov_b32_e32 v4, v6
	v_mov_b32_e32 v5, v6
	v_mov_b32_e32 v10, v6
	v_mov_b32_e32 v11, v6
	v_mov_b32_e32 v12, v6
	v_mov_b32_e32 v13, v6
	v_mov_b32_e32 v14, v6
	v_mov_b32_e32 v15, v6
	v_mov_b32_e32 v16, v6
	v_mov_b32_e32 v17, v6
.LBB0_967:
	s_waitcnt vmcnt(2) lgkmcnt(0)
	s_barrier
	s_setprio 1
	s_lshl_b32 s10, s9, 13
	v_or_b32_e32 v0, s10, v24
	v_add_u32_e32 v28, v0, v26
	v_add_u32_e32 v32, v0, v25
	v_add_u32_e32 v0, v0, v23
	s_waitcnt vmcnt(0)
	ds_read_b128 v[28:31], v28
	ds_read_b128 v[32:35], v32
	ds_read_b128 v[36:39], v0 offset:4096
	ds_read_b128 v[40:43], v0 offset:5120
	s_addk_i32 s10, 0xe000
	s_cmp_gt_i32 s9, 0
	s_cselect_b32 s10, s10, 0x4000
	v_add_u32_e32 v0, s10, v27
	v_add_u32_e32 v52, 0x1000, v0
	v_lshl_add_u64 v[48:49], v[18:19], 0, s[0:1]
	v_lshl_add_u64 v[48:49], v[48:49], 0, s[0:1]
	v_readfirstlane_b32 s10, v0
	v_lshl_add_u64 v[44:45], v[20:21], 0, s[0:1]
	s_mov_b64 s[98:99], 0x47e1100
	v_lshl_add_u64 v[50:51], v[48:49], 0, s[98:99]
	s_mov_b32 m0, s10
	v_readfirstlane_b32 s10, v52
	v_lshl_add_u64 v[46:47], v[44:45], 0, s[56:57]
	global_load_lds_dwordx4 v[50:51], off
	s_mov_b32 m0, s10
	s_nop 0
	global_load_lds_dwordx4 v[46:47], off
	s_setprio 0
	s_waitcnt lgkmcnt(0)
	v_mfma_f32_16x16x32_bf16 v[14:17], v[36:39], v[28:31], v[14:17]
	s_add_i32 s10, s9, 1
	s_waitcnt vmcnt(2) lgkmcnt(0)
	s_cmp_lg_u32 s9, 2
	v_mfma_f32_16x16x32_bf16 v[10:13], v[40:43], v[28:31], v[10:13]
	s_cselect_b32 s9, s10, 0
	s_barrier
	v_mfma_f32_16x16x32_bf16 v[2:5], v[36:39], v[32:35], v[2:5]
	v_mfma_f32_16x16x32_bf16 v[6:9], v[40:43], v[32:35], v[6:9]
	s_setprio 1
	s_lshl_b32 s10, s9, 13
	v_or_b32_e32 v0, s10, v24
	v_add_u32_e32 v28, v0, v26
	v_add_u32_e32 v32, v0, v25
	v_add_u32_e32 v0, v0, v23
	s_waitcnt vmcnt(0)
	ds_read_b128 v[28:31], v28
	ds_read_b128 v[32:35], v32
	ds_read_b128 v[36:39], v0 offset:4096
	ds_read_b128 v[40:43], v0 offset:5120
	s_addk_i32 s10, 0xe000
	s_cmp_gt_i32 s9, 0
	s_cselect_b32 s10, s10, 0x4000
	v_add_u32_e32 v0, s10, v27
	s_mov_b64 s[10:11], 0x20610c0
	v_add_u32_e32 v52, 0x1000, v0
	v_lshl_add_u64 v[46:47], v[44:45], 0, s[10:11]
	v_readfirstlane_b32 s10, v0
	s_mov_b64 s[98:99], 0x47e1180
	v_lshl_add_u64 v[50:51], v[48:49], 0, s[98:99]
	s_mov_b32 m0, s10
	v_readfirstlane_b32 s10, v52
	global_load_lds_dwordx4 v[50:51], off
	s_mov_b32 m0, s10
	s_nop 0
	global_load_lds_dwordx4 v[46:47], off
	s_setprio 0
	s_waitcnt lgkmcnt(0)
	v_mfma_f32_16x16x32_bf16 v[14:17], v[36:39], v[28:31], v[14:17]
	s_add_i32 s10, s9, 1
	s_waitcnt vmcnt(2) lgkmcnt(0)
	s_cmp_lg_u32 s9, 2
	v_mfma_f32_16x16x32_bf16 v[10:13], v[40:43], v[28:31], v[10:13]
	s_cselect_b32 s9, s10, 0
	s_barrier
; template <int MI, int NI>
; DI void gemm256(f32x4 (&acc)[MI][NI], const u16* __restrict__ A, int lda, const u16* __restrict__ Bt, int ldb, int K, int m0, int n0, char* smem) {
;     ...
;   for (int kt = 0; kt < nk; ++kt) {
;     if (kt + 1 < nk) asm volatile("s_waitcnt vmcnt(%0) lgkmcnt(0)" :: "n"(LPS) : "memory");
;     else asm volatile("s_waitcnt vmcnt(0) lgkmcnt(0)" ::: "memory");
;     __builtin_amdgcn_s_barrier();
;     __builtin_amdgcn_s_setprio(1);
;     const char* sb = smem + st * STAGE + foff;
;     bf16x8 af[MI], bfr[NI];
; #pragma unroll
;     for (int mi = 0; mi < MI; ++mi) af[mi] = *(const bf16x8*)(sb + (wr * MI + mi) * 1024);
; #pragma unroll
;     for (int ni = 0; ni < NI; ++ni) bfr[ni] = *(const bf16x8*)(sb + ABYTES + (wc * NI + ni) * 1024);
;     __builtin_amdgcn_sched_barrier(0x0);
;     if (kt + 2 < nk) { const int s2 = st >= 1 ? st - 1 : 2; G256_ISSUE(s2, (kt + 2) * 32); }
;     __builtin_amdgcn_s_setprio(0);
; #pragma unroll
;     for (int mi = 0; mi < MI; ++mi)
; #pragma unroll
;       for (int ni = 0; ni < NI; ++ni)
;         acc[mi][ni] = __builtin_amdgcn_mfma_f32_16x16x32_bf16(bfr[ni], af[mi], acc[mi][ni], 0, 0, 0);
;     st = st == 2 ? 0 : st + 1;
;   }
; template <int MI, int NI>
; DI void resid_tile(const u16* A, int K, const u16* Bt, const float* gate, const float* xl_in, const float* xc_in, float* xl_out, float* xc_out,
;                    int m0, int n0, char* smem) {
;     ...
; #pragma unroll
;   for (int mi = 0; mi < MI; ++mi) {
;     const int m = m0 + wr * 16 * MI + mi * 16 + lr;
;     const int b9 = m < NTL ? m >> 12 : 8;
;     const float* xi = xrow(xl_in, xc_in, m);
;     float* xo = m < NTL ? xl_out + (size_t)m * D : xc_out + (size_t)(m - NTL) * D;
; #pragma unroll
;     for (int ni = 0; ni < NI; ++ni) {
;       const int n = n0 + wc * 16 * NI + ni * 16 + lq * 4;
;       const float4 g = *(const float4*)(gate + (size_t)b9 * 6144 + n);
;       const float4 xv = *(const float4*)(xi + n);
;       float4 ov;
;       ov.x = xv.x + g.x * acc[mi][ni][0]; ov.y = xv.y + g.y * acc[mi][ni][1]; ov.z = xv.z + g.z * acc[mi][ni][2]; ov.w = xv.w + g.w * acc[mi][ni][3];
;       *(float4*)(xo + n) = ov;
;     }
	v_mfma_f32_16x16x32_bf16 v[2:5], v[36:39], v[32:35], v[2:5]
	v_mfma_f32_16x16x32_bf16 v[6:9], v[40:43], v[32:35], v[6:9]
	s_setprio 1
	s_lshl_b32 s10, s9, 13
	v_or_b32_e32 v0, s10, v24
	v_add_u32_e32 v28, v0, v26
	v_add_u32_e32 v32, v0, v25
	v_add_u32_e32 v0, v0, v23
	s_waitcnt vmcnt(0)
	ds_read_b128 v[28:31], v28
	ds_read_b128 v[32:35], v32
	ds_read_b128 v[36:39], v0 offset:4096
	ds_read_b128 v[40:43], v0 offset:5120
	s_addk_i32 s10, 0xe000
	s_cmp_gt_i32 s9, 0
	s_cselect_b32 s10, s10, 0x4000
	v_add_u32_e32 v0, s10, v27
	s_mov_b64 s[10:11], 0x2061100
	v_add_u32_e32 v50, 0x1000, v0
	v_lshl_add_u64 v[44:45], v[44:45], 0, s[10:11]
	v_readfirstlane_b32 s10, v0
	s_mov_b64 s[98:99], 0x47e1200
	v_lshl_add_u64 v[46:47], v[48:49], 0, s[98:99]
	s_mov_b32 m0, s10
	v_readfirstlane_b32 s10, v50
	global_load_lds_dwordx4 v[46:47], off
	s_mov_b32 m0, s10
	s_nop 0
	global_load_lds_dwordx4 v[44:45], off
	s_setprio 0
	s_add_i32 s10, s9, 1
	s_waitcnt lgkmcnt(0)
	v_mfma_f32_16x16x32_bf16 v[14:17], v[36:39], v[28:31], v[14:17]
	s_cmp_lg_u32 s9, 2
	s_cselect_b32 s9, s10, 0
	s_add_u32 s0, s0, 0xc0
	v_mfma_f32_16x16x32_bf16 v[10:13], v[40:43], v[28:31], v[10:13]
	s_addc_u32 s1, s1, 0
	s_cmpk_eq_i32 s0, 0x1f80
	v_mfma_f32_16x16x32_bf16 v[2:5], v[36:39], v[32:35], v[2:5]
	v_mfma_f32_16x16x32_bf16 v[6:9], v[40:43], v[32:35], v[6:9]
	s_cbranch_scc0 .LBB0_967
	s_waitcnt vmcnt(2) lgkmcnt(0)
	s_barrier
	s_setprio 1
	s_lshl_b32 s0, s9, 13
	v_or_b32_e32 v0, s0, v24
	v_add_u32_e32 v18, v0, v26
	v_add_u32_e32 v27, v0, v25
	v_add_u32_e32 v0, v0, v23
	s_waitcnt vmcnt(0)
	ds_read_b128 v[18:21], v18
	ds_read_b128 v[28:31], v27
	ds_read_b128 v[32:35], v0 offset:4096
	ds_read_b128 v[36:39], v0 offset:5120
	v_bfe_u32 v0, v22, 6, 1
	s_setprio 0
	s_waitcnt vmcnt(0) lgkmcnt(0)
	s_waitcnt lgkmcnt(1)
	v_mfma_f32_16x16x32_bf16 v[14:17], v[32:35], v[18:21], v[14:17]
	v_ashrrev_i32_e32 v40, 7, v22
	v_and_b32_e32 v41, 15, v22
	v_bfe_u32 v22, v22, 4, 2
	s_waitcnt lgkmcnt(0)
	v_mfma_f32_16x16x32_bf16 v[10:13], v[36:39], v[18:21], v[10:13]
	s_barrier
	v_mfma_f32_16x16x32_bf16 v[2:5], v[32:35], v[28:31], v[2:5]
	v_mfma_f32_16x16x32_bf16 v[18:21], v[36:39], v[28:31], v[6:9]
	s_setprio 1
	s_addk_i32 s0, 0x2000
	s_cmp_lg_u32 s9, 2
	s_cselect_b32 s0, s0, 0
	v_or_b32_e32 v28, s0, v24
	v_add_u32_e32 v6, v28, v26
	v_add_u32_e32 v24, v28, v25
	v_add_u32_e32 v23, v28, v23
	ds_read_b128 v[6:9], v6
	ds_read_b128 v[24:27], v24
	ds_read_b128 v[28:31], v23 offset:4096
	ds_read_b128 v[32:35], v23 offset:5120
	s_setprio 0
	s_waitcnt lgkmcnt(1)
	v_mfma_f32_16x16x32_bf16 v[14:17], v[28:31], v[6:9], v[14:17]
	s_waitcnt lgkmcnt(0)
	s_barrier
	s_waitcnt lgkmcnt(0)
	v_mfma_f32_16x16x32_bf16 v[10:13], v[32:35], v[6:9], v[10:13]
	v_mfma_f32_16x16x32_bf16 v[6:9], v[28:31], v[24:27], v[2:5]
	v_lshlrev_b32_e32 v0, 5, v0
	v_mov_b32_e32 v36, s95
	v_mov_b32_e32 v37, s49
	v_mfma_f32_16x16x32_bf16 v[2:5], v[32:35], v[24:27], v[18:21]
	v_mov_b32_e32 v38, s94
	v_mov_b32_e32 v39, s48
	s_nop 0
	v_lshlrev_b32_e32 v18, 5, v40
	v_add3_u32 v26, v41, s8, v18
	v_lshlrev_b32_e32 v18, 2, v22
	v_add3_u32 v18, v18, s7, v0
	v_min_i32_e32 v0, 0x8000, v26
	v_cmp_gt_i32_e32 vcc, s58, v26
	v_ashrrev_i32_e32 v28, 12, v0
	v_add_u32_e32 v0, 0xffff8000, v26
	v_ashrrev_i32_e32 v27, 31, v26
	v_cndmask_b32_e32 v21, 0, v27, vcc
	v_cndmask_b32_e32 v20, v0, v26, vcc
	v_cndmask_b32_e32 v23, v36, v37, vcc
	v_cndmask_b32_e32 v22, v38, v39, vcc
	v_lshlrev_b64 v[20:21], 12, v[20:21]
	v_lshl_add_u64 v[20:21], v[22:23], 0, v[20:21]
	v_lshlrev_b64 v[22:23], 12, v[26:27]
	v_lshlrev_b64 v[24:25], 12, v[0:1]
	v_lshl_add_u64 v[22:23], s[48:49], 0, v[22:23]
	v_lshl_add_u64 v[24:25], s[94:95], 0, v[24:25]
	v_ashrrev_i32_e32 v19, 31, v18
	v_cndmask_b32_e32 v23, v25, v23, vcc
	v_cndmask_b32_e32 v22, v24, v22, vcc
	v_mul_hi_i32_i24_e32 v25, 0x6000, v28
	v_mul_i32_i24_e32 v24, 0x6000, v28
	v_lshl_add_u64 v[24:25], s[82:83], 0, v[24:25]
	v_lshlrev_b64 v[28:29], 2, v[18:19]
	v_lshl_add_u64 v[30:31], v[24:25], 0, v[28:29]
	v_lshl_add_u64 v[32:33], v[20:21], 0, v[28:29]
	v_lshl_add_u64 v[34:35], v[22:23], 0, v[28:29]
	flat_load_dwordx4 v[18:21], v[30:31]
	flat_load_dwordx4 v[22:25], v[32:33]
	s_waitcnt vmcnt(0) lgkmcnt(0)
	v_pk_fma_f32 v[14:15], v[14:15], v[18:19], v[22:23]
	v_pk_fma_f32 v[16:17], v[16:17], v[20:21], v[24:25]
	flat_store_dwordx4 v[34:35], v[14:17]
	flat_load_dwordx4 v[14:17], v[30:31] offset:64
	s_nop 0
	flat_load_dwordx4 v[18:21], v[32:33] offset:64
	s_waitcnt vmcnt(0) lgkmcnt(0)
	v_pk_fma_f32 v[10:11], v[10:11], v[14:15], v[18:19]
	v_pk_fma_f32 v[12:13], v[12:13], v[16:17], v[20:21]
	flat_store_dwordx4 v[34:35], v[10:13] offset:64
	s_nop 1
	v_add_u32_e32 v10, 16, v26
	v_min_i32_e32 v0, 0x8000, v10
	v_cmp_gt_i32_e32 vcc, s58, v10
	v_ashrrev_i32_e32 v16, 12, v0
	v_add_u32_e32 v0, 0xffff8010, v26
	v_ashrrev_i32_e32 v11, 31, v10
	v_cndmask_b32_e32 v13, 0, v11, vcc
	v_cndmask_b32_e32 v12, v0, v10, vcc
	v_cndmask_b32_e32 v15, v36, v37, vcc
	v_cndmask_b32_e32 v14, v38, v39, vcc
	v_lshlrev_b64 v[12:13], 12, v[12:13]
	v_lshl_add_u64 v[12:13], v[14:15], 0, v[12:13]
	v_lshlrev_b64 v[10:11], 12, v[10:11]
	v_lshlrev_b64 v[14:15], 12, v[0:1]
	v_lshl_add_u64 v[10:11], s[48:49], 0, v[10:11]
	v_lshl_add_u64 v[14:15], s[94:95], 0, v[14:15]
	v_cndmask_b32_e32 v11, v15, v11, vcc
	v_cndmask_b32_e32 v10, v14, v10, vcc
	v_mul_hi_i32_i24_e32 v15, 0x6000, v16
	v_mul_i32_i24_e32 v14, 0x6000, v16
	v_lshl_add_u64 v[14:15], s[82:83], 0, v[14:15]
	v_lshl_add_u64 v[18:19], v[14:15], 0, v[28:29]
	v_lshl_add_u64 v[20:21], v[12:13], 0, v[28:29]
	v_lshl_add_u64 v[22:23], v[10:11], 0, v[28:29]
	flat_load_dwordx4 v[10:13], v[18:19]
	flat_load_dwordx4 v[14:17], v[20:21]
	s_waitcnt vmcnt(0) lgkmcnt(0)
	v_pk_fma_f32 v[6:7], v[6:7], v[10:11], v[14:15]
	v_pk_fma_f32 v[8:9], v[8:9], v[12:13], v[16:17]
	flat_store_dwordx4 v[22:23], v[6:9]
	flat_load_dwordx4 v[6:9], v[18:19] offset:64
	s_nop 0
	flat_load_dwordx4 v[10:13], v[20:21] offset:64
	s_waitcnt vmcnt(0) lgkmcnt(0)
	v_pk_fma_f32 v[2:3], v[2:3], v[6:7], v[10:11]
	v_pk_fma_f32 v[4:5], v[4:5], v[8:9], v[12:13]
	flat_store_dwordx4 v[22:23], v[2:5] offset:64
	s_add_i32 s4, s4, s79
	s_add_i32 s5, s5, s40
	s_add_i32 s6, s6, s41
	s_cmpk_gt_i32 s4, 0x1ff
	s_cbranch_scc0 .LBB0_966

; DI unsigned pack2(float a, float b) { float2_t v = {a, b}; bf16x2_t r = __builtin_convertvector(v, bf16x2_t); return __builtin_bit_cast(unsigned, r); }
; DI void phase_norm(const float* xl, const float* xc, const float* tab  , u16* hb, int M) {
;     ...
;   const int wave = tid__ >> 6, lane = tid__ & 63;
;   const int nw = gridDim.x * 4, rpw = (M + nw - 1) / nw;
;   const int rbeg = (blk__ * 4 + wave) * rpw, rend = min(rbeg + rpw, M);
;   int cur_b9 = -1;
;   float4 g[4], sh[4];
; #pragma unroll
;   for (int i = 0; i < 4; ++i) { g[i] = make_float4(0.f, 0.f, 0.f, 0.f); sh[i] = g[i]; }
;   float4 vn[4];
;   if (rbeg < rend) {
;     const float* xp0 = xrow(xl, xc, rbeg);
; #pragma unroll
;     for (int i = 0; i < 4; ++i) vn[i] = *(const float4*)(xp0 + i * 256 + lane * 4);
;   }
;   for (int r = rbeg; r < rend; ++r) {
;     const int b9 = r < NTL ? r >> 12 : 8;
;     float4 v[4];
; #pragma unroll
;     for (int i = 0; i < 4; ++i) v[i] = vn[i];
;     {
;       const float* xpn = xrow(xl, xc, min(r + 1, rend - 1));
; #pragma unroll
;       for (int i = 0; i < 4; ++i) vn[i] = *(const float4*)(xpn + i * 256 + lane * 4);
;     }
;     if (b9 != cur_b9) {
;       cur_b9 = b9;
;       const float* t = tab + b9 * 2048;
; #pragma unroll
;       for (int i = 0; i < 4; ++i) { g[i] = *(const float4*)(t + i * 256 + lane * 4); sh[i] = *(const float4*)(t + 1024 + i * 256 + lane * 4); }
;     }
;     float s = 0.f;
; #pragma unroll
;     for (int i = 0; i < 4; ++i) s += v[i].x * v[i].x + v[i].y * v[i].y + v[i].z * v[i].z + v[i].w * v[i].w;
;     s = wavesum(s);
;     const float rs = rsqrtf(s * (1.f / 1024.f) + 1e-6f);
; #pragma unroll
;     for (int i = 0; i < 4; ++i) {
;       const int k = i * 256 + lane * 4;
;       *(uint2*)(hb + (size_t)r * 1024 + k) = make_uint2(pack2(v[i].x * rs * g[i].x + sh[i].x, v[i].y * rs * g[i].y + sh[i].y), pack2(v[i].z * rs * g[i].z + sh[i].z, v[i].w * rs * g[i].w + sh[i].w));
;     }
;   }
.LBB0_970:
	s_and_b64 vcc, exec, s[0:1]
	s_cbranch_vccz .LBB0_433
	v_mov_b32_e32 v18, v163
	s_mov_b32 s0, s2
	s_nop 0
	v_ashrrev_i32_e32 v0, 6, v18
	v_lshl_add_u32 v0, s0, 2, v0
	v_readlane_b32 s0, v253, 31
	s_nop 1
	v_mul_lo_u32 v66, v0, s0
	v_add_u32_e32 v0, s0, v66
	v_min_i32_e32 v69, 0x8800, v0
	v_cmp_lt_i32_e32 vcc, v66, v69
	s_and_saveexec_b64 s[0:1], vcc
	s_cbranch_execz .LBB0_432
	v_add_u32_e32 v0, 0xffff8000, v66
	v_cmp_gt_i32_e32 vcc, s58, v66
	v_readlane_b32 s4, v253, 55
	v_ashrrev_i32_e32 v67, 31, v66
	v_cndmask_b32_e32 v2, v0, v66, vcc
	v_mov_b32_e32 v0, s4
	v_readlane_b32 s4, v253, 53
	v_cndmask_b32_e32 v3, 0, v67, vcc
	v_lshlrev_b64 v[2:3], 12, v[2:3]
	s_waitcnt vmcnt(0)
	v_mov_b32_e32 v4, s4
	v_readlane_b32 s4, v253, 56
	v_cndmask_b32_e32 v5, v0, v4, vcc
	v_lshrrev_b32_e32 v20, 1, v66
	v_mov_b32_e32 v21, 0
	v_lshlrev_b64 v[20:21], 12, v[20:21]
	v_and_b32_e32 v90, 1, v66
	v_lshl_or_b32 v20, v90, 6, v20
	v_mov_b32_e32 v0, s4
	v_readlane_b32 s4, v253, 54
	v_mov_b32_e32 v73, -1
	v_add_u32_e32 v72, -1, v69
	v_mov_b32_e32 v4, s4
	v_cndmask_b32_e32 v4, v0, v4, vcc
	v_lshlrev_b32_e32 v0, 2, v18
	v_and_b32_e32 v68, 0xfc, v0
	v_lshl_add_u64 v[2:3], v[4:5], 0, v[2:3]
	v_lshlrev_b32_e32 v0, 2, v68
	v_lshl_add_u64 v[14:15], v[2:3], 0, v[0:1]
	flat_load_dwordx4 v[2:5], v[14:15]
	flat_load_dwordx4 v[6:9], v[14:15] offset:1024
	flat_load_dwordx4 v[10:13], v[14:15] offset:2048
	s_nop 0
	flat_load_dwordx4 v[14:17], v[14:15] offset:3072
	v_bfe_u32 v0, v18, 3, 3
	v_lshl_or_b32 v20, v0, 7, v20
	v_and_b32_e32 v0, 7, v18
	v_lshl_or_b32 v20, v0, 3, v20
	v_mov_b32_e32 v0, v1
	v_lshl_add_u64 v[70:71], s[22:23], 0, v[20:21]
	s_mov_b64 s[4:5], 0
	v_mov_b64_e32 v[44:45], v[0:1]
	s_waitcnt lgkmcnt(0)
	v_mov_b64_e32 v[42:43], v[0:1]
	v_mov_b64_e32 v[32:33], v[0:1]
	v_mov_b64_e32 v[30:31], v[0:1]
	v_mov_b64_e32 v[28:29], v[0:1]
	v_mov_b64_e32 v[26:27], v[0:1]
	v_mov_b64_e32 v[40:41], v[0:1]
	v_mov_b64_e32 v[38:39], v[0:1]
	v_mov_b64_e32 v[18:19], v[0:1]
	v_mov_b64_e32 v[20:21], v[0:1]
	v_mov_b64_e32 v[22:23], v[0:1]
	v_mov_b64_e32 v[24:25], v[0:1]
	v_mov_b64_e32 v[34:35], v[0:1]
	v_mov_b64_e32 v[36:37], v[0:1]
	v_mov_b64_e32 v[46:47], v[0:1]
	v_mov_b64_e32 v[48:49], v[0:1]
	s_branch .LBB0_974
.LBB0_973:
	s_or_b64 exec, exec, s[6:7]
	s_waitcnt vmcnt(0)
	v_pk_mul_f32 v[74:75], v[2:3], v[2:3]
	v_pk_mul_f32 v[78:79], v[6:7], v[6:7]
	v_mov_b32_e32 v82, v14
	v_mov_b32_e32 v83, v10
	v_pk_mul_f32 v[76:77], v[4:5], v[4:5]
	v_pk_mul_f32 v[80:81], v[8:9], v[8:9]
	v_pk_mul_f32 v[82:83], v[82:83], v[82:83]
	v_mov_b32_e32 v84, v15
	v_mov_b32_e32 v85, v11
	v_add_f32_e32 v0, v75, v74
	v_add_f32_e32 v67, v79, v78
	v_pk_fma_f32 v[82:83], v[84:85], v[84:85], v[82:83]
	v_mov_b32_e32 v84, v16
	v_mov_b32_e32 v85, v12
	v_add_f32_e32 v0, v76, v0
	v_add_f32_e32 v67, v80, v67
	v_pk_fma_f32 v[82:83], v[84:85], v[84:85], v[82:83]
	v_mov_b32_e32 v84, v17
	v_mov_b32_e32 v85, v13
	v_add_f32_e32 v0, v77, v0
	v_add_f32_e32 v67, v81, v67
	v_pk_fma_f32 v[82:83], v[84:85], v[84:85], v[82:83]
	v_add_f32_e32 v0, v67, v0
	v_add_f32_e32 v0, v83, v0
	v_add_f32_e32 v0, v82, v0
	s_nop 1
	v_add_f32_dpp v0, v0, v0 row_ror:8 row_mask:0xf bank_mask:0xf bound_ctrl:1
	s_nop 1
	v_add_f32_dpp v0, v0, v0 row_ror:4 row_mask:0xf bank_mask:0xf bound_ctrl:1
	s_nop 1
	v_add_f32_dpp v0, v0, v0 row_ror:2 row_mask:0xf bank_mask:0xf bound_ctrl:1
	s_nop 1
	v_add_f32_dpp v0, v0, v0 row_ror:1 row_mask:0xf bank_mask:0xf bound_ctrl:1
	s_nop 0
	v_readlane_b32 s7, v0, 16
	v_readlane_b32 s6, v0, 0
	s_nop 0
	v_mov_b32_e32 v67, s7
	v_add_f32_e32 v67, s6, v67
	v_readlane_b32 s6, v0, 32
	s_nop 1
	v_add_f32_e32 v67, s6, v67
	v_readlane_b32 s6, v0, 48
	s_nop 1
	v_add_f32_e32 v0, s6, v67
	v_fmamk_f32 v0, v0, 0x3a800000, v162
	v_mul_f32_e32 v67, 0x4b800000, v0
	v_cmp_gt_f32_e32 vcc, s31, v0
	s_mov_b64 s[6:7], 0x800
	s_nop 0
	v_cndmask_b32_e32 v0, v0, v67, vcc
	v_rsq_f32_e32 v0, v0
	s_nop 0
	v_mul_f32_e32 v67, 0x45800000, v0
	v_cndmask_b32_e32 v0, v0, v67, vcc
	v_pk_mul_f32 v[2:3], v[2:3], v[0:1] op_sel_hi:[1,0]
	v_pk_mul_f32 v[4:5], v[4:5], v[0:1] op_sel_hi:[1,0]
	s_waitcnt lgkmcnt(0)
	v_pk_fma_f32 v[2:3], v[18:19], v[2:3], v[38:39]
	v_pk_fma_f32 v[4:5], v[20:21], v[4:5], v[40:41]
	v_cvt_pk_bf16_f32 v2, v2, v3
	v_cvt_pk_bf16_f32 v3, v4, v5
	flat_store_dwordx2 v[70:71], v[2:3]
	v_pk_mul_f32 v[2:3], v[6:7], v[0:1] op_sel_hi:[1,0]
	v_pk_mul_f32 v[4:5], v[8:9], v[0:1] op_sel_hi:[1,0]
	v_pk_fma_f32 v[2:3], v[22:23], v[2:3], v[26:27]
	v_pk_fma_f32 v[4:5], v[24:25], v[4:5], v[28:29]
	v_cvt_pk_bf16_f32 v2, v2, v3
	v_cvt_pk_bf16_f32 v3, v4, v5
	flat_store_dwordx2 v[70:71], v[2:3] offset:1024
	v_pk_mul_f32 v[2:3], v[10:11], v[0:1] op_sel_hi:[1,0]
	v_pk_mul_f32 v[4:5], v[12:13], v[0:1] op_sel_hi:[1,0]
	v_pk_fma_f32 v[2:3], v[34:35], v[2:3], v[30:31]
	v_pk_fma_f32 v[4:5], v[36:37], v[4:5], v[32:33]
	v_cvt_pk_bf16_f32 v2, v2, v3
	v_cvt_pk_bf16_f32 v3, v4, v5
	flat_store_dwordx2 v[70:71], v[2:3] offset:2048
	v_pk_mul_f32 v[2:3], v[14:15], v[0:1] op_sel_hi:[1,0]
	v_pk_mul_f32 v[4:5], v[16:17], v[0:1] op_sel_hi:[1,0]
	v_pk_fma_f32 v[2:3], v[46:47], v[2:3], v[42:43]
	v_pk_fma_f32 v[4:5], v[48:49], v[4:5], v[44:45]
	v_cvt_pk_bf16_f32 v2, v2, v3
	v_cvt_pk_bf16_f32 v3, v4, v5
	v_cmp_ge_i32_e32 vcc, v66, v69
	flat_store_dwordx2 v[70:71], v[2:3] offset:3072
	v_and_b32_e32 v90, 1, v66
	v_mul_u32_u24_e32 v90, 0xf80, v90
	v_sub_u32_e32 v90, 0xfc0, v90
	v_mov_b32_e32 v91, 0
	v_lshl_add_u64 v[70:71], v[70:71], 0, v[90:91]
	s_or_b64 s[4:5], vcc, s[4:5]
	v_mov_b64_e32 v[4:5], v[64:65]
	v_mov_b64_e32 v[2:3], v[62:63]
	v_mov_b64_e32 v[8:9], v[60:61]
	v_mov_b64_e32 v[6:7], v[58:59]
	v_mov_b64_e32 v[12:13], v[56:57]
	v_mov_b64_e32 v[10:11], v[54:55]
	v_mov_b64_e32 v[16:17], v[52:53]
	v_mov_b64_e32 v[14:15], v[50:51]
	s_andn2_b64 exec, exec, s[4:5]
	s_cbranch_execz .LBB0_432

; __global__ void __launch_bounds__(256, 2) fwd_megakernel(Params pk) {
;   __shared__ __attribute__((aligned(16))) char smem[73728];
	.amdhsa_kernel _Z14fwd_megakernel6Params
		.amdhsa_group_segment_fixed_size 73768
		.amdhsa_private_segment_fixed_size 0
		.amdhsa_kernarg_size 544
		.amdhsa_user_sgpr_count 2
		.amdhsa_user_sgpr_dispatch_ptr 0
		.amdhsa_user_sgpr_queue_ptr 0
		.amdhsa_user_sgpr_kernarg_segment_ptr 1
		.amdhsa_user_sgpr_dispatch_id 0
		.amdhsa_user_sgpr_kernarg_preload_length 0
		.amdhsa_user_sgpr_kernarg_preload_offset 0
		.amdhsa_user_sgpr_private_segment_size 0
		.amdhsa_uses_dynamic_stack 0
		.amdhsa_enable_private_segment 0
		.amdhsa_system_sgpr_workgroup_id_x 1
		.amdhsa_system_sgpr_workgroup_id_y 0
		.amdhsa_system_sgpr_workgroup_id_z 0
		.amdhsa_system_sgpr_workgroup_info 0
		.amdhsa_system_vgpr_workitem_id 2
		.amdhsa_next_free_vgpr 256
		.amdhsa_next_free_sgpr 102
		.amdhsa_accum_offset 256
		.amdhsa_reserve_vcc 1
		.amdhsa_float_round_mode_32 0
		.amdhsa_float_round_mode_16_64 0
		.amdhsa_float_denorm_mode_32 3
		.amdhsa_float_denorm_mode_16_64 3
		.amdhsa_dx10_clamp 1
		.amdhsa_ieee_mode 1
		.amdhsa_fp16_overflow 0
		.amdhsa_tg_split 0
		.amdhsa_exception_fp_ieee_invalid_op 0
		.amdhsa_exception_fp_denorm_src 0
		.amdhsa_exception_fp_ieee_div_zero 0
		.amdhsa_exception_fp_ieee_overflow 0
		.amdhsa_exception_fp_ieee_underflow 0
		.amdhsa_exception_fp_ieee_inexact 0
		.amdhsa_exception_int_div_zero 0
	.end_amdhsa_kernel

; __global__ void __launch_bounds__(256, 2) fwd_megakernel(Params pk) {
;   __shared__ __attribute__((aligned(16))) char smem[73728];
amdhsa.kernels:
  - .agpr_count:     0
    .args:
      - .offset:         0
        .size:           288
        .value_kind:     by_value
      - .offset:         288
        .size:           4
        .value_kind:     hidden_block_count_x
      - .offset:         292
        .size:           4
        .value_kind:     hidden_block_count_y
      - .offset:         296
        .size:           4
        .value_kind:     hidden_block_count_z
      - .offset:         300
        .size:           2
        .value_kind:     hidden_group_size_x
      - .offset:         302
        .size:           2
        .value_kind:     hidden_group_size_y
      - .offset:         304
        .size:           2
        .value_kind:     hidden_group_size_z
      - .offset:         306
        .size:           2
        .value_kind:     hidden_remainder_x
      - .offset:         308
        .size:           2
        .value_kind:     hidden_remainder_y
      - .offset:         310
        .size:           2
        .value_kind:     hidden_remainder_z
      - .offset:         328
        .size:           8
        .value_kind:     hidden_global_offset_x
      - .offset:         336
        .size:           8
        .value_kind:     hidden_global_offset_y
      - .offset:         344
        .size:           8
        .value_kind:     hidden_global_offset_z
      - .offset:         352
        .size:           2
        .value_kind:     hidden_grid_dims
      - .offset:         376
        .size:           8
        .value_kind:     hidden_multigrid_sync_arg
    .group_segment_fixed_size: 73768
    .kernarg_segment_align: 8
    .kernarg_segment_size: 544
    .language:       OpenCL C
    .language_version:
      - 2
      - 0
    .max_flat_workgroup_size: 256
    .name:           _Z14fwd_megakernel6Params
    .private_segment_fixed_size: 0
    .sgpr_count:     108
    .sgpr_spill_count: 149
    .symbol:         _Z14fwd_megakernel6Params.kd
    .uniform_work_group_size: 1
    .uses_dynamic_stack: false
    .vgpr_count:     256
    .vgpr_spill_count: 0
    .wavefront_size: 64
